# speedup vs baseline: 1.0002x; 1.0002x over previous
; #define PG8_STAGE(bufoff, gbase, voff) do { _Pragma("unroll") for (int _i = 0; _i < 2; ++_i) \
;         __builtin_amdgcn_global_load_lds((const unsigned*)((const char*)(gbase) + (voff)[_i]), (LAS unsigned*)(lds + (bufoff) + ldsw + _i * 8192), 16, 0, 0); } while (0)
; #define PG8_LDA(dst, b, h) do { _Pragma("unroll") for (int m = 0; m < 4; ++m) _Pragma("unroll") for (int k = 0; k < 2; ++k) dst[m][k] = *(const LAS bf16x8*)(lds + PG8_SA(b, h) + aoff + m * 2048 + k * 1024); } while (0)
; #define PG8_LDB(dst, b, h) do { _Pragma("unroll") for (int n = 0; n < 2; ++n) _Pragma("unroll") for (int k = 0; k < 2; ++k) dst[n][k] = *(const LAS bf16x8*)(lds + PG8_SB(b, h) + boff + n * 2048 + k * 1024); } while (0)
; #define PG8_WAIT_L(n) asm volatile("s_waitcnt lgkmcnt(" #n ")" ::: "memory")
; #define PG8_BAR __builtin_amdgcn_s_barrier()
; #define PG8_SCHED __builtin_amdgcn_sched_barrier(0)
;     ...
;         for (int t = 0; t < nt; t += 2) {
;             const bool last = (t == nt - 2);
;             if (last && has_next && gate != nullptr && nxt.pm >= 32) {
;                 if (tid < 64) { unsigned sp = 0;
;                     while ((unsigned)__builtin_amdgcn_readfirstlane(__hip_atomic_load(gate, __ATOMIC_RELAXED, __HIP_MEMORY_SCOPE_AGENT)) < gate_need) { __builtin_amdgcn_s_sleep(2); if (++sp > (1u << 20)) break; }
;                     __builtin_amdgcn_fence(__ATOMIC_ACQUIRE, "agent"); asm volatile("s_waitcnt vmcnt(0)" ::: "memory"); }
;                 asm volatile("" ::: "memory"); PG8_BAR; asm volatile("" ::: "memory");
;             }
;             const char* a1 = cA + (size_t)(t + 1) * kstep;
;             const char* a2 = last ? nA : cA + (size_t)(t + 2) * kstep; const char* b2 = last ? nB : cB + (size_t)(t + 2) * kstep;
;             const char* a3 = a2 + kstep; const char* b3 = b2 + kstep;
;             PG8_LDB(B0, 0, 0); PG8_SCHED; PG8_LDA(At, 0, 0); PG8_STAGE(PG8_SA(1, 1), a1 + hstep, voffA);
;             PG8_WAIT_L(8); PG8_BAR; PG8_WAIT_L(0); PG8_MMA(0, 0, At, B0); PG8_BAR; PG8_SCHED;
;             PG8_LDB(B1, 0, 1); PG8_STAGE(PG8_SB(0, 0), b2, voffB);
;             PG8_BAR; PG8_WAIT_L(0); PG8_MMA(0, 1, At, B1); PG8_BAR;
;             PG8_LDA(At, 0, 1); PG8_STAGE(PG8_SA(0, 0), a2, voffA);
;             PG8_BAR; PG8_WAIT_L(0); PG8_MMA(1, 0, At, B0); PG8_BAR; PG8_SCHED;
.LBB0_120:
	s_add_i32 s44, s2, 2
	s_add_u32 s10, s8, 0x100
	s_addc_u32 s11, s9, 0
	s_add_i32 s35, 0, 0x10000
	v_add_u32_e32 v156, s35, v145
	ds_read_b128 v[140:143], v156
	ds_read_b128 v[148:151], v156 offset:1024
	ds_read_b128 v[152:155], v156 offset:2048
	ds_read_b128 v[156:159], v156 offset:3072
	s_cmp_eq_u32 s41, s2
	s_cselect_b32 s2, s6, s10
	s_cselect_b32 s3, s7, s11
	s_cselect_b32 s13, s19, s43
	s_cselect_b32 s12, s18, s42
	v_lshl_add_u64 v[192:193], s[8:9], 0, v[136:137]
	s_add_i32 m0, s21, 0xc000
	ds_read_b128 v[160:163], v147
	ds_read_b128 v[164:167], v147 offset:1024
	ds_read_b128 v[168:171], v147 offset:2048
	ds_read_b128 v[172:175], v147 offset:3072
	ds_read_b128 v[176:179], v147 offset:4096
	ds_read_b128 v[180:183], v147 offset:5120
	ds_read_b128 v[184:187], v147 offset:6144
	ds_read_b128 v[188:191], v147 offset:7168
	global_load_lds_dwordx4 v[192:193], off
	v_lshl_add_u64 v[192:193], s[8:9], 0, v[138:139]
	s_add_i32 m0, s21, 0xe000
	s_nop 0
	global_load_lds_dwordx4 v[192:193], off
	s_waitcnt lgkmcnt(8)
	s_barrier
	s_waitcnt lgkmcnt(0)
	v_mfma_f32_16x16x32_bf16 v[126:129], v[140:143], v[160:163], v[126:129]
	v_mfma_f32_16x16x32_bf16 v[122:125], v[152:155], v[160:163], v[122:125]
	v_mfma_f32_16x16x32_bf16 v[110:113], v[140:143], v[168:171], v[110:113]
	v_mfma_f32_16x16x32_bf16 v[106:109], v[152:155], v[168:171], v[106:109]
	v_mfma_f32_16x16x32_bf16 v[94:97], v[140:143], v[176:179], v[94:97]
	v_mfma_f32_16x16x32_bf16 v[90:93], v[152:155], v[176:179], v[90:93]
	v_mfma_f32_16x16x32_bf16 v[78:81], v[140:143], v[184:187], v[78:81]
	v_mfma_f32_16x16x32_bf16 v[74:77], v[152:155], v[184:187], v[74:77]
	v_mfma_f32_16x16x32_bf16 v[126:129], v[148:151], v[164:167], v[126:129]
	v_mfma_f32_16x16x32_bf16 v[122:125], v[156:159], v[164:167], v[122:125]
	v_mfma_f32_16x16x32_bf16 v[110:113], v[148:151], v[172:175], v[110:113]
	v_mfma_f32_16x16x32_bf16 v[106:109], v[156:159], v[172:175], v[106:109]
	v_mfma_f32_16x16x32_bf16 v[94:97], v[148:151], v[180:183], v[94:97]
	v_mfma_f32_16x16x32_bf16 v[90:93], v[156:159], v[180:183], v[90:93]
	v_mfma_f32_16x16x32_bf16 v[78:81], v[148:151], v[188:191], v[78:81]
	v_mfma_f32_16x16x32_bf16 v[74:77], v[156:159], v[188:191], v[74:77]
	s_barrier
	s_add_i32 s45, 0, 0x14000
	v_add_u32_e32 v208, s45, v145
	s_add_i32 s8, s35, s20
	ds_read_b128 v[192:195], v208
	ds_read_b128 v[196:199], v208 offset:1024
	ds_read_b128 v[220:223], v208 offset:2048
	ds_read_b128 v[224:227], v208 offset:3072
	v_lshl_add_u64 v[208:209], s[12:13], 0, v[64:65]
	s_mov_b32 m0, s8
	v_lshl_add_u64 v[210:211], s[12:13], 0, v[134:135]
	global_load_lds_dwordx4 v[208:209], off
	s_add_i32 m0, s8, 0x2000
	s_nop 0
	global_load_lds_dwordx4 v[210:211], off
	s_waitcnt lgkmcnt(0)
	s_barrier
	v_mfma_f32_16x16x32_bf16 v[118:121], v[192:195], v[160:163], v[118:121]
	v_mfma_f32_16x16x32_bf16 v[114:117], v[220:223], v[160:163], v[114:117]
	v_mfma_f32_16x16x32_bf16 v[102:105], v[192:195], v[168:171], v[102:105]
	v_mfma_f32_16x16x32_bf16 v[98:101], v[220:223], v[168:171], v[98:101]
	v_mfma_f32_16x16x32_bf16 v[86:89], v[192:195], v[176:179], v[86:89]
	v_mfma_f32_16x16x32_bf16 v[82:85], v[220:223], v[176:179], v[82:85]
	v_mfma_f32_16x16x32_bf16 v[70:73], v[192:195], v[184:187], v[70:73]
	v_mfma_f32_16x16x32_bf16 v[66:69], v[220:223], v[184:187], v[66:69]
	v_mfma_f32_16x16x32_bf16 v[118:121], v[196:199], v[164:167], v[118:121]
	v_mfma_f32_16x16x32_bf16 v[114:117], v[224:227], v[164:167], v[114:117]
	v_mfma_f32_16x16x32_bf16 v[102:105], v[196:199], v[172:175], v[102:105]
	v_mfma_f32_16x16x32_bf16 v[98:101], v[224:227], v[172:175], v[98:101]
	v_mfma_f32_16x16x32_bf16 v[86:89], v[196:199], v[180:183], v[86:89]
	v_mfma_f32_16x16x32_bf16 v[82:85], v[224:227], v[180:183], v[82:85]
	v_mfma_f32_16x16x32_bf16 v[70:73], v[196:199], v[188:191], v[70:73]
	v_mfma_f32_16x16x32_bf16 v[66:69], v[224:227], v[188:191], v[66:69]
	s_mov_b32 m0, s21
	v_lshl_add_u64 v[212:213], s[2:3], 0, v[130:131]
	s_barrier
	ds_read_b128 v[160:163], v147 offset:16384
	ds_read_b128 v[164:167], v147 offset:17408
	ds_read_b128 v[168:171], v147 offset:18432
	ds_read_b128 v[172:175], v147 offset:19456
	ds_read_b128 v[176:179], v147 offset:20480
	ds_read_b128 v[180:183], v147 offset:21504
	ds_read_b128 v[184:187], v147 offset:22528
	ds_read_b128 v[188:191], v147 offset:23552
	global_load_lds_dwordx4 v[212:213], off
	v_lshl_add_u64 v[214:215], s[2:3], 0, v[132:133]
	s_mov_b32 m0, s22
	s_nop 0
	global_load_lds_dwordx4 v[214:215], off
	s_waitcnt lgkmcnt(0)
	s_barrier
	v_mfma_f32_16x16x32_bf16 v[60:63], v[140:143], v[160:163], v[60:63]
	v_mfma_f32_16x16x32_bf16 v[56:59], v[152:155], v[160:163], v[56:59]
	v_mfma_f32_16x16x32_bf16 v[44:47], v[140:143], v[168:171], v[44:47]
	v_mfma_f32_16x16x32_bf16 v[40:43], v[152:155], v[168:171], v[40:43]
	v_mfma_f32_16x16x32_bf16 v[28:31], v[140:143], v[176:179], v[28:31]
	v_mfma_f32_16x16x32_bf16 v[24:27], v[152:155], v[176:179], v[24:27]
	v_mfma_f32_16x16x32_bf16 v[12:15], v[140:143], v[184:187], v[12:15]
	v_mfma_f32_16x16x32_bf16 v[8:11], v[152:155], v[184:187], v[8:11]
	v_mfma_f32_16x16x32_bf16 v[60:63], v[148:151], v[164:167], v[60:63]
	v_mfma_f32_16x16x32_bf16 v[56:59], v[156:159], v[164:167], v[56:59]
	v_mfma_f32_16x16x32_bf16 v[44:47], v[148:151], v[172:175], v[44:47]
	v_mfma_f32_16x16x32_bf16 v[40:43], v[156:159], v[172:175], v[40:43]
	v_mfma_f32_16x16x32_bf16 v[28:31], v[148:151], v[180:183], v[28:31]
	v_mfma_f32_16x16x32_bf16 v[24:27], v[156:159], v[180:183], v[24:27]
	v_mfma_f32_16x16x32_bf16 v[12:15], v[148:151], v[188:191], v[12:15]
	v_mfma_f32_16x16x32_bf16 v[8:11], v[156:159], v[188:191], v[8:11]
	s_barrier
; #define PG8_STAGE(bufoff, gbase, voff) do { _Pragma("unroll") for (int _i = 0; _i < 2; ++_i) \
;         __builtin_amdgcn_global_load_lds((const unsigned*)((const char*)(gbase) + (voff)[_i]), (LAS unsigned*)(lds + (bufoff) + ldsw + _i * 8192), 16, 0, 0); } while (0)
; #define PG8_LDA(dst, b, h) do { _Pragma("unroll") for (int m = 0; m < 4; ++m) _Pragma("unroll") for (int k = 0; k < 2; ++k) dst[m][k] = *(const LAS bf16x8*)(lds + PG8_SA(b, h) + aoff + m * 2048 + k * 1024); } while (0)
; #define PG8_LDB(dst, b, h) do { _Pragma("unroll") for (int n = 0; n < 2; ++n) _Pragma("unroll") for (int k = 0; k < 2; ++k) dst[n][k] = *(const LAS bf16x8*)(lds + PG8_SB(b, h) + boff + n * 2048 + k * 1024); } while (0)
; #define PG8_MMA(ai, bj, At, Bt) do { __builtin_amdgcn_s_setprio(1); _Pragma("unroll") for (int m = 0; m < 4; ++m) _Pragma("unroll") for (int n = 0; n < 2; ++n) _Pragma("unroll") for (int k = 0; k < 2; ++k) \
;         acc[ai][bj][m][n] = __builtin_amdgcn_mfma_f32_16x16x32_bf16(Bt[n][k], At[m][k], acc[ai][bj][m][n], 0, 0, 0); __builtin_amdgcn_s_setprio(0); } while (0)
; #define PG8_WAIT_V(n) asm volatile("s_waitcnt vmcnt(" #n ")" ::: "memory")
; #define PG8_WAIT_L(n) asm volatile("s_waitcnt lgkmcnt(" #n ")" ::: "memory")
; #define PG8_BAR __builtin_amdgcn_s_barrier()
; #define PG8_SCHED __builtin_amdgcn_sched_barrier(0)
;     ...
;             PG8_STAGE(PG8_SB(0, 1), b2 + hstep, voffB);
;             PG8_WAIT_V(6); PG8_BAR; PG8_MMA(1, 1, At, B1); PG8_BAR;
;             PG8_LDB(B0, 1, 0); PG8_SCHED; PG8_LDA(At, 1, 0); PG8_STAGE(PG8_SA(0, 1), a2 + hstep, voffA);
;             PG8_WAIT_L(8); PG8_BAR; PG8_WAIT_L(0); PG8_MMA(0, 0, At, B0); PG8_BAR; PG8_SCHED;
;             PG8_LDB(B1, 1, 1); PG8_STAGE(PG8_SB(1, 0), b3, voffB);
;             PG8_BAR; PG8_WAIT_L(0); PG8_MMA(0, 1, At, B1); PG8_BAR;
;             PG8_LDA(At, 1, 1); PG8_STAGE(PG8_SA(1, 0), a3, voffA);
;             PG8_BAR; PG8_WAIT_L(0); PG8_MMA(1, 0, At, B0); PG8_BAR; PG8_SCHED;
	s_add_u32 s8, s12, 0x84000
	s_addc_u32 s9, s13, 0
	s_add_i32 s35, s45, s20
	v_lshl_add_u64 v[140:141], s[8:9], 0, v[64:65]
	s_mov_b32 m0, s35
	s_nop 0
	global_load_lds_dwordx4 v[140:141], off
	v_lshl_add_u64 v[140:141], s[8:9], 0, v[134:135]
	s_add_i32 m0, s35, 0x2000
	s_nop 0
	global_load_lds_dwordx4 v[140:141], off
	s_waitcnt vmcnt(6)
	s_barrier
	v_mfma_f32_16x16x32_bf16 v[52:55], v[192:195], v[160:163], v[52:55]
	v_mfma_f32_16x16x32_bf16 v[48:51], v[220:223], v[160:163], v[48:51]
	v_mfma_f32_16x16x32_bf16 v[36:39], v[192:195], v[168:171], v[36:39]
	v_mfma_f32_16x16x32_bf16 v[32:35], v[220:223], v[168:171], v[32:35]
	v_mfma_f32_16x16x32_bf16 v[20:23], v[192:195], v[176:179], v[20:23]
	v_mfma_f32_16x16x32_bf16 v[16:19], v[220:223], v[176:179], v[16:19]
	v_mfma_f32_16x16x32_bf16 v[4:7], v[192:195], v[184:187], v[4:7]
	v_mfma_f32_16x16x32_bf16 v[0:3], v[220:223], v[184:187], v[0:3]
	v_mfma_f32_16x16x32_bf16 v[52:55], v[196:199], v[164:167], v[52:55]
	v_mfma_f32_16x16x32_bf16 v[48:51], v[224:227], v[164:167], v[48:51]
	v_mfma_f32_16x16x32_bf16 v[36:39], v[196:199], v[172:175], v[36:39]
	v_mfma_f32_16x16x32_bf16 v[32:35], v[224:227], v[172:175], v[32:35]
	v_mfma_f32_16x16x32_bf16 v[20:23], v[196:199], v[180:183], v[20:23]
	v_mfma_f32_16x16x32_bf16 v[16:19], v[224:227], v[180:183], v[16:19]
	v_mfma_f32_16x16x32_bf16 v[4:7], v[196:199], v[188:191], v[4:7]
	v_mfma_f32_16x16x32_bf16 v[0:3], v[224:227], v[188:191], v[0:3]
	s_add_i32 s8, 0, 0x18000
	v_add_u32_e32 v156, s8, v145
	s_barrier
	ds_read_b128 v[140:143], v156
	ds_read_b128 v[148:151], v156 offset:1024
	ds_read_b128 v[152:155], v156 offset:2048
	ds_read_b128 v[156:159], v156 offset:3072
	s_add_u32 s2, s2, 0x84000
	s_addc_u32 s3, s3, 0
	s_mov_b32 m0, s23
	v_lshl_add_u64 v[192:193], s[2:3], 0, v[130:131]
	ds_read_b128 v[160:163], v147 offset:32768
	ds_read_b128 v[164:167], v147 offset:33792
	ds_read_b128 v[168:171], v147 offset:34816
	ds_read_b128 v[172:175], v147 offset:35840
	ds_read_b128 v[176:179], v147 offset:36864
	ds_read_b128 v[180:183], v147 offset:37888
	ds_read_b128 v[184:187], v147 offset:38912
	ds_read_b128 v[188:191], v147 offset:39936
	global_load_lds_dwordx4 v[192:193], off
	v_lshl_add_u64 v[192:193], s[2:3], 0, v[132:133]
	s_mov_b32 m0, s24
	s_nop 0
	global_load_lds_dwordx4 v[192:193], off
	s_waitcnt lgkmcnt(8)
	s_barrier
	s_waitcnt lgkmcnt(0)
	v_mfma_f32_16x16x32_bf16 v[126:129], v[140:143], v[160:163], v[126:129]
	v_mfma_f32_16x16x32_bf16 v[122:125], v[152:155], v[160:163], v[122:125]
	v_mfma_f32_16x16x32_bf16 v[110:113], v[140:143], v[168:171], v[110:113]
	v_mfma_f32_16x16x32_bf16 v[106:109], v[152:155], v[168:171], v[106:109]
	v_mfma_f32_16x16x32_bf16 v[94:97], v[140:143], v[176:179], v[94:97]
	v_mfma_f32_16x16x32_bf16 v[90:93], v[152:155], v[176:179], v[90:93]
	v_mfma_f32_16x16x32_bf16 v[78:81], v[140:143], v[184:187], v[78:81]
	v_mfma_f32_16x16x32_bf16 v[74:77], v[152:155], v[184:187], v[74:77]
	v_mfma_f32_16x16x32_bf16 v[126:129], v[148:151], v[164:167], v[126:129]
	v_mfma_f32_16x16x32_bf16 v[122:125], v[156:159], v[164:167], v[122:125]
	v_mfma_f32_16x16x32_bf16 v[110:113], v[148:151], v[172:175], v[110:113]
	v_mfma_f32_16x16x32_bf16 v[106:109], v[156:159], v[172:175], v[106:109]
	v_mfma_f32_16x16x32_bf16 v[94:97], v[148:151], v[180:183], v[94:97]
	v_mfma_f32_16x16x32_bf16 v[90:93], v[156:159], v[180:183], v[90:93]
	v_mfma_f32_16x16x32_bf16 v[78:81], v[148:151], v[188:191], v[78:81]
	v_mfma_f32_16x16x32_bf16 v[74:77], v[156:159], v[188:191], v[74:77]
	s_barrier
	s_add_i32 s9, 0, 0x1c000
	s_add_i32 s2, s8, s20
	v_add_u32_e32 v219, s9, v145
	v_lshl_add_u64 v[208:209], v[208:209], 0, s[16:17]
	s_mov_b32 m0, s2
	ds_read_b128 v[192:195], v219
	ds_read_b128 v[196:199], v219 offset:1024
	ds_read_b128 v[220:223], v219 offset:2048
	ds_read_b128 v[224:227], v219 offset:3072
	global_load_lds_dwordx4 v[208:209], off
	v_lshl_add_u64 v[208:209], v[210:211], 0, s[16:17]
	s_add_i32 m0, s2, 0x2000
	s_nop 0
	global_load_lds_dwordx4 v[208:209], off
	s_waitcnt lgkmcnt(0)
	s_barrier
	v_mfma_f32_16x16x32_bf16 v[118:121], v[192:195], v[160:163], v[118:121]
	v_mfma_f32_16x16x32_bf16 v[114:117], v[220:223], v[160:163], v[114:117]
	v_mfma_f32_16x16x32_bf16 v[102:105], v[192:195], v[168:171], v[102:105]
	v_mfma_f32_16x16x32_bf16 v[98:101], v[220:223], v[168:171], v[98:101]
	v_mfma_f32_16x16x32_bf16 v[86:89], v[192:195], v[176:179], v[86:89]
	v_mfma_f32_16x16x32_bf16 v[82:85], v[220:223], v[176:179], v[82:85]
	v_mfma_f32_16x16x32_bf16 v[70:73], v[192:195], v[184:187], v[70:73]
	v_mfma_f32_16x16x32_bf16 v[66:69], v[220:223], v[184:187], v[66:69]
	v_mfma_f32_16x16x32_bf16 v[118:121], v[196:199], v[164:167], v[118:121]
	v_mfma_f32_16x16x32_bf16 v[114:117], v[224:227], v[164:167], v[114:117]
	v_mfma_f32_16x16x32_bf16 v[102:105], v[196:199], v[172:175], v[102:105]
	v_mfma_f32_16x16x32_bf16 v[98:101], v[224:227], v[172:175], v[98:101]
	v_mfma_f32_16x16x32_bf16 v[86:89], v[196:199], v[180:183], v[86:89]
	v_mfma_f32_16x16x32_bf16 v[82:85], v[224:227], v[180:183], v[82:85]
	v_mfma_f32_16x16x32_bf16 v[70:73], v[196:199], v[188:191], v[70:73]
	v_mfma_f32_16x16x32_bf16 v[66:69], v[224:227], v[188:191], v[66:69]
	s_mov_b32 m0, s25
	v_lshl_add_u64 v[208:209], v[212:213], 0, s[16:17]
	s_barrier
	ds_read_b128 v[160:163], v147 offset:49152
	ds_read_b128 v[164:167], v147 offset:50176
	ds_read_b128 v[168:171], v147 offset:51200
	ds_read_b128 v[172:175], v147 offset:52224
	ds_read_b128 v[176:179], v147 offset:53248
	ds_read_b128 v[180:183], v147 offset:54272
	ds_read_b128 v[184:187], v147 offset:55296
	ds_read_b128 v[188:191], v147 offset:56320
	global_load_lds_dwordx4 v[208:209], off
	v_lshl_add_u64 v[208:209], v[214:215], 0, s[16:17]
	s_mov_b32 m0, s26
	s_nop 0
	global_load_lds_dwordx4 v[208:209], off
	s_waitcnt lgkmcnt(0)
	s_barrier
; __device__ __forceinline__ unsigned cvt_pk_bf16(float lo, float hi) { unsigned r; asm volatile("v_cvt_pk_bf16_f32 %0, %1, %2" : "=v"(r) : "v"(lo), "v"(hi)); return r; }
; #define PG8_STAGE(bufoff, gbase, voff) do { _Pragma("unroll") for (int _i = 0; _i < 2; ++_i) \
;         __builtin_amdgcn_global_load_lds((const unsigned*)((const char*)(gbase) + (voff)[_i]), (LAS unsigned*)(lds + (bufoff) + ldsw + _i * 8192), 16, 0, 0); } while (0)
; #define PG8_MMA(ai, bj, At, Bt) do { __builtin_amdgcn_s_setprio(1); _Pragma("unroll") for (int m = 0; m < 4; ++m) _Pragma("unroll") for (int n = 0; n < 2; ++n) _Pragma("unroll") for (int k = 0; k < 2; ++k) \
;         acc[ai][bj][m][n] = __builtin_amdgcn_mfma_f32_16x16x32_bf16(Bt[n][k], At[m][k], acc[ai][bj][m][n], 0, 0, 0); __builtin_amdgcn_s_setprio(0); } while (0)
; #define PG8_WAIT_V(n) asm volatile("s_waitcnt vmcnt(" #n ")" ::: "memory")
; #define PG8_WAIT_L(n) asm volatile("s_waitcnt lgkmcnt(" #n ")" ::: "memory")
;     __device__ __forceinline__ void operator()(const f32x4 (&acc)[2][2][4][2], const Unit& u, int wr, int wc, int fr, int fq) const {
;         const int row0 = u.pm * BM + wr * 64 + fr, col0 = u.pn * BM + wc * 32 + 8 * fq;
; #pragma unroll
;         for (int ai = 0; ai < 2; ++ai)
; #pragma unroll
;             for (int m = 0; m < 4; ++m) { bf16_t* rowp = O + (size_t)(row0 + ai * HALF + m * 16) * LDF + col0;
; #pragma unroll
;                 for (int bj = 0; bj < 2; ++bj) { f32x4 v0 = acc[ai][bj][m][0], v1 = acc[ai][bj][m][1];
; #pragma unroll
;                     for (int j = 0; j < 4; ++j) { const float a = fmaxf(v0[j], 0.f), b = fmaxf(v1[j], 0.f); v0[j] = a * a; v1[j] = b * b; }
;                     u32x4 w; w.x = cvt_pk_bf16(v0[0], v0[1]); w.y = cvt_pk_bf16(v0[2], v0[3]); w.z = cvt_pk_bf16(v1[0], v1[1]); w.w = cvt_pk_bf16(v1[2], v1[3]);
;                     *(u32x4*)(rowp + bj * HALF) = w; } }
;     ...
;             PG8_BAR; PG8_WAIT_L(0); PG8_MMA(1, 0, At, B0); PG8_BAR; PG8_SCHED;
;             PG8_STAGE(PG8_SB(1, 1), b3 + hstep, voffB);
;             PG8_WAIT_V(6); PG8_BAR; PG8_MMA(1, 1, At, B1); PG8_BAR;
;         }
;         if constexpr (Epi::FUSE_LN) {
;             if (E.fuse && cur.ks < 0) { if (wr == 0) PG8_BAR; E.fused(acc, cur, wr, wc, fr, fq, lds); if (wr == 1) PG8_BAR; }
;             else E(acc, cur, wr, wc, fr, fq);
;         } else E(acc, cur, wr, wc, fr, fq);
;         if (!has_next) break;
	v_mfma_f32_16x16x32_bf16 v[60:63], v[140:143], v[160:163], v[60:63]
	v_mfma_f32_16x16x32_bf16 v[56:59], v[152:155], v[160:163], v[56:59]
	v_mfma_f32_16x16x32_bf16 v[44:47], v[140:143], v[168:171], v[44:47]
	v_mfma_f32_16x16x32_bf16 v[40:43], v[152:155], v[168:171], v[40:43]
	v_mfma_f32_16x16x32_bf16 v[28:31], v[140:143], v[176:179], v[28:31]
	v_mfma_f32_16x16x32_bf16 v[24:27], v[152:155], v[176:179], v[24:27]
	v_mfma_f32_16x16x32_bf16 v[12:15], v[140:143], v[184:187], v[12:15]
	v_mfma_f32_16x16x32_bf16 v[8:11], v[152:155], v[184:187], v[8:11]
	v_mfma_f32_16x16x32_bf16 v[60:63], v[148:151], v[164:167], v[60:63]
	v_mfma_f32_16x16x32_bf16 v[56:59], v[156:159], v[164:167], v[56:59]
	v_mfma_f32_16x16x32_bf16 v[44:47], v[148:151], v[172:175], v[44:47]
	v_mfma_f32_16x16x32_bf16 v[40:43], v[156:159], v[172:175], v[40:43]
	v_mfma_f32_16x16x32_bf16 v[28:31], v[148:151], v[180:183], v[28:31]
	v_mfma_f32_16x16x32_bf16 v[24:27], v[156:159], v[180:183], v[24:27]
	v_mfma_f32_16x16x32_bf16 v[12:15], v[148:151], v[188:191], v[12:15]
	v_mfma_f32_16x16x32_bf16 v[8:11], v[156:159], v[188:191], v[8:11]
	s_barrier
	s_add_u32 s2, s12, 0x84080
	s_addc_u32 s3, s13, 0
	s_add_i32 s8, s9, s20
	v_lshl_add_u64 v[140:141], s[2:3], 0, v[64:65]
	s_mov_b32 m0, s8
	s_nop 0
	global_load_lds_dwordx4 v[140:141], off
	v_lshl_add_u64 v[140:141], s[2:3], 0, v[134:135]
	s_add_i32 m0, s8, 0x2000
	s_nop 0
	global_load_lds_dwordx4 v[140:141], off
	s_waitcnt vmcnt(6)
	s_barrier
	v_mfma_f32_16x16x32_bf16 v[52:55], v[192:195], v[160:163], v[52:55]
	v_mfma_f32_16x16x32_bf16 v[48:51], v[220:223], v[160:163], v[48:51]
	v_mfma_f32_16x16x32_bf16 v[36:39], v[192:195], v[168:171], v[36:39]
	v_mfma_f32_16x16x32_bf16 v[32:35], v[220:223], v[168:171], v[32:35]
	v_mfma_f32_16x16x32_bf16 v[20:23], v[192:195], v[176:179], v[20:23]
	v_mfma_f32_16x16x32_bf16 v[16:19], v[220:223], v[176:179], v[16:19]
	v_mfma_f32_16x16x32_bf16 v[4:7], v[192:195], v[184:187], v[4:7]
	v_mfma_f32_16x16x32_bf16 v[0:3], v[220:223], v[184:187], v[0:3]
	v_mfma_f32_16x16x32_bf16 v[52:55], v[196:199], v[164:167], v[52:55]
	v_mfma_f32_16x16x32_bf16 v[48:51], v[224:227], v[164:167], v[48:51]
	v_mfma_f32_16x16x32_bf16 v[36:39], v[196:199], v[172:175], v[36:39]
	v_mfma_f32_16x16x32_bf16 v[32:35], v[224:227], v[172:175], v[32:35]
	v_mfma_f32_16x16x32_bf16 v[20:23], v[196:199], v[180:183], v[20:23]
	v_mfma_f32_16x16x32_bf16 v[16:19], v[224:227], v[180:183], v[16:19]
	v_mfma_f32_16x16x32_bf16 v[4:7], v[196:199], v[188:191], v[4:7]
	v_mfma_f32_16x16x32_bf16 v[0:3], v[224:227], v[188:191], v[0:3]
	s_add_u32 s42, s42, 0x100
	s_addc_u32 s43, s43, 0
	s_cmp_ge_u32 s44, s40
	s_mov_b64 s[8:9], s[10:11]
	s_mov_b32 s2, s44
	s_barrier
	s_cbranch_scc0 .LBB0_120
	v_max_f32_e32 v122, 0, v122
	v_lshl_or_b32 v142, s37, 8, v146
	v_mul_f32_e32 v151, v122, v122
	v_max_f32_e32 v122, v127, v127
	v_max_f32_e32 v123, 0, v123
	v_max_f32_e32 v124, 0, v124
	v_lshl_add_u32 v150, s38, 8, v144
	v_ashrrev_i32_e32 v143, 31, v142
	v_mov_b64_e32 v[140:141], s[80:81]
	s_movk_i32 s8, 0x4080
	v_max_f32_e32 v122, 0, v122
	v_mul_f32_e32 v127, v123, v123
	v_max_f32_e32 v123, v128, v128
	v_mul_f32_e32 v128, v124, v124
	v_max_f32_e32 v124, v129, v129
	v_mad_i64_i32 v[148:149], s[2:3], v150, s8, v[140:141]
	v_lshlrev_b64 v[142:143], 1, v[142:143]
	v_max_f32_e32 v126, 0, v126
	v_mul_f32_e32 v122, v122, v122
	v_max_f32_e32 v123, 0, v123
	v_max_f32_e32 v124, 0, v124
	v_max_f32_e32 v125, 0, v125
	v_lshl_add_u64 v[148:149], v[148:149], 0, v[142:143]
	v_mul_f32_e32 v126, v126, v126
	v_mul_f32_e32 v123, v123, v123
	v_mul_f32_e32 v124, v124, v124
	v_mul_f32_e32 v125, v125, v125
	v_cvt_pk_bf16_f32 v122, v126, v122
	v_max_f32_e32 v114, 0, v114
	v_max_f32_e32 v115, 0, v115
	v_max_f32_e32 v116, 0, v116
	v_cvt_pk_bf16_f32 v123, v123, v124
	v_cvt_pk_bf16_f32 v124, v151, v127
	v_cvt_pk_bf16_f32 v125, v128, v125
	global_store_dwordx4 v[148:149], v[122:125], off
	s_nop 1
	v_mul_f32_e32 v122, v114, v114
	v_max_f32_e32 v114, v119, v119
	v_mul_f32_e32 v119, v115, v115
	v_max_f32_e32 v115, v120, v120
	v_mul_f32_e32 v120, v116, v116
	v_max_f32_e32 v116, v121, v121
	v_max_f32_e32 v114, 0, v114
	v_max_f32_e32 v115, 0, v115
	v_max_f32_e32 v116, 0, v116
	v_max_f32_e32 v118, 0, v118
	v_mul_f32_e32 v114, v114, v114
	v_mul_f32_e32 v115, v115, v115
	v_max_f32_e32 v117, 0, v117
	v_mul_f32_e32 v116, v116, v116
	v_mul_f32_e32 v118, v118, v118
	v_mul_f32_e32 v117, v117, v117
	v_cvt_pk_bf16_f32 v114, v118, v114
	v_cvt_pk_bf16_f32 v115, v115, v116
	v_cvt_pk_bf16_f32 v116, v122, v119
	v_max_f32_e32 v106, 0, v106
	v_cvt_pk_bf16_f32 v117, v120, v117
	global_store_dwordx4 v[148:149], v[114:117], off offset:256
	s_nop 1
	v_max_f32_e32 v107, 0, v107
	v_max_f32_e32 v108, 0, v108
	v_mul_f32_e32 v116, v106, v106
	v_max_f32_e32 v106, v111, v111
	v_or_b32_e32 v114, 16, v150
	v_max_f32_e32 v106, 0, v106
	v_mul_f32_e32 v111, v107, v107
	v_max_f32_e32 v107, v112, v112
	v_mul_f32_e32 v112, v108, v108
	v_max_f32_e32 v108, v113, v113
	v_mad_i64_i32 v[114:115], s[2:3], v114, s8, v[140:141]
	v_max_f32_e32 v110, 0, v110
	v_mul_f32_e32 v106, v106, v106
	v_max_f32_e32 v107, 0, v107
	v_max_f32_e32 v108, 0, v108
	v_max_f32_e32 v109, 0, v109
	v_lshl_add_u64 v[114:115], v[114:115], 0, v[142:143]
	v_mul_f32_e32 v110, v110, v110
	v_mul_f32_e32 v107, v107, v107
	v_mul_f32_e32 v108, v108, v108
	v_mul_f32_e32 v109, v109, v109
	v_cvt_pk_bf16_f32 v106, v110, v106
	v_max_f32_e32 v98, 0, v98
	v_max_f32_e32 v99, 0, v99
	v_max_f32_e32 v100, 0, v100
	v_cvt_pk_bf16_f32 v107, v107, v108
	v_cvt_pk_bf16_f32 v108, v116, v111
	v_cvt_pk_bf16_f32 v109, v112, v109
	global_store_dwordx4 v[114:115], v[106:109], off
	s_nop 1
	v_mul_f32_e32 v106, v98, v98
; __device__ __forceinline__ unsigned cvt_pk_bf16(float lo, float hi) { unsigned r; asm volatile("v_cvt_pk_bf16_f32 %0, %1, %2" : "=v"(r) : "v"(lo), "v"(hi)); return r; }
;     __device__ __forceinline__ void operator()(const f32x4 (&acc)[2][2][4][2], const Unit& u, int wr, int wc, int fr, int fq) const {
;         const int row0 = u.pm * BM + wr * 64 + fr, col0 = u.pn * BM + wc * 32 + 8 * fq;
; #pragma unroll
;         for (int ai = 0; ai < 2; ++ai)
; #pragma unroll
;             for (int m = 0; m < 4; ++m) { bf16_t* rowp = O + (size_t)(row0 + ai * HALF + m * 16) * LDF + col0;
; #pragma unroll
;                 for (int bj = 0; bj < 2; ++bj) { f32x4 v0 = acc[ai][bj][m][0], v1 = acc[ai][bj][m][1];
; #pragma unroll
;                     for (int j = 0; j < 4; ++j) { const float a = fmaxf(v0[j], 0.f), b = fmaxf(v1[j], 0.f); v0[j] = a * a; v1[j] = b * b; }
;                     u32x4 w; w.x = cvt_pk_bf16(v0[0], v0[1]); w.y = cvt_pk_bf16(v0[2], v0[3]); w.z = cvt_pk_bf16(v1[0], v1[1]); w.w = cvt_pk_bf16(v1[2], v1[3]);
;                     *(u32x4*)(rowp + bj * HALF) = w; } }
	v_max_f32_e32 v98, v103, v103
	v_mul_f32_e32 v103, v99, v99
	v_max_f32_e32 v99, v104, v104
	v_mul_f32_e32 v104, v100, v100
	v_max_f32_e32 v100, v105, v105
	v_max_f32_e32 v98, 0, v98
	v_max_f32_e32 v99, 0, v99
	v_max_f32_e32 v100, 0, v100
	v_max_f32_e32 v102, 0, v102
	v_mul_f32_e32 v98, v98, v98
	v_mul_f32_e32 v99, v99, v99
	v_max_f32_e32 v101, 0, v101
	v_mul_f32_e32 v100, v100, v100
	v_mul_f32_e32 v102, v102, v102
	v_mul_f32_e32 v101, v101, v101
	v_cvt_pk_bf16_f32 v98, v102, v98
	v_cvt_pk_bf16_f32 v99, v99, v100
	v_cvt_pk_bf16_f32 v100, v106, v103
	v_max_f32_e32 v90, 0, v90
	v_cvt_pk_bf16_f32 v101, v104, v101
	global_store_dwordx4 v[114:115], v[98:101], off offset:256
	s_nop 1
	v_max_f32_e32 v91, 0, v91
	v_max_f32_e32 v92, 0, v92
	v_mul_f32_e32 v100, v90, v90
	v_max_f32_e32 v90, v95, v95
	v_or_b32_e32 v98, 32, v150
	v_max_f32_e32 v90, 0, v90
	v_mul_f32_e32 v95, v91, v91
	v_max_f32_e32 v91, v96, v96
	v_mul_f32_e32 v96, v92, v92
	v_max_f32_e32 v92, v97, v97
	v_mad_i64_i32 v[98:99], s[2:3], v98, s8, v[140:141]
	v_max_f32_e32 v94, 0, v94
	v_mul_f32_e32 v90, v90, v90
	v_max_f32_e32 v91, 0, v91
	v_max_f32_e32 v92, 0, v92
	v_max_f32_e32 v93, 0, v93
	v_lshl_add_u64 v[98:99], v[98:99], 0, v[142:143]
	v_mul_f32_e32 v94, v94, v94
	v_mul_f32_e32 v91, v91, v91
	v_mul_f32_e32 v92, v92, v92
	v_mul_f32_e32 v93, v93, v93
	v_cvt_pk_bf16_f32 v90, v94, v90
	v_max_f32_e32 v82, 0, v82
	v_max_f32_e32 v83, 0, v83
	v_max_f32_e32 v84, 0, v84
	v_cvt_pk_bf16_f32 v91, v91, v92
	v_cvt_pk_bf16_f32 v92, v100, v95
	v_cvt_pk_bf16_f32 v93, v96, v93
	global_store_dwordx4 v[98:99], v[90:93], off
	s_nop 1
	v_mul_f32_e32 v90, v82, v82
	v_max_f32_e32 v82, v87, v87
	v_mul_f32_e32 v87, v83, v83
	v_max_f32_e32 v83, v88, v88
	v_mul_f32_e32 v88, v84, v84
	v_max_f32_e32 v84, v89, v89
	v_max_f32_e32 v82, 0, v82
	v_max_f32_e32 v83, 0, v83
	v_max_f32_e32 v84, 0, v84
	v_max_f32_e32 v86, 0, v86
	v_mul_f32_e32 v82, v82, v82
	v_mul_f32_e32 v83, v83, v83
	v_max_f32_e32 v85, 0, v85
	v_mul_f32_e32 v84, v84, v84
	v_mul_f32_e32 v86, v86, v86
	v_mul_f32_e32 v85, v85, v85
	v_cvt_pk_bf16_f32 v82, v86, v82
	v_cvt_pk_bf16_f32 v83, v83, v84
	v_cvt_pk_bf16_f32 v84, v90, v87
	v_max_f32_e32 v74, 0, v74
	v_cvt_pk_bf16_f32 v85, v88, v85
	global_store_dwordx4 v[98:99], v[82:85], off offset:256
	s_nop 1
	v_max_f32_e32 v75, 0, v75
	v_max_f32_e32 v76, 0, v76
	v_mul_f32_e32 v84, v74, v74
	v_max_f32_e32 v74, v79, v79
	v_or_b32_e32 v82, 48, v150
	v_max_f32_e32 v74, 0, v74
	v_mul_f32_e32 v79, v75, v75
	v_max_f32_e32 v75, v80, v80
	v_mul_f32_e32 v80, v76, v76
	v_max_f32_e32 v76, v81, v81
	v_mad_i64_i32 v[82:83], s[2:3], v82, s8, v[140:141]
	v_max_f32_e32 v78, 0, v78
	v_mul_f32_e32 v74, v74, v74
	v_max_f32_e32 v75, 0, v75
	v_max_f32_e32 v76, 0, v76
	v_max_f32_e32 v77, 0, v77
	v_lshl_add_u64 v[82:83], v[82:83], 0, v[142:143]
	v_mul_f32_e32 v78, v78, v78
	v_mul_f32_e32 v75, v75, v75
	v_mul_f32_e32 v76, v76, v76
	v_mul_f32_e32 v77, v77, v77
	v_cvt_pk_bf16_f32 v74, v78, v74
	v_max_f32_e32 v66, 0, v66
	v_max_f32_e32 v67, 0, v67
	v_max_f32_e32 v68, 0, v68
	v_cvt_pk_bf16_f32 v75, v75, v76
	v_cvt_pk_bf16_f32 v76, v84, v79
	v_cvt_pk_bf16_f32 v77, v80, v77
	global_store_dwordx4 v[82:83], v[74:77], off
	s_nop 1
	v_mul_f32_e32 v74, v66, v66
	v_max_f32_e32 v66, v71, v71
	v_mul_f32_e32 v71, v67, v67
	v_max_f32_e32 v67, v72, v72
	v_mul_f32_e32 v72, v68, v68
	v_max_f32_e32 v68, v73, v73
	v_max_f32_e32 v66, 0, v66
	v_max_f32_e32 v67, 0, v67
	v_max_f32_e32 v68, 0, v68
	v_max_f32_e32 v70, 0, v70
	v_mul_f32_e32 v66, v66, v66
	v_mul_f32_e32 v67, v67, v67
	v_max_f32_e32 v69, 0, v69
	v_mul_f32_e32 v68, v68, v68
	v_mul_f32_e32 v70, v70, v70
	v_mul_f32_e32 v69, v69, v69
	v_cvt_pk_bf16_f32 v66, v70, v66
	v_cvt_pk_bf16_f32 v67, v67, v68
	v_cvt_pk_bf16_f32 v68, v74, v71
	v_max_f32_e32 v56, 0, v56
	v_cvt_pk_bf16_f32 v69, v72, v69
	global_store_dwordx4 v[82:83], v[66:69], off offset:256
	s_nop 1
	v_max_f32_e32 v57, 0, v57
	v_max_f32_e32 v58, 0, v58
	v_mul_f32_e32 v68, v56, v56
	v_max_f32_e32 v56, v61, v61
	v_add_u32_e32 v66, 0x80, v150
	v_max_f32_e32 v56, 0, v56
	v_mul_f32_e32 v61, v57, v57
	v_max_f32_e32 v57, v62, v62
	v_mul_f32_e32 v62, v58, v58
	v_max_f32_e32 v58, v63, v63
	v_mad_i64_i32 v[66:67], s[2:3], v66, s8, v[140:141]
	v_max_f32_e32 v60, 0, v60
	v_mul_f32_e32 v56, v56, v56
	v_max_f32_e32 v57, 0, v57
	v_max_f32_e32 v58, 0, v58
	v_max_f32_e32 v59, 0, v59
	v_lshl_add_u64 v[66:67], v[66:67], 0, v[142:143]
	v_mul_f32_e32 v60, v60, v60
	v_mul_f32_e32 v57, v57, v57
	v_mul_f32_e32 v58, v58, v58
	v_mul_f32_e32 v59, v59, v59
	v_cvt_pk_bf16_f32 v56, v60, v56
	v_max_f32_e32 v48, 0, v48
	v_max_f32_e32 v49, 0, v49
	v_max_f32_e32 v50, 0, v50
	v_cvt_pk_bf16_f32 v57, v57, v58
	v_cvt_pk_bf16_f32 v58, v68, v61
	v_cvt_pk_bf16_f32 v59, v62, v59
	global_store_dwordx4 v[66:67], v[56:59], off
	s_nop 1
	v_mul_f32_e32 v56, v48, v48
	v_max_f32_e32 v48, v53, v53
	v_mul_f32_e32 v53, v49, v49
	v_max_f32_e32 v49, v54, v54
	v_mul_f32_e32 v54, v50, v50
	v_max_f32_e32 v50, v55, v55
	v_max_f32_e32 v48, 0, v48
	v_max_f32_e32 v49, 0, v49
	v_max_f32_e32 v50, 0, v50
	v_max_f32_e32 v52, 0, v52
	v_mul_f32_e32 v48, v48, v48
	v_mul_f32_e32 v49, v49, v49
	v_max_f32_e32 v51, 0, v51
	v_mul_f32_e32 v50, v50, v50
	v_mul_f32_e32 v52, v52, v52
	v_mul_f32_e32 v51, v51, v51
	v_cvt_pk_bf16_f32 v48, v52, v48
; __device__ __forceinline__ unsigned cvt_pk_bf16(float lo, float hi) { unsigned r; asm volatile("v_cvt_pk_bf16_f32 %0, %1, %2" : "=v"(r) : "v"(lo), "v"(hi)); return r; }
; #define PG8_WAIT_V(n) asm volatile("s_waitcnt vmcnt(" #n ")" ::: "memory")
; #define PG8_BAR __builtin_amdgcn_s_barrier()
;     __device__ __forceinline__ void operator()(const f32x4 (&acc)[2][2][4][2], const Unit& u, int wr, int wc, int fr, int fq) const {
;         const int row0 = u.pm * BM + wr * 64 + fr, col0 = u.pn * BM + wc * 32 + 8 * fq;
; #pragma unroll
;         for (int ai = 0; ai < 2; ++ai)
; #pragma unroll
;             for (int m = 0; m < 4; ++m) { bf16_t* rowp = O + (size_t)(row0 + ai * HALF + m * 16) * LDF + col0;
; #pragma unroll
;                 for (int bj = 0; bj < 2; ++bj) { f32x4 v0 = acc[ai][bj][m][0], v1 = acc[ai][bj][m][1];
; #pragma unroll
;                     for (int j = 0; j < 4; ++j) { const float a = fmaxf(v0[j], 0.f), b = fmaxf(v1[j], 0.f); v0[j] = a * a; v1[j] = b * b; }
;                     u32x4 w; w.x = cvt_pk_bf16(v0[0], v0[1]); w.y = cvt_pk_bf16(v0[2], v0[3]); w.z = cvt_pk_bf16(v1[0], v1[1]); w.w = cvt_pk_bf16(v1[2], v1[3]);
;                     *(u32x4*)(rowp + bj * HALF) = w; } }
;     ...
;         if (!has_next) break;
; #pragma unroll
;         for (int a = 0; a < 2; ++a)
; #pragma unroll
;             for (int b = 0; b < 2; ++b)
; #pragma unroll
;                 for (int m = 0; m < 4; ++m)
; #pragma unroll
;                     for (int n = 0; n < 2; ++n) acc[a][b][m][n] = (f32x4){0.f, 0.f, 0.f, 0.f};
;         cur = nxt; cA = nA; cB = nB; ++ui;
;     }
;     PG8_WAIT_V(0);
;     if (wr == 0) PG8_BAR;
;     PG8_BAR;
	v_cvt_pk_bf16_f32 v49, v49, v50
	v_cvt_pk_bf16_f32 v50, v56, v53
	v_max_f32_e32 v40, 0, v40
	v_cvt_pk_bf16_f32 v51, v54, v51
	global_store_dwordx4 v[66:67], v[48:51], off offset:256
	s_nop 1
	v_max_f32_e32 v41, 0, v41
	v_max_f32_e32 v42, 0, v42
	v_mul_f32_e32 v50, v40, v40
	v_max_f32_e32 v40, v45, v45
	v_add_u32_e32 v48, 0x90, v150
	v_max_f32_e32 v40, 0, v40
	v_mul_f32_e32 v45, v41, v41
	v_max_f32_e32 v41, v46, v46
	v_mul_f32_e32 v46, v42, v42
	v_max_f32_e32 v42, v47, v47
	v_mad_i64_i32 v[48:49], s[2:3], v48, s8, v[140:141]
	v_max_f32_e32 v44, 0, v44
	v_mul_f32_e32 v40, v40, v40
	v_max_f32_e32 v41, 0, v41
	v_max_f32_e32 v42, 0, v42
	v_max_f32_e32 v43, 0, v43
	v_lshl_add_u64 v[48:49], v[48:49], 0, v[142:143]
	v_mul_f32_e32 v44, v44, v44
	v_mul_f32_e32 v41, v41, v41
	v_mul_f32_e32 v42, v42, v42
	v_mul_f32_e32 v43, v43, v43
	v_cvt_pk_bf16_f32 v40, v44, v40
	v_max_f32_e32 v32, 0, v32
	v_max_f32_e32 v33, 0, v33
	v_max_f32_e32 v34, 0, v34
	v_cvt_pk_bf16_f32 v41, v41, v42
	v_cvt_pk_bf16_f32 v42, v50, v45
	v_cvt_pk_bf16_f32 v43, v46, v43
	global_store_dwordx4 v[48:49], v[40:43], off
	s_nop 1
	v_mul_f32_e32 v40, v32, v32
	v_max_f32_e32 v32, v37, v37
	v_mul_f32_e32 v37, v33, v33
	v_max_f32_e32 v33, v38, v38
	v_mul_f32_e32 v38, v34, v34
	v_max_f32_e32 v34, v39, v39
	v_max_f32_e32 v32, 0, v32
	v_max_f32_e32 v33, 0, v33
	v_max_f32_e32 v34, 0, v34
	v_max_f32_e32 v36, 0, v36
	v_mul_f32_e32 v32, v32, v32
	v_mul_f32_e32 v33, v33, v33
	v_max_f32_e32 v35, 0, v35
	v_mul_f32_e32 v34, v34, v34
	v_mul_f32_e32 v36, v36, v36
	v_mul_f32_e32 v35, v35, v35
	v_cvt_pk_bf16_f32 v32, v36, v32
	v_cvt_pk_bf16_f32 v33, v33, v34
	v_cvt_pk_bf16_f32 v34, v40, v37
	v_max_f32_e32 v24, 0, v24
	v_cvt_pk_bf16_f32 v35, v38, v35
	global_store_dwordx4 v[48:49], v[32:35], off offset:256
	s_nop 1
	v_max_f32_e32 v25, 0, v25
	v_max_f32_e32 v26, 0, v26
	v_mul_f32_e32 v34, v24, v24
	v_max_f32_e32 v24, v29, v29
	v_add_u32_e32 v32, 0xa0, v150
	v_max_f32_e32 v24, 0, v24
	v_mul_f32_e32 v29, v25, v25
	v_max_f32_e32 v25, v30, v30
	v_mul_f32_e32 v30, v26, v26
	v_max_f32_e32 v26, v31, v31
	v_mad_i64_i32 v[32:33], s[2:3], v32, s8, v[140:141]
	v_max_f32_e32 v28, 0, v28
	v_mul_f32_e32 v24, v24, v24
	v_max_f32_e32 v25, 0, v25
	v_max_f32_e32 v26, 0, v26
	v_max_f32_e32 v27, 0, v27
	v_lshl_add_u64 v[32:33], v[32:33], 0, v[142:143]
	v_mul_f32_e32 v28, v28, v28
	v_mul_f32_e32 v25, v25, v25
	v_mul_f32_e32 v26, v26, v26
	v_mul_f32_e32 v27, v27, v27
	v_cvt_pk_bf16_f32 v24, v28, v24
	v_max_f32_e32 v16, 0, v16
	v_max_f32_e32 v17, 0, v17
	v_max_f32_e32 v18, 0, v18
	v_cvt_pk_bf16_f32 v25, v25, v26
	v_cvt_pk_bf16_f32 v26, v34, v29
	v_cvt_pk_bf16_f32 v27, v30, v27
	global_store_dwordx4 v[32:33], v[24:27], off
	s_nop 1
	v_mul_f32_e32 v24, v16, v16
	v_max_f32_e32 v16, v21, v21
	v_mul_f32_e32 v21, v17, v17
	v_max_f32_e32 v17, v22, v22
	v_mul_f32_e32 v22, v18, v18
	v_max_f32_e32 v18, v23, v23
	v_max_f32_e32 v16, 0, v16
	v_max_f32_e32 v17, 0, v17
	v_max_f32_e32 v18, 0, v18
	v_max_f32_e32 v20, 0, v20
	v_mul_f32_e32 v16, v16, v16
	v_mul_f32_e32 v17, v17, v17
	v_max_f32_e32 v19, 0, v19
	v_mul_f32_e32 v18, v18, v18
	v_mul_f32_e32 v20, v20, v20
	v_mul_f32_e32 v19, v19, v19
	v_cvt_pk_bf16_f32 v16, v20, v16
	v_cvt_pk_bf16_f32 v17, v17, v18
	v_cvt_pk_bf16_f32 v18, v24, v21
	v_max_f32_e32 v8, 0, v8
	v_cvt_pk_bf16_f32 v19, v22, v19
	global_store_dwordx4 v[32:33], v[16:19], off offset:256
	s_nop 1
	v_max_f32_e32 v9, 0, v9
	v_max_f32_e32 v10, 0, v10
	v_mul_f32_e32 v18, v8, v8
	v_max_f32_e32 v8, v13, v13
	v_add_u32_e32 v16, 0xb0, v150
	v_max_f32_e32 v8, 0, v8
	v_mul_f32_e32 v13, v9, v9
	v_max_f32_e32 v9, v14, v14
	v_mul_f32_e32 v14, v10, v10
	v_max_f32_e32 v10, v15, v15
	v_mad_i64_i32 v[16:17], s[2:3], v16, s8, v[140:141]
	v_max_f32_e32 v12, 0, v12
	v_mul_f32_e32 v8, v8, v8
	v_max_f32_e32 v9, 0, v9
	v_max_f32_e32 v10, 0, v10
	v_max_f32_e32 v11, 0, v11
	v_lshl_add_u64 v[16:17], v[16:17], 0, v[142:143]
	v_mul_f32_e32 v12, v12, v12
	v_mul_f32_e32 v9, v9, v9
	v_mul_f32_e32 v10, v10, v10
	v_mul_f32_e32 v11, v11, v11
	v_cvt_pk_bf16_f32 v8, v12, v8
	v_max_f32_e32 v0, 0, v0
	v_max_f32_e32 v1, 0, v1
	v_max_f32_e32 v2, 0, v2
	v_cvt_pk_bf16_f32 v9, v9, v10
	v_cvt_pk_bf16_f32 v10, v18, v13
	v_cvt_pk_bf16_f32 v11, v14, v11
	global_store_dwordx4 v[16:17], v[8:11], off
	s_nop 1
	v_mul_f32_e32 v8, v0, v0
	v_max_f32_e32 v0, v5, v5
	v_mul_f32_e32 v5, v1, v1
	v_max_f32_e32 v1, v6, v6
	v_mul_f32_e32 v6, v2, v2
	v_max_f32_e32 v2, v7, v7
	v_max_f32_e32 v0, 0, v0
	v_max_f32_e32 v1, 0, v1
	v_max_f32_e32 v2, 0, v2
	v_max_f32_e32 v3, 0, v3
	v_max_f32_e32 v4, 0, v4
	v_mul_f32_e32 v0, v0, v0
	v_mul_f32_e32 v1, v1, v1
	v_mul_f32_e32 v2, v2, v2
	v_mul_f32_e32 v3, v3, v3
	s_and_b64 vcc, exec, s[4:5]
	s_mov_b32 s38, s34
	s_mov_b32 s37, s36
	s_mov_b32 s40, s39
	s_mov_b64 s[10:11], s[18:19]
	s_mov_b64 s[8:9], s[6:7]
	s_mov_b32 s18, s33
	v_readlane_b32 s35, v251, 41
	v_mul_f32_e32 v4, v4, v4
	v_cvt_pk_bf16_f32 v0, v4, v0
	v_cvt_pk_bf16_f32 v1, v1, v2
	v_cvt_pk_bf16_f32 v2, v8, v5
	v_cvt_pk_bf16_f32 v3, v6, v3
	global_store_dwordx4 v[16:17], v[0:3], off offset:256
	s_nop 1
	s_cbranch_vccz .LBB0_96
	s_waitcnt vmcnt(0)
	v_readlane_b32 s40, v251, 24
	v_readlane_b32 s28, v252, 58
	s_cmpk_gt_u32 s15, 0xff
	s_movk_i32 s27, 0x1000
	v_readlane_b32 s41, v251, 25
	v_readlane_b32 s29, v252, 59
	s_cbranch_scc1 .LBB0_124
	s_barrier

; #define PG8_STAGE(bufoff, gbase, voff) do { _Pragma("unroll") for (int _i = 0; _i < 2; ++_i) \
;         __builtin_amdgcn_global_load_lds((const unsigned*)((const char*)(gbase) + (voff)[_i]), (LAS unsigned*)(lds + (bufoff) + ldsw + _i * 8192), 16, 0, 0); } while (0)
; #define PG8_LDA(dst, b, h) do { _Pragma("unroll") for (int m = 0; m < 4; ++m) _Pragma("unroll") for (int k = 0; k < 2; ++k) dst[m][k] = *(const LAS bf16x8*)(lds + PG8_SA(b, h) + aoff + m * 2048 + k * 1024); } while (0)
; #define PG8_LDB(dst, b, h) do { _Pragma("unroll") for (int n = 0; n < 2; ++n) _Pragma("unroll") for (int k = 0; k < 2; ++k) dst[n][k] = *(const LAS bf16x8*)(lds + PG8_SB(b, h) + boff + n * 2048 + k * 1024); } while (0)
; #define PG8_MMA(ai, bj, At, Bt) do { __builtin_amdgcn_s_setprio(1); _Pragma("unroll") for (int m = 0; m < 4; ++m) _Pragma("unroll") for (int n = 0; n < 2; ++n) _Pragma("unroll") for (int k = 0; k < 2; ++k) \
;         acc[ai][bj][m][n] = __builtin_amdgcn_mfma_f32_16x16x32_bf16(Bt[n][k], At[m][k], acc[ai][bj][m][n], 0, 0, 0); __builtin_amdgcn_s_setprio(0); } while (0)
; #define PG8_WAIT_L(n) asm volatile("s_waitcnt lgkmcnt(" #n ")" ::: "memory")
; #define PG8_BAR __builtin_amdgcn_s_barrier()
; #define PG8_SCHED __builtin_amdgcn_sched_barrier(0)
;     ...
;             const char* a1 = cA + (size_t)(t + 1) * kstep;
;             const char* a2 = last ? nA : cA + (size_t)(t + 2) * kstep; const char* b2 = last ? nB : cB + (size_t)(t + 2) * kstep;
;             const char* a3 = a2 + kstep; const char* b3 = b2 + kstep;
;             PG8_LDB(B0, 0, 0); PG8_SCHED; PG8_LDA(At, 0, 0); PG8_STAGE(PG8_SA(1, 1), a1 + hstep, voffA);
;             PG8_WAIT_L(8); PG8_BAR; PG8_WAIT_L(0); PG8_MMA(0, 0, At, B0); PG8_BAR; PG8_SCHED;
;             PG8_LDB(B1, 0, 1); PG8_STAGE(PG8_SB(0, 0), b2, voffB);
;             PG8_BAR; PG8_WAIT_L(0); PG8_MMA(0, 1, At, B1); PG8_BAR;
;             PG8_LDA(At, 0, 1); PG8_STAGE(PG8_SA(0, 0), a2, voffA);
;             PG8_BAR; PG8_WAIT_L(0); PG8_MMA(1, 0, At, B0); PG8_BAR; PG8_SCHED;
.LBB0_146:
	s_add_u32 s2, s8, 0xe515c080
	s_addc_u32 s3, s9, -1
	s_cmp_lg_u32 s27, 28
	s_cselect_b32 s10, s2, 0
	s_cselect_b32 s11, s3, 0
	s_add_u32 s2, s6, s10
	s_addc_u32 s3, s7, s11
	s_add_i32 s28, 0, 0x10000
	v_add_u32_e32 v156, s28, v142
	ds_read_b128 v[144:147], v156
	ds_read_b128 v[148:151], v156 offset:1024
	ds_read_b128 v[152:155], v156 offset:2048
	ds_read_b128 v[156:159], v156 offset:3072
	s_add_u32 s10, s4, s10
	s_addc_u32 s11, s5, s11
	v_lshl_add_u64 v[192:193], v[136:137], 0, s[8:9]
	s_add_i32 m0, s20, 0xc000
	ds_read_b128 v[160:163], v143
	ds_read_b128 v[164:167], v143 offset:1024
	ds_read_b128 v[168:171], v143 offset:2048
	ds_read_b128 v[172:175], v143 offset:3072
	ds_read_b128 v[176:179], v143 offset:4096
	ds_read_b128 v[180:183], v143 offset:5120
	ds_read_b128 v[184:187], v143 offset:6144
	ds_read_b128 v[188:191], v143 offset:7168
	global_load_lds_dwordx4 v[192:193], off
	v_lshl_add_u64 v[192:193], v[138:139], 0, s[8:9]
	s_add_i32 m0, s20, 0xe000
	s_nop 0
	global_load_lds_dwordx4 v[192:193], off
	s_waitcnt lgkmcnt(8)
	s_barrier
	s_waitcnt lgkmcnt(0)
	v_mfma_f32_16x16x32_bf16 v[126:129], v[144:147], v[160:163], v[126:129]
	v_mfma_f32_16x16x32_bf16 v[122:125], v[152:155], v[160:163], v[122:125]
	v_mfma_f32_16x16x32_bf16 v[110:113], v[144:147], v[168:171], v[110:113]
	v_mfma_f32_16x16x32_bf16 v[106:109], v[152:155], v[168:171], v[106:109]
	v_mfma_f32_16x16x32_bf16 v[94:97], v[144:147], v[176:179], v[94:97]
	v_mfma_f32_16x16x32_bf16 v[90:93], v[152:155], v[176:179], v[90:93]
	v_mfma_f32_16x16x32_bf16 v[78:81], v[144:147], v[184:187], v[78:81]
	v_mfma_f32_16x16x32_bf16 v[74:77], v[152:155], v[184:187], v[74:77]
	v_mfma_f32_16x16x32_bf16 v[126:129], v[148:151], v[164:167], v[126:129]
	v_mfma_f32_16x16x32_bf16 v[122:125], v[156:159], v[164:167], v[122:125]
	v_mfma_f32_16x16x32_bf16 v[110:113], v[148:151], v[172:175], v[110:113]
	v_mfma_f32_16x16x32_bf16 v[106:109], v[156:159], v[172:175], v[106:109]
	v_mfma_f32_16x16x32_bf16 v[94:97], v[148:151], v[180:183], v[94:97]
	v_mfma_f32_16x16x32_bf16 v[90:93], v[156:159], v[180:183], v[90:93]
	v_mfma_f32_16x16x32_bf16 v[78:81], v[148:151], v[188:191], v[78:81]
	v_mfma_f32_16x16x32_bf16 v[74:77], v[156:159], v[188:191], v[74:77]
	s_barrier
	s_add_i32 s31, 0, 0x14000
	s_add_i32 s28, s28, s15
	v_add_u32_e32 v208, s31, v142
	v_lshl_add_u64 v[228:229], s[10:11], 0, v[64:65]
	s_mov_b32 m0, s28
	ds_read_b128 v[192:195], v208
	ds_read_b128 v[196:199], v208 offset:1024
	ds_read_b128 v[220:223], v208 offset:2048
	ds_read_b128 v[224:227], v208 offset:3072
	global_load_lds_dwordx4 v[228:229], off
	v_lshl_add_u64 v[230:231], s[10:11], 0, v[130:131]
	s_add_i32 m0, s28, 0x2000
	s_nop 0
	global_load_lds_dwordx4 v[230:231], off
	s_waitcnt lgkmcnt(0)
	s_barrier
	v_mfma_f32_16x16x32_bf16 v[118:121], v[192:195], v[160:163], v[118:121]
	v_mfma_f32_16x16x32_bf16 v[114:117], v[220:223], v[160:163], v[114:117]
	v_mfma_f32_16x16x32_bf16 v[102:105], v[192:195], v[168:171], v[102:105]
	v_mfma_f32_16x16x32_bf16 v[98:101], v[220:223], v[168:171], v[98:101]
	v_mfma_f32_16x16x32_bf16 v[86:89], v[192:195], v[176:179], v[86:89]
	v_mfma_f32_16x16x32_bf16 v[82:85], v[220:223], v[176:179], v[82:85]
	v_mfma_f32_16x16x32_bf16 v[70:73], v[192:195], v[184:187], v[70:73]
	v_mfma_f32_16x16x32_bf16 v[66:69], v[220:223], v[184:187], v[66:69]
	v_mfma_f32_16x16x32_bf16 v[118:121], v[196:199], v[164:167], v[118:121]
	v_mfma_f32_16x16x32_bf16 v[114:117], v[224:227], v[164:167], v[114:117]
	v_mfma_f32_16x16x32_bf16 v[102:105], v[196:199], v[172:175], v[102:105]
	v_mfma_f32_16x16x32_bf16 v[98:101], v[224:227], v[172:175], v[98:101]
	v_mfma_f32_16x16x32_bf16 v[86:89], v[196:199], v[180:183], v[86:89]
	v_mfma_f32_16x16x32_bf16 v[82:85], v[224:227], v[180:183], v[82:85]
	v_mfma_f32_16x16x32_bf16 v[70:73], v[196:199], v[188:191], v[70:73]
	v_mfma_f32_16x16x32_bf16 v[66:69], v[224:227], v[188:191], v[66:69]
	s_mov_b32 m0, s20
	v_lshl_add_u64 v[232:233], s[2:3], 0, v[134:135]
	s_barrier
	ds_read_b128 v[160:163], v143 offset:16384
	ds_read_b128 v[164:167], v143 offset:17408
	ds_read_b128 v[168:171], v143 offset:18432
	ds_read_b128 v[172:175], v143 offset:19456
	ds_read_b128 v[176:179], v143 offset:20480
	ds_read_b128 v[180:183], v143 offset:21504
	ds_read_b128 v[184:187], v143 offset:22528
	ds_read_b128 v[188:191], v143 offset:23552
	global_load_lds_dwordx4 v[232:233], off
	v_lshl_add_u64 v[234:235], s[2:3], 0, v[132:133]
	s_mov_b32 m0, s21
	s_nop 0
	global_load_lds_dwordx4 v[234:235], off
	s_waitcnt lgkmcnt(0)
	s_barrier
	v_mfma_f32_16x16x32_bf16 v[60:63], v[144:147], v[160:163], v[60:63]
	v_mfma_f32_16x16x32_bf16 v[56:59], v[152:155], v[160:163], v[56:59]
	v_mfma_f32_16x16x32_bf16 v[44:47], v[144:147], v[168:171], v[44:47]
	v_mfma_f32_16x16x32_bf16 v[40:43], v[152:155], v[168:171], v[40:43]
	v_mfma_f32_16x16x32_bf16 v[28:31], v[144:147], v[176:179], v[28:31]
	v_mfma_f32_16x16x32_bf16 v[24:27], v[152:155], v[176:179], v[24:27]
	v_mfma_f32_16x16x32_bf16 v[12:15], v[144:147], v[184:187], v[12:15]
	v_mfma_f32_16x16x32_bf16 v[8:11], v[152:155], v[184:187], v[8:11]
	v_mfma_f32_16x16x32_bf16 v[60:63], v[148:151], v[164:167], v[60:63]
	v_mfma_f32_16x16x32_bf16 v[56:59], v[156:159], v[164:167], v[56:59]
	v_mfma_f32_16x16x32_bf16 v[44:47], v[148:151], v[172:175], v[44:47]
	v_mfma_f32_16x16x32_bf16 v[40:43], v[156:159], v[172:175], v[40:43]
	v_mfma_f32_16x16x32_bf16 v[28:31], v[148:151], v[180:183], v[28:31]
	v_mfma_f32_16x16x32_bf16 v[24:27], v[156:159], v[180:183], v[24:27]
	v_mfma_f32_16x16x32_bf16 v[12:15], v[148:151], v[188:191], v[12:15]
	v_mfma_f32_16x16x32_bf16 v[8:11], v[156:159], v[188:191], v[8:11]
	s_barrier
; #define PG8_STAGE(bufoff, gbase, voff) do { _Pragma("unroll") for (int _i = 0; _i < 2; ++_i) \
;         __builtin_amdgcn_global_load_lds((const unsigned*)((const char*)(gbase) + (voff)[_i]), (LAS unsigned*)(lds + (bufoff) + ldsw + _i * 8192), 16, 0, 0); } while (0)
; #define PG8_LDA(dst, b, h) do { _Pragma("unroll") for (int m = 0; m < 4; ++m) _Pragma("unroll") for (int k = 0; k < 2; ++k) dst[m][k] = *(const LAS bf16x8*)(lds + PG8_SA(b, h) + aoff + m * 2048 + k * 1024); } while (0)
; #define PG8_LDB(dst, b, h) do { _Pragma("unroll") for (int n = 0; n < 2; ++n) _Pragma("unroll") for (int k = 0; k < 2; ++k) dst[n][k] = *(const LAS bf16x8*)(lds + PG8_SB(b, h) + boff + n * 2048 + k * 1024); } while (0)
; #define PG8_MMA(ai, bj, At, Bt) do { __builtin_amdgcn_s_setprio(1); _Pragma("unroll") for (int m = 0; m < 4; ++m) _Pragma("unroll") for (int n = 0; n < 2; ++n) _Pragma("unroll") for (int k = 0; k < 2; ++k) \
;         acc[ai][bj][m][n] = __builtin_amdgcn_mfma_f32_16x16x32_bf16(Bt[n][k], At[m][k], acc[ai][bj][m][n], 0, 0, 0); __builtin_amdgcn_s_setprio(0); } while (0)
; #define PG8_WAIT_V(n) asm volatile("s_waitcnt vmcnt(" #n ")" ::: "memory")
; #define PG8_WAIT_L(n) asm volatile("s_waitcnt lgkmcnt(" #n ")" ::: "memory")
; #define PG8_BAR __builtin_amdgcn_s_barrier()
; #define PG8_SCHED __builtin_amdgcn_sched_barrier(0)
;     ...
;             PG8_STAGE(PG8_SB(0, 1), b2 + hstep, voffB);
;             PG8_WAIT_V(6); PG8_BAR; PG8_MMA(1, 1, At, B1); PG8_BAR;
;             PG8_LDB(B0, 1, 0); PG8_SCHED; PG8_LDA(At, 1, 0); PG8_STAGE(PG8_SA(0, 1), a2 + hstep, voffA);
;             PG8_WAIT_L(8); PG8_BAR; PG8_WAIT_L(0); PG8_MMA(0, 0, At, B0); PG8_BAR; PG8_SCHED;
;             PG8_LDB(B1, 1, 1); PG8_STAGE(PG8_SB(1, 0), b3, voffB);
;             PG8_BAR; PG8_WAIT_L(0); PG8_MMA(0, 1, At, B1); PG8_BAR;
;             PG8_LDA(At, 1, 1); PG8_STAGE(PG8_SA(1, 0), a3, voffA);
;             PG8_BAR; PG8_WAIT_L(0); PG8_MMA(1, 0, At, B0); PG8_BAR; PG8_SCHED;
	s_add_u32 s28, s10, 0x84000
	s_addc_u32 s29, s11, 0
	s_add_i32 s31, s31, s15
	v_lshl_add_u64 v[144:145], s[28:29], 0, v[64:65]
	s_mov_b32 m0, s31
	s_nop 0
	global_load_lds_dwordx4 v[144:145], off
	v_lshl_add_u64 v[144:145], s[28:29], 0, v[130:131]
	s_add_i32 m0, s31, 0x2000
	s_nop 0
	global_load_lds_dwordx4 v[144:145], off
	s_waitcnt vmcnt(6)
	s_barrier
	v_mfma_f32_16x16x32_bf16 v[52:55], v[192:195], v[160:163], v[52:55]
	v_mfma_f32_16x16x32_bf16 v[48:51], v[220:223], v[160:163], v[48:51]
	v_mfma_f32_16x16x32_bf16 v[36:39], v[192:195], v[168:171], v[36:39]
	v_mfma_f32_16x16x32_bf16 v[32:35], v[220:223], v[168:171], v[32:35]
	v_mfma_f32_16x16x32_bf16 v[20:23], v[192:195], v[176:179], v[20:23]
	v_mfma_f32_16x16x32_bf16 v[16:19], v[220:223], v[176:179], v[16:19]
	v_mfma_f32_16x16x32_bf16 v[4:7], v[192:195], v[184:187], v[4:7]
	v_mfma_f32_16x16x32_bf16 v[0:3], v[220:223], v[184:187], v[0:3]
	v_mfma_f32_16x16x32_bf16 v[52:55], v[196:199], v[164:167], v[52:55]
	v_mfma_f32_16x16x32_bf16 v[48:51], v[224:227], v[164:167], v[48:51]
	v_mfma_f32_16x16x32_bf16 v[36:39], v[196:199], v[172:175], v[36:39]
	v_mfma_f32_16x16x32_bf16 v[32:35], v[224:227], v[172:175], v[32:35]
	v_mfma_f32_16x16x32_bf16 v[20:23], v[196:199], v[180:183], v[20:23]
	v_mfma_f32_16x16x32_bf16 v[16:19], v[224:227], v[180:183], v[16:19]
	v_mfma_f32_16x16x32_bf16 v[4:7], v[196:199], v[188:191], v[4:7]
	v_mfma_f32_16x16x32_bf16 v[0:3], v[224:227], v[188:191], v[0:3]
	s_add_i32 s28, 0, 0x18000
	v_add_u32_e32 v156, s28, v142
	s_barrier
	ds_read_b128 v[144:147], v156
	ds_read_b128 v[148:151], v156 offset:1024
	ds_read_b128 v[152:155], v156 offset:2048
	ds_read_b128 v[156:159], v156 offset:3072
	s_add_u32 s2, s2, 0x84000
	s_addc_u32 s3, s3, 0
	s_mov_b32 m0, s22
	v_lshl_add_u64 v[192:193], s[2:3], 0, v[134:135]
	ds_read_b128 v[160:163], v143 offset:32768
	ds_read_b128 v[164:167], v143 offset:33792
	ds_read_b128 v[168:171], v143 offset:34816
	ds_read_b128 v[172:175], v143 offset:35840
	ds_read_b128 v[176:179], v143 offset:36864
	ds_read_b128 v[180:183], v143 offset:37888
	ds_read_b128 v[184:187], v143 offset:38912
	ds_read_b128 v[188:191], v143 offset:39936
	global_load_lds_dwordx4 v[192:193], off
	v_lshl_add_u64 v[192:193], s[2:3], 0, v[132:133]
	s_mov_b32 m0, s23
	s_nop 0
	global_load_lds_dwordx4 v[192:193], off
	s_waitcnt lgkmcnt(8)
	s_barrier
	s_waitcnt lgkmcnt(0)
	v_mfma_f32_16x16x32_bf16 v[126:129], v[144:147], v[160:163], v[126:129]
	v_mfma_f32_16x16x32_bf16 v[122:125], v[152:155], v[160:163], v[122:125]
	v_mfma_f32_16x16x32_bf16 v[110:113], v[144:147], v[168:171], v[110:113]
	v_mfma_f32_16x16x32_bf16 v[106:109], v[152:155], v[168:171], v[106:109]
	v_mfma_f32_16x16x32_bf16 v[94:97], v[144:147], v[176:179], v[94:97]
	v_mfma_f32_16x16x32_bf16 v[90:93], v[152:155], v[176:179], v[90:93]
	v_mfma_f32_16x16x32_bf16 v[78:81], v[144:147], v[184:187], v[78:81]
	v_mfma_f32_16x16x32_bf16 v[74:77], v[152:155], v[184:187], v[74:77]
	v_mfma_f32_16x16x32_bf16 v[126:129], v[148:151], v[164:167], v[126:129]
	v_mfma_f32_16x16x32_bf16 v[122:125], v[156:159], v[164:167], v[122:125]
	v_mfma_f32_16x16x32_bf16 v[110:113], v[148:151], v[172:175], v[110:113]
	v_mfma_f32_16x16x32_bf16 v[106:109], v[156:159], v[172:175], v[106:109]
	v_mfma_f32_16x16x32_bf16 v[94:97], v[148:151], v[180:183], v[94:97]
	v_mfma_f32_16x16x32_bf16 v[90:93], v[156:159], v[180:183], v[90:93]
	v_mfma_f32_16x16x32_bf16 v[78:81], v[148:151], v[188:191], v[78:81]
	v_mfma_f32_16x16x32_bf16 v[74:77], v[156:159], v[188:191], v[74:77]
	s_barrier
	s_add_i32 s29, 0, 0x1c000
	s_add_i32 s2, s28, s15
	v_add_u32_e32 v208, s29, v142
	v_lshl_add_u64 v[228:229], v[228:229], 0, s[16:17]
	s_mov_b32 m0, s2
	ds_read_b128 v[192:195], v208
	ds_read_b128 v[196:199], v208 offset:1024
	ds_read_b128 v[220:223], v208 offset:2048
	ds_read_b128 v[224:227], v208 offset:3072
	global_load_lds_dwordx4 v[228:229], off
	v_lshl_add_u64 v[228:229], v[230:231], 0, s[16:17]
	s_add_i32 m0, s2, 0x2000
	s_nop 0
	global_load_lds_dwordx4 v[228:229], off
	s_waitcnt lgkmcnt(0)
	s_barrier
	v_mfma_f32_16x16x32_bf16 v[118:121], v[192:195], v[160:163], v[118:121]
	v_mfma_f32_16x16x32_bf16 v[114:117], v[220:223], v[160:163], v[114:117]
	v_mfma_f32_16x16x32_bf16 v[102:105], v[192:195], v[168:171], v[102:105]
	v_mfma_f32_16x16x32_bf16 v[98:101], v[220:223], v[168:171], v[98:101]
	v_mfma_f32_16x16x32_bf16 v[86:89], v[192:195], v[176:179], v[86:89]
	v_mfma_f32_16x16x32_bf16 v[82:85], v[220:223], v[176:179], v[82:85]
	v_mfma_f32_16x16x32_bf16 v[70:73], v[192:195], v[184:187], v[70:73]
	v_mfma_f32_16x16x32_bf16 v[66:69], v[220:223], v[184:187], v[66:69]
	v_mfma_f32_16x16x32_bf16 v[118:121], v[196:199], v[164:167], v[118:121]
	v_mfma_f32_16x16x32_bf16 v[114:117], v[224:227], v[164:167], v[114:117]
	v_mfma_f32_16x16x32_bf16 v[102:105], v[196:199], v[172:175], v[102:105]
	v_mfma_f32_16x16x32_bf16 v[98:101], v[224:227], v[172:175], v[98:101]
	v_mfma_f32_16x16x32_bf16 v[86:89], v[196:199], v[180:183], v[86:89]
	v_mfma_f32_16x16x32_bf16 v[82:85], v[224:227], v[180:183], v[82:85]
	v_mfma_f32_16x16x32_bf16 v[70:73], v[196:199], v[188:191], v[70:73]
	v_mfma_f32_16x16x32_bf16 v[66:69], v[224:227], v[188:191], v[66:69]
	s_mov_b32 m0, s25
	v_lshl_add_u64 v[228:229], v[232:233], 0, s[16:17]
	s_barrier
	ds_read_b128 v[160:163], v143 offset:49152
	ds_read_b128 v[164:167], v143 offset:50176
	ds_read_b128 v[168:171], v143 offset:51200
	ds_read_b128 v[172:175], v143 offset:52224
	ds_read_b128 v[176:179], v143 offset:53248
	ds_read_b128 v[180:183], v143 offset:54272
	ds_read_b128 v[184:187], v143 offset:55296
	ds_read_b128 v[188:191], v143 offset:56320
	global_load_lds_dwordx4 v[228:229], off
	v_lshl_add_u64 v[228:229], v[234:235], 0, s[16:17]
	s_mov_b32 m0, s26
	s_nop 0
	global_load_lds_dwordx4 v[228:229], off
	s_waitcnt lgkmcnt(0)
	s_barrier
; __device__ __forceinline__ unsigned cvt_pk_bf16(float lo, float hi) { unsigned r; asm volatile("v_cvt_pk_bf16_f32 %0, %1, %2" : "=v"(r) : "v"(lo), "v"(hi)); return r; }
; #define PG8_STAGE(bufoff, gbase, voff) do { _Pragma("unroll") for (int _i = 0; _i < 2; ++_i) \
;         __builtin_amdgcn_global_load_lds((const unsigned*)((const char*)(gbase) + (voff)[_i]), (LAS unsigned*)(lds + (bufoff) + ldsw + _i * 8192), 16, 0, 0); } while (0)
; #define PG8_MMA(ai, bj, At, Bt) do { __builtin_amdgcn_s_setprio(1); _Pragma("unroll") for (int m = 0; m < 4; ++m) _Pragma("unroll") for (int n = 0; n < 2; ++n) _Pragma("unroll") for (int k = 0; k < 2; ++k) \
;         acc[ai][bj][m][n] = __builtin_amdgcn_mfma_f32_16x16x32_bf16(Bt[n][k], At[m][k], acc[ai][bj][m][n], 0, 0, 0); __builtin_amdgcn_s_setprio(0); } while (0)
; #define PG8_WAIT_V(n) asm volatile("s_waitcnt vmcnt(" #n ")" ::: "memory")
; #define PG8_WAIT_L(n) asm volatile("s_waitcnt lgkmcnt(" #n ")" ::: "memory")
;     __device__ __forceinline__ void operator()(const f32x4 (&acc)[2][2][4][2], const Unit& u, int wr, int wc, int fr, int fq) const {
;         const int row0 = u.pm * BM + wr * 64 + fr, col0 = u.pn * BM + wc * 32 + 8 * fq;
; #pragma unroll
;         for (int ai = 0; ai < 2; ++ai)
; #pragma unroll
;             for (int m = 0; m < 4; ++m) { bf16_t* rowp = O + (size_t)(row0 + ai * HALF + m * 16) * LDF + col0;
; #pragma unroll
;                 for (int bj = 0; bj < 2; ++bj) { f32x4 v0 = acc[ai][bj][m][0], v1 = acc[ai][bj][m][1];
; #pragma unroll
;                     for (int j = 0; j < 4; ++j) { const float a = fmaxf(v0[j], 0.f), b = fmaxf(v1[j], 0.f); v0[j] = a * a; v1[j] = b * b; }
;                     u32x4 w; w.x = cvt_pk_bf16(v0[0], v0[1]); w.y = cvt_pk_bf16(v0[2], v0[3]); w.z = cvt_pk_bf16(v1[0], v1[1]); w.w = cvt_pk_bf16(v1[2], v1[3]);
;                     *(u32x4*)(rowp + bj * HALF) = w; } }
;     ...
;             PG8_BAR; PG8_WAIT_L(0); PG8_MMA(1, 0, At, B0); PG8_BAR; PG8_SCHED;
;             PG8_STAGE(PG8_SB(1, 1), b3 + hstep, voffB);
;             PG8_WAIT_V(6); PG8_BAR; PG8_MMA(1, 1, At, B1); PG8_BAR;
;         }
;         if constexpr (Epi::FUSE_LN) {
;             if (E.fuse && cur.ks < 0) { if (wr == 0) PG8_BAR; E.fused(acc, cur, wr, wc, fr, fq, lds); if (wr == 1) PG8_BAR; }
;             else E(acc, cur, wr, wc, fr, fq);
;         } else E(acc, cur, wr, wc, fr, fq);
;         if (!has_next) break;
	v_mfma_f32_16x16x32_bf16 v[60:63], v[144:147], v[160:163], v[60:63]
	v_mfma_f32_16x16x32_bf16 v[56:59], v[152:155], v[160:163], v[56:59]
	v_mfma_f32_16x16x32_bf16 v[44:47], v[144:147], v[168:171], v[44:47]
	v_mfma_f32_16x16x32_bf16 v[40:43], v[152:155], v[168:171], v[40:43]
	v_mfma_f32_16x16x32_bf16 v[28:31], v[144:147], v[176:179], v[28:31]
	v_mfma_f32_16x16x32_bf16 v[24:27], v[152:155], v[176:179], v[24:27]
	v_mfma_f32_16x16x32_bf16 v[12:15], v[144:147], v[184:187], v[12:15]
	v_mfma_f32_16x16x32_bf16 v[8:11], v[152:155], v[184:187], v[8:11]
	v_mfma_f32_16x16x32_bf16 v[60:63], v[148:151], v[164:167], v[60:63]
	v_mfma_f32_16x16x32_bf16 v[56:59], v[156:159], v[164:167], v[56:59]
	v_mfma_f32_16x16x32_bf16 v[44:47], v[148:151], v[172:175], v[44:47]
	v_mfma_f32_16x16x32_bf16 v[40:43], v[156:159], v[172:175], v[40:43]
	v_mfma_f32_16x16x32_bf16 v[28:31], v[148:151], v[180:183], v[28:31]
	v_mfma_f32_16x16x32_bf16 v[24:27], v[156:159], v[180:183], v[24:27]
	v_mfma_f32_16x16x32_bf16 v[12:15], v[148:151], v[188:191], v[12:15]
	v_mfma_f32_16x16x32_bf16 v[8:11], v[156:159], v[188:191], v[8:11]
	s_barrier
	s_add_u32 s2, s10, 0x84080
	s_addc_u32 s3, s11, 0
	s_add_i32 s10, s29, s15
	v_lshl_add_u64 v[144:145], s[2:3], 0, v[64:65]
	s_mov_b32 m0, s10
	s_nop 0
	global_load_lds_dwordx4 v[144:145], off
	v_lshl_add_u64 v[144:145], s[2:3], 0, v[130:131]
	s_add_i32 m0, s10, 0x2000
	s_nop 0
	global_load_lds_dwordx4 v[144:145], off
	s_waitcnt vmcnt(6)
	s_barrier
	v_mfma_f32_16x16x32_bf16 v[52:55], v[192:195], v[160:163], v[52:55]
	v_mfma_f32_16x16x32_bf16 v[48:51], v[220:223], v[160:163], v[48:51]
	v_mfma_f32_16x16x32_bf16 v[36:39], v[192:195], v[168:171], v[36:39]
	v_mfma_f32_16x16x32_bf16 v[32:35], v[220:223], v[168:171], v[32:35]
	v_mfma_f32_16x16x32_bf16 v[20:23], v[192:195], v[176:179], v[20:23]
	v_mfma_f32_16x16x32_bf16 v[16:19], v[220:223], v[176:179], v[16:19]
	v_mfma_f32_16x16x32_bf16 v[4:7], v[192:195], v[184:187], v[4:7]
	v_mfma_f32_16x16x32_bf16 v[0:3], v[220:223], v[184:187], v[0:3]
	v_mfma_f32_16x16x32_bf16 v[52:55], v[196:199], v[164:167], v[52:55]
	v_mfma_f32_16x16x32_bf16 v[48:51], v[224:227], v[164:167], v[48:51]
	v_mfma_f32_16x16x32_bf16 v[36:39], v[196:199], v[172:175], v[36:39]
	v_mfma_f32_16x16x32_bf16 v[32:35], v[224:227], v[172:175], v[32:35]
	v_mfma_f32_16x16x32_bf16 v[20:23], v[196:199], v[180:183], v[20:23]
	v_mfma_f32_16x16x32_bf16 v[16:19], v[224:227], v[180:183], v[16:19]
	v_mfma_f32_16x16x32_bf16 v[4:7], v[196:199], v[188:191], v[4:7]
	v_mfma_f32_16x16x32_bf16 v[0:3], v[224:227], v[188:191], v[0:3]
	s_add_i32 s27, s27, 2
	s_add_u32 s8, s8, 0x100
	s_addc_u32 s9, s9, 0
	s_cmp_gt_u32 s27, 29
	s_barrier
	s_cbranch_scc0 .LBB0_146
	s_lshl_b32 s2, s19, 8
	v_max_f32_e32 v122, 0, v122
	s_or_b32 s2, s24, s2
	v_mul_f32_e32 v135, v122, v122
	v_max_f32_e32 v122, v127, v127
	v_max_f32_e32 v123, 0, v123
	v_max_f32_e32 v124, 0, v124
	v_lshl_add_u32 v134, s18, 8, v141
	v_or_b32_e32 v64, s2, v140
	v_mov_b64_e32 v[130:131], s[80:81]
	s_movk_i32 s4, 0x4080
	v_max_f32_e32 v122, 0, v122
	v_mul_f32_e32 v127, v123, v123
	v_max_f32_e32 v123, v128, v128
	v_mul_f32_e32 v128, v124, v124
	v_max_f32_e32 v124, v129, v129
	v_mad_i64_i32 v[132:133], s[2:3], v134, s4, v[130:131]
	v_lshlrev_b32_e32 v64, 1, v64
	v_max_f32_e32 v126, 0, v126
	v_mul_f32_e32 v122, v122, v122
	v_max_f32_e32 v123, 0, v123
	v_max_f32_e32 v124, 0, v124
	v_max_f32_e32 v125, 0, v125
	v_lshl_add_u64 v[132:133], v[132:133], 0, v[64:65]
	v_mul_f32_e32 v126, v126, v126
	v_mul_f32_e32 v123, v123, v123
	v_mul_f32_e32 v124, v124, v124
	v_mul_f32_e32 v125, v125, v125
	v_cvt_pk_bf16_f32 v122, v126, v122
	v_max_f32_e32 v114, 0, v114
	v_max_f32_e32 v115, 0, v115
	v_max_f32_e32 v116, 0, v116
	v_cvt_pk_bf16_f32 v123, v123, v124
	v_cvt_pk_bf16_f32 v124, v135, v127
	v_cvt_pk_bf16_f32 v125, v128, v125
	global_store_dwordx4 v[132:133], v[122:125], off
	s_nop 1
	v_mul_f32_e32 v122, v114, v114
	v_max_f32_e32 v114, v119, v119
	v_mul_f32_e32 v119, v115, v115
	v_max_f32_e32 v115, v120, v120
	v_mul_f32_e32 v120, v116, v116
	v_max_f32_e32 v116, v121, v121
	v_max_f32_e32 v114, 0, v114
	v_max_f32_e32 v115, 0, v115
	v_max_f32_e32 v116, 0, v116
	v_max_f32_e32 v118, 0, v118
	v_mul_f32_e32 v114, v114, v114
	v_mul_f32_e32 v115, v115, v115
	v_max_f32_e32 v117, 0, v117
	v_mul_f32_e32 v116, v116, v116
	v_mul_f32_e32 v118, v118, v118
	v_mul_f32_e32 v117, v117, v117
	v_cvt_pk_bf16_f32 v114, v118, v114
	v_cvt_pk_bf16_f32 v115, v115, v116
	v_cvt_pk_bf16_f32 v116, v122, v119
	v_max_f32_e32 v106, 0, v106
	v_cvt_pk_bf16_f32 v117, v120, v117
	global_store_dwordx4 v[132:133], v[114:117], off offset:256
	s_nop 1
	v_max_f32_e32 v107, 0, v107
	v_max_f32_e32 v108, 0, v108
	v_mul_f32_e32 v116, v106, v106
	v_max_f32_e32 v106, v111, v111
	v_or_b32_e32 v114, 16, v134
	v_max_f32_e32 v106, 0, v106
	v_mul_f32_e32 v111, v107, v107
	v_max_f32_e32 v107, v112, v112
	v_mul_f32_e32 v112, v108, v108
	v_max_f32_e32 v108, v113, v113
	v_mad_i64_i32 v[114:115], s[2:3], v114, s4, v[130:131]
	v_max_f32_e32 v110, 0, v110
	v_mul_f32_e32 v106, v106, v106
	v_max_f32_e32 v107, 0, v107
	v_max_f32_e32 v108, 0, v108
	v_max_f32_e32 v109, 0, v109
	v_lshl_add_u64 v[114:115], v[114:115], 0, v[64:65]
	v_mul_f32_e32 v110, v110, v110
	v_mul_f32_e32 v107, v107, v107
	v_mul_f32_e32 v108, v108, v108
	v_mul_f32_e32 v109, v109, v109
	v_cvt_pk_bf16_f32 v106, v110, v106
	v_max_f32_e32 v98, 0, v98
	v_max_f32_e32 v99, 0, v99
	v_max_f32_e32 v100, 0, v100
	v_cvt_pk_bf16_f32 v107, v107, v108
	v_cvt_pk_bf16_f32 v108, v116, v111
	v_cvt_pk_bf16_f32 v109, v112, v109
	global_store_dwordx4 v[114:115], v[106:109], off
	s_nop 1
	v_mul_f32_e32 v106, v98, v98
	v_max_f32_e32 v98, v103, v103
; __device__ __forceinline__ unsigned cvt_pk_bf16(float lo, float hi) { unsigned r; asm volatile("v_cvt_pk_bf16_f32 %0, %1, %2" : "=v"(r) : "v"(lo), "v"(hi)); return r; }
;     __device__ __forceinline__ void operator()(const f32x4 (&acc)[2][2][4][2], const Unit& u, int wr, int wc, int fr, int fq) const {
;         const int row0 = u.pm * BM + wr * 64 + fr, col0 = u.pn * BM + wc * 32 + 8 * fq;
; #pragma unroll
;         for (int ai = 0; ai < 2; ++ai)
; #pragma unroll
;             for (int m = 0; m < 4; ++m) { bf16_t* rowp = O + (size_t)(row0 + ai * HALF + m * 16) * LDF + col0;
; #pragma unroll
;                 for (int bj = 0; bj < 2; ++bj) { f32x4 v0 = acc[ai][bj][m][0], v1 = acc[ai][bj][m][1];
; #pragma unroll
;                     for (int j = 0; j < 4; ++j) { const float a = fmaxf(v0[j], 0.f), b = fmaxf(v1[j], 0.f); v0[j] = a * a; v1[j] = b * b; }
;                     u32x4 w; w.x = cvt_pk_bf16(v0[0], v0[1]); w.y = cvt_pk_bf16(v0[2], v0[3]); w.z = cvt_pk_bf16(v1[0], v1[1]); w.w = cvt_pk_bf16(v1[2], v1[3]);
;                     *(u32x4*)(rowp + bj * HALF) = w; } }
	v_mul_f32_e32 v103, v99, v99
	v_max_f32_e32 v99, v104, v104
	v_mul_f32_e32 v104, v100, v100
	v_max_f32_e32 v100, v105, v105
	v_max_f32_e32 v98, 0, v98
	v_max_f32_e32 v99, 0, v99
	v_max_f32_e32 v100, 0, v100
	v_max_f32_e32 v102, 0, v102
	v_mul_f32_e32 v98, v98, v98
	v_mul_f32_e32 v99, v99, v99
	v_max_f32_e32 v101, 0, v101
	v_mul_f32_e32 v100, v100, v100
	v_mul_f32_e32 v102, v102, v102
	v_mul_f32_e32 v101, v101, v101
	v_cvt_pk_bf16_f32 v98, v102, v98
	v_cvt_pk_bf16_f32 v99, v99, v100
	v_cvt_pk_bf16_f32 v100, v106, v103
	v_max_f32_e32 v90, 0, v90
	v_cvt_pk_bf16_f32 v101, v104, v101
	global_store_dwordx4 v[114:115], v[98:101], off offset:256
	s_nop 1
	v_max_f32_e32 v91, 0, v91
	v_max_f32_e32 v92, 0, v92
	v_mul_f32_e32 v100, v90, v90
	v_max_f32_e32 v90, v95, v95
	v_or_b32_e32 v98, 32, v134
	v_max_f32_e32 v90, 0, v90
	v_mul_f32_e32 v95, v91, v91
	v_max_f32_e32 v91, v96, v96
	v_mul_f32_e32 v96, v92, v92
	v_max_f32_e32 v92, v97, v97
	v_mad_i64_i32 v[98:99], s[2:3], v98, s4, v[130:131]
	v_max_f32_e32 v94, 0, v94
	v_mul_f32_e32 v90, v90, v90
	v_max_f32_e32 v91, 0, v91
	v_max_f32_e32 v92, 0, v92
	v_max_f32_e32 v93, 0, v93
	v_lshl_add_u64 v[98:99], v[98:99], 0, v[64:65]
	v_mul_f32_e32 v94, v94, v94
	v_mul_f32_e32 v91, v91, v91
	v_mul_f32_e32 v92, v92, v92
	v_mul_f32_e32 v93, v93, v93
	v_cvt_pk_bf16_f32 v90, v94, v90
	v_max_f32_e32 v82, 0, v82
	v_max_f32_e32 v83, 0, v83
	v_max_f32_e32 v84, 0, v84
	v_cvt_pk_bf16_f32 v91, v91, v92
	v_cvt_pk_bf16_f32 v92, v100, v95
	v_cvt_pk_bf16_f32 v93, v96, v93
	global_store_dwordx4 v[98:99], v[90:93], off
	s_nop 1
	v_mul_f32_e32 v90, v82, v82
	v_max_f32_e32 v82, v87, v87
	v_mul_f32_e32 v87, v83, v83
	v_max_f32_e32 v83, v88, v88
	v_mul_f32_e32 v88, v84, v84
	v_max_f32_e32 v84, v89, v89
	v_max_f32_e32 v82, 0, v82
	v_max_f32_e32 v83, 0, v83
	v_max_f32_e32 v84, 0, v84
	v_max_f32_e32 v86, 0, v86
	v_mul_f32_e32 v82, v82, v82
	v_mul_f32_e32 v83, v83, v83
	v_max_f32_e32 v85, 0, v85
	v_mul_f32_e32 v84, v84, v84
	v_mul_f32_e32 v86, v86, v86
	v_mul_f32_e32 v85, v85, v85
	v_cvt_pk_bf16_f32 v82, v86, v82
	v_cvt_pk_bf16_f32 v83, v83, v84
	v_cvt_pk_bf16_f32 v84, v90, v87
	v_max_f32_e32 v74, 0, v74
	v_cvt_pk_bf16_f32 v85, v88, v85
	global_store_dwordx4 v[98:99], v[82:85], off offset:256
	s_nop 1
	v_max_f32_e32 v75, 0, v75
	v_max_f32_e32 v76, 0, v76
	v_mul_f32_e32 v84, v74, v74
	v_max_f32_e32 v74, v79, v79
	v_or_b32_e32 v82, 48, v134
	v_max_f32_e32 v74, 0, v74
	v_mul_f32_e32 v79, v75, v75
	v_max_f32_e32 v75, v80, v80
	v_mul_f32_e32 v80, v76, v76
	v_max_f32_e32 v76, v81, v81
	v_mad_i64_i32 v[82:83], s[2:3], v82, s4, v[130:131]
	v_max_f32_e32 v78, 0, v78
	v_mul_f32_e32 v74, v74, v74
	v_max_f32_e32 v75, 0, v75
	v_max_f32_e32 v76, 0, v76
	v_max_f32_e32 v77, 0, v77
	v_lshl_add_u64 v[82:83], v[82:83], 0, v[64:65]
	v_mul_f32_e32 v78, v78, v78
	v_mul_f32_e32 v75, v75, v75
	v_mul_f32_e32 v76, v76, v76
	v_mul_f32_e32 v77, v77, v77
	v_cvt_pk_bf16_f32 v74, v78, v74
	v_max_f32_e32 v66, 0, v66
	v_max_f32_e32 v67, 0, v67
	v_max_f32_e32 v68, 0, v68
	v_cvt_pk_bf16_f32 v75, v75, v76
	v_cvt_pk_bf16_f32 v76, v84, v79
	v_cvt_pk_bf16_f32 v77, v80, v77
	global_store_dwordx4 v[82:83], v[74:77], off
	s_nop 1
	v_mul_f32_e32 v74, v66, v66
	v_max_f32_e32 v66, v71, v71
	v_mul_f32_e32 v71, v67, v67
	v_max_f32_e32 v67, v72, v72
	v_mul_f32_e32 v72, v68, v68
	v_max_f32_e32 v68, v73, v73
	v_max_f32_e32 v66, 0, v66
	v_max_f32_e32 v67, 0, v67
	v_max_f32_e32 v68, 0, v68
	v_max_f32_e32 v70, 0, v70
	v_mul_f32_e32 v66, v66, v66
	v_mul_f32_e32 v67, v67, v67
	v_max_f32_e32 v69, 0, v69
	v_mul_f32_e32 v68, v68, v68
	v_mul_f32_e32 v70, v70, v70
	v_mul_f32_e32 v69, v69, v69
	v_cvt_pk_bf16_f32 v66, v70, v66
	v_cvt_pk_bf16_f32 v67, v67, v68
	v_cvt_pk_bf16_f32 v68, v74, v71
	v_max_f32_e32 v56, 0, v56
	v_cvt_pk_bf16_f32 v69, v72, v69
	global_store_dwordx4 v[82:83], v[66:69], off offset:256
	s_nop 1
	v_max_f32_e32 v57, 0, v57
	v_max_f32_e32 v58, 0, v58
	v_mul_f32_e32 v68, v56, v56
	v_max_f32_e32 v56, v61, v61
	v_add_u32_e32 v66, 0x80, v134
	v_max_f32_e32 v56, 0, v56
	v_mul_f32_e32 v61, v57, v57
	v_max_f32_e32 v57, v62, v62
	v_mul_f32_e32 v62, v58, v58
	v_max_f32_e32 v58, v63, v63
	v_mad_i64_i32 v[66:67], s[2:3], v66, s4, v[130:131]
	v_max_f32_e32 v60, 0, v60
	v_mul_f32_e32 v56, v56, v56
	v_max_f32_e32 v57, 0, v57
	v_max_f32_e32 v58, 0, v58
	v_max_f32_e32 v59, 0, v59
	v_lshl_add_u64 v[66:67], v[66:67], 0, v[64:65]
	v_mul_f32_e32 v60, v60, v60
	v_mul_f32_e32 v57, v57, v57
	v_mul_f32_e32 v58, v58, v58
	v_mul_f32_e32 v59, v59, v59
	v_cvt_pk_bf16_f32 v56, v60, v56
	v_max_f32_e32 v48, 0, v48
	v_max_f32_e32 v49, 0, v49
	v_max_f32_e32 v50, 0, v50
	v_cvt_pk_bf16_f32 v57, v57, v58
	v_cvt_pk_bf16_f32 v58, v68, v61
	v_cvt_pk_bf16_f32 v59, v62, v59
	global_store_dwordx4 v[66:67], v[56:59], off
	s_nop 1
	v_mul_f32_e32 v56, v48, v48
	v_max_f32_e32 v48, v53, v53
	v_mul_f32_e32 v53, v49, v49
	v_max_f32_e32 v49, v54, v54
	v_mul_f32_e32 v54, v50, v50
	v_max_f32_e32 v50, v55, v55
	v_max_f32_e32 v48, 0, v48
	v_max_f32_e32 v49, 0, v49
	v_max_f32_e32 v50, 0, v50
	v_max_f32_e32 v52, 0, v52
	v_mul_f32_e32 v48, v48, v48
	v_mul_f32_e32 v49, v49, v49
; __device__ __forceinline__ unsigned cvt_pk_bf16(float lo, float hi) { unsigned r; asm volatile("v_cvt_pk_bf16_f32 %0, %1, %2" : "=v"(r) : "v"(lo), "v"(hi)); return r; }
; #define PG8_WAIT_V(n) asm volatile("s_waitcnt vmcnt(" #n ")" ::: "memory")
; #define PG8_BAR __builtin_amdgcn_s_barrier()
;     __device__ __forceinline__ void operator()(const f32x4 (&acc)[2][2][4][2], const Unit& u, int wr, int wc, int fr, int fq) const {
;         const int row0 = u.pm * BM + wr * 64 + fr, col0 = u.pn * BM + wc * 32 + 8 * fq;
; #pragma unroll
;         for (int ai = 0; ai < 2; ++ai)
; #pragma unroll
;             for (int m = 0; m < 4; ++m) { bf16_t* rowp = O + (size_t)(row0 + ai * HALF + m * 16) * LDF + col0;
; #pragma unroll
;                 for (int bj = 0; bj < 2; ++bj) { f32x4 v0 = acc[ai][bj][m][0], v1 = acc[ai][bj][m][1];
; #pragma unroll
;                     for (int j = 0; j < 4; ++j) { const float a = fmaxf(v0[j], 0.f), b = fmaxf(v1[j], 0.f); v0[j] = a * a; v1[j] = b * b; }
;                     u32x4 w; w.x = cvt_pk_bf16(v0[0], v0[1]); w.y = cvt_pk_bf16(v0[2], v0[3]); w.z = cvt_pk_bf16(v1[0], v1[1]); w.w = cvt_pk_bf16(v1[2], v1[3]);
;                     *(u32x4*)(rowp + bj * HALF) = w; } }
;     ...
;     PG8_WAIT_V(0);
;     if (wr == 0) PG8_BAR;
;     PG8_BAR;
	v_max_f32_e32 v51, 0, v51
	v_mul_f32_e32 v50, v50, v50
	v_mul_f32_e32 v52, v52, v52
	v_mul_f32_e32 v51, v51, v51
	v_cvt_pk_bf16_f32 v48, v52, v48
	v_cvt_pk_bf16_f32 v49, v49, v50
	v_cvt_pk_bf16_f32 v50, v56, v53
	v_max_f32_e32 v40, 0, v40
	v_cvt_pk_bf16_f32 v51, v54, v51
	global_store_dwordx4 v[66:67], v[48:51], off offset:256
	s_nop 1
	v_max_f32_e32 v41, 0, v41
	v_max_f32_e32 v42, 0, v42
	v_mul_f32_e32 v50, v40, v40
	v_max_f32_e32 v40, v45, v45
	v_add_u32_e32 v48, 0x90, v134
	v_max_f32_e32 v40, 0, v40
	v_mul_f32_e32 v45, v41, v41
	v_max_f32_e32 v41, v46, v46
	v_mul_f32_e32 v46, v42, v42
	v_max_f32_e32 v42, v47, v47
	v_mad_i64_i32 v[48:49], s[2:3], v48, s4, v[130:131]
	v_max_f32_e32 v44, 0, v44
	v_mul_f32_e32 v40, v40, v40
	v_max_f32_e32 v41, 0, v41
	v_max_f32_e32 v42, 0, v42
	v_max_f32_e32 v43, 0, v43
	v_lshl_add_u64 v[48:49], v[48:49], 0, v[64:65]
	v_mul_f32_e32 v44, v44, v44
	v_mul_f32_e32 v41, v41, v41
	v_mul_f32_e32 v42, v42, v42
	v_mul_f32_e32 v43, v43, v43
	v_cvt_pk_bf16_f32 v40, v44, v40
	v_max_f32_e32 v32, 0, v32
	v_max_f32_e32 v33, 0, v33
	v_max_f32_e32 v34, 0, v34
	v_cvt_pk_bf16_f32 v41, v41, v42
	v_cvt_pk_bf16_f32 v42, v50, v45
	v_cvt_pk_bf16_f32 v43, v46, v43
	global_store_dwordx4 v[48:49], v[40:43], off
	s_nop 1
	v_mul_f32_e32 v40, v32, v32
	v_max_f32_e32 v32, v37, v37
	v_mul_f32_e32 v37, v33, v33
	v_max_f32_e32 v33, v38, v38
	v_mul_f32_e32 v38, v34, v34
	v_max_f32_e32 v34, v39, v39
	v_max_f32_e32 v32, 0, v32
	v_max_f32_e32 v33, 0, v33
	v_max_f32_e32 v34, 0, v34
	v_max_f32_e32 v36, 0, v36
	v_mul_f32_e32 v32, v32, v32
	v_mul_f32_e32 v33, v33, v33
	v_max_f32_e32 v35, 0, v35
	v_mul_f32_e32 v34, v34, v34
	v_mul_f32_e32 v36, v36, v36
	v_mul_f32_e32 v35, v35, v35
	v_cvt_pk_bf16_f32 v32, v36, v32
	v_cvt_pk_bf16_f32 v33, v33, v34
	v_cvt_pk_bf16_f32 v34, v40, v37
	v_max_f32_e32 v24, 0, v24
	v_cvt_pk_bf16_f32 v35, v38, v35
	global_store_dwordx4 v[48:49], v[32:35], off offset:256
	s_nop 1
	v_max_f32_e32 v25, 0, v25
	v_max_f32_e32 v26, 0, v26
	v_mul_f32_e32 v34, v24, v24
	v_max_f32_e32 v24, v29, v29
	v_add_u32_e32 v32, 0xa0, v134
	v_max_f32_e32 v24, 0, v24
	v_mul_f32_e32 v29, v25, v25
	v_max_f32_e32 v25, v30, v30
	v_mul_f32_e32 v30, v26, v26
	v_max_f32_e32 v26, v31, v31
	v_mad_i64_i32 v[32:33], s[2:3], v32, s4, v[130:131]
	v_max_f32_e32 v28, 0, v28
	v_mul_f32_e32 v24, v24, v24
	v_max_f32_e32 v25, 0, v25
	v_max_f32_e32 v26, 0, v26
	v_max_f32_e32 v27, 0, v27
	v_lshl_add_u64 v[32:33], v[32:33], 0, v[64:65]
	v_mul_f32_e32 v28, v28, v28
	v_mul_f32_e32 v25, v25, v25
	v_mul_f32_e32 v26, v26, v26
	v_mul_f32_e32 v27, v27, v27
	v_cvt_pk_bf16_f32 v24, v28, v24
	v_max_f32_e32 v16, 0, v16
	v_max_f32_e32 v17, 0, v17
	v_max_f32_e32 v18, 0, v18
	v_cvt_pk_bf16_f32 v25, v25, v26
	v_cvt_pk_bf16_f32 v26, v34, v29
	v_cvt_pk_bf16_f32 v27, v30, v27
	global_store_dwordx4 v[32:33], v[24:27], off
	s_nop 1
	v_mul_f32_e32 v24, v16, v16
	v_max_f32_e32 v16, v21, v21
	v_mul_f32_e32 v21, v17, v17
	v_max_f32_e32 v17, v22, v22
	v_mul_f32_e32 v22, v18, v18
	v_max_f32_e32 v18, v23, v23
	v_max_f32_e32 v16, 0, v16
	v_max_f32_e32 v17, 0, v17
	v_max_f32_e32 v18, 0, v18
	v_max_f32_e32 v20, 0, v20
	v_mul_f32_e32 v16, v16, v16
	v_mul_f32_e32 v17, v17, v17
	v_max_f32_e32 v19, 0, v19
	v_mul_f32_e32 v18, v18, v18
	v_mul_f32_e32 v20, v20, v20
	v_mul_f32_e32 v19, v19, v19
	v_cvt_pk_bf16_f32 v16, v20, v16
	v_cvt_pk_bf16_f32 v17, v17, v18
	v_cvt_pk_bf16_f32 v18, v24, v21
	v_max_f32_e32 v8, 0, v8
	v_cvt_pk_bf16_f32 v19, v22, v19
	global_store_dwordx4 v[32:33], v[16:19], off offset:256
	s_nop 1
	v_max_f32_e32 v9, 0, v9
	v_max_f32_e32 v10, 0, v10
	v_mul_f32_e32 v18, v8, v8
	v_max_f32_e32 v8, v13, v13
	v_add_u32_e32 v16, 0xb0, v134
	v_max_f32_e32 v8, 0, v8
	v_mul_f32_e32 v13, v9, v9
	v_max_f32_e32 v9, v14, v14
	v_mul_f32_e32 v14, v10, v10
	v_max_f32_e32 v10, v15, v15
	v_mad_i64_i32 v[16:17], s[2:3], v16, s4, v[130:131]
	v_max_f32_e32 v12, 0, v12
	v_mul_f32_e32 v8, v8, v8
	v_max_f32_e32 v9, 0, v9
	v_max_f32_e32 v10, 0, v10
	v_max_f32_e32 v11, 0, v11
	v_lshl_add_u64 v[16:17], v[16:17], 0, v[64:65]
	v_mul_f32_e32 v12, v12, v12
	v_mul_f32_e32 v9, v9, v9
	v_mul_f32_e32 v10, v10, v10
	v_mul_f32_e32 v11, v11, v11
	v_cvt_pk_bf16_f32 v8, v12, v8
	v_max_f32_e32 v0, 0, v0
	v_max_f32_e32 v1, 0, v1
	v_max_f32_e32 v2, 0, v2
	v_cvt_pk_bf16_f32 v9, v9, v10
	v_cvt_pk_bf16_f32 v10, v18, v13
	v_cvt_pk_bf16_f32 v11, v14, v11
	global_store_dwordx4 v[16:17], v[8:11], off
	s_nop 1
	v_mul_f32_e32 v8, v0, v0
	v_max_f32_e32 v0, v5, v5
	v_mul_f32_e32 v5, v1, v1
	v_max_f32_e32 v1, v6, v6
	v_mul_f32_e32 v6, v2, v2
	v_max_f32_e32 v2, v7, v7
	v_max_f32_e32 v0, 0, v0
	v_max_f32_e32 v1, 0, v1
	v_max_f32_e32 v2, 0, v2
	v_max_f32_e32 v3, 0, v3
	v_max_f32_e32 v4, 0, v4
	v_mul_f32_e32 v0, v0, v0
	v_mul_f32_e32 v1, v1, v1
	v_mul_f32_e32 v2, v2, v2
	v_mul_f32_e32 v3, v3, v3
	v_mul_f32_e32 v4, v4, v4
	v_cvt_pk_bf16_f32 v0, v4, v0
	v_cvt_pk_bf16_f32 v1, v1, v2
	v_cvt_pk_bf16_f32 v2, v8, v5
	v_cvt_pk_bf16_f32 v3, v6, v3
	global_store_dwordx4 v[16:17], v[0:3], off offset:256
	s_nop 1
	s_waitcnt vmcnt(0)
	s_cmpk_lt_u32 s14, 0x100
	s_movk_i32 s27, 0x1000
	s_cbranch_scc0 .LBB0_149
	s_barrier

; #define PG8_STAGE(bufoff, gbase, voff) do { _Pragma("unroll") for (int _i = 0; _i < 2; ++_i) \
;         __builtin_amdgcn_global_load_lds((const unsigned*)((const char*)(gbase) + (voff)[_i]), (LAS unsigned*)(lds + (bufoff) + ldsw + _i * 8192), 16, 0, 0); } while (0)
; #define PG8_LDA(dst, b, h) do { _Pragma("unroll") for (int m = 0; m < 4; ++m) _Pragma("unroll") for (int k = 0; k < 2; ++k) dst[m][k] = *(const LAS bf16x8*)(lds + PG8_SA(b, h) + aoff + m * 2048 + k * 1024); } while (0)
; #define PG8_LDB(dst, b, h) do { _Pragma("unroll") for (int n = 0; n < 2; ++n) _Pragma("unroll") for (int k = 0; k < 2; ++k) dst[n][k] = *(const LAS bf16x8*)(lds + PG8_SB(b, h) + boff + n * 2048 + k * 1024); } while (0)
; #define PG8_MMA(ai, bj, At, Bt) do { __builtin_amdgcn_s_setprio(1); _Pragma("unroll") for (int m = 0; m < 4; ++m) _Pragma("unroll") for (int n = 0; n < 2; ++n) _Pragma("unroll") for (int k = 0; k < 2; ++k) \
;         acc[ai][bj][m][n] = __builtin_amdgcn_mfma_f32_16x16x32_bf16(Bt[n][k], At[m][k], acc[ai][bj][m][n], 0, 0, 0); __builtin_amdgcn_s_setprio(0); } while (0)
; #define PG8_WAIT_L(n) asm volatile("s_waitcnt lgkmcnt(" #n ")" ::: "memory")
; #define PG8_BAR __builtin_amdgcn_s_barrier()
; #define PG8_SCHED __builtin_amdgcn_sched_barrier(0)
;     ...
;             const char* a1 = cA + (size_t)(t + 1) * kstep;
;             const char* a2 = last ? nA : cA + (size_t)(t + 2) * kstep; const char* b2 = last ? nB : cB + (size_t)(t + 2) * kstep;
;             const char* a3 = a2 + kstep; const char* b3 = b2 + kstep;
;             PG8_LDB(B0, 0, 0); PG8_SCHED; PG8_LDA(At, 0, 0); PG8_STAGE(PG8_SA(1, 1), a1 + hstep, voffA);
;             PG8_WAIT_L(8); PG8_BAR; PG8_WAIT_L(0); PG8_MMA(0, 0, At, B0); PG8_BAR; PG8_SCHED;
;             PG8_LDB(B1, 0, 1); PG8_STAGE(PG8_SB(0, 0), b2, voffB);
;             PG8_BAR; PG8_WAIT_L(0); PG8_MMA(0, 1, At, B1); PG8_BAR;
;             PG8_LDA(At, 0, 1); PG8_STAGE(PG8_SA(0, 0), a2, voffA);
;             PG8_BAR; PG8_WAIT_L(0); PG8_MMA(1, 0, At, B0); PG8_BAR; PG8_SCHED;
.LBB0_475:
	s_or_b32 s94, s12, 1
	s_add_i32 s12, s12, 2
	s_mov_b32 s13, s95
	s_lshl_b64 s[2:3], s[12:13], 7
	s_add_u32 s7, s24, s2
	s_addc_u32 s13, s25, s3
	s_and_b64 vcc, s[44:45], exec
	s_cselect_b32 vcc_hi, s85, s13
	s_cselect_b32 vcc_lo, s84, s7
	s_add_u32 s7, s42, s2
	s_addc_u32 s13, s43, s3
	s_add_i32 s35, 0, 0x10000
	v_add_u32_e32 v64, s35, v220
	ds_read_b128 v[134:137], v64
	ds_read_b128 v[138:141], v64 offset:1024
	ds_read_b128 v[142:145], v64 offset:2048
	ds_read_b128 v[146:149], v64 offset:3072
	s_and_b64 s[2:3], s[44:45], exec
	s_cselect_b32 s45, s9, s13
	s_cselect_b32 s44, s8, s7
	s_lshl_b64 s[2:3], s[94:95], 7
	s_add_u32 s2, s47, s2
	s_addc_u32 s3, s89, s3
	v_lshl_add_u64 v[182:183], s[2:3], 0, v[130:131]
	s_add_i32 m0, s19, 0xc000
	ds_read_b128 v[150:153], v229
	ds_read_b128 v[154:157], v229 offset:1024
	ds_read_b128 v[158:161], v229 offset:2048
	ds_read_b128 v[162:165], v229 offset:3072
	ds_read_b128 v[166:169], v229 offset:4096
	ds_read_b128 v[170:173], v229 offset:5120
	ds_read_b128 v[174:177], v229 offset:6144
	ds_read_b128 v[178:181], v229 offset:7168
	global_load_lds_dwordx4 v[182:183], off
	v_lshl_add_u64 v[182:183], s[2:3], 0, v[132:133]
	s_add_i32 m0, s19, 0xe000
	s_nop 0
	global_load_lds_dwordx4 v[182:183], off
	s_waitcnt lgkmcnt(8)
	s_barrier
	s_waitcnt lgkmcnt(0)
	v_mfma_f32_16x16x32_bf16 v[118:121], v[134:137], v[150:153], v[118:121]
	v_mfma_f32_16x16x32_bf16 v[114:117], v[142:145], v[150:153], v[114:117]
	v_mfma_f32_16x16x32_bf16 v[102:105], v[134:137], v[158:161], v[102:105]
	v_mfma_f32_16x16x32_bf16 v[98:101], v[142:145], v[158:161], v[98:101]
	v_mfma_f32_16x16x32_bf16 v[86:89], v[134:137], v[166:169], v[86:89]
	v_mfma_f32_16x16x32_bf16 v[82:85], v[142:145], v[166:169], v[82:85]
	v_mfma_f32_16x16x32_bf16 v[70:73], v[134:137], v[174:177], v[70:73]
	v_mfma_f32_16x16x32_bf16 v[66:69], v[142:145], v[174:177], v[66:69]
	v_mfma_f32_16x16x32_bf16 v[118:121], v[138:141], v[154:157], v[118:121]
	v_mfma_f32_16x16x32_bf16 v[114:117], v[146:149], v[154:157], v[114:117]
	v_mfma_f32_16x16x32_bf16 v[102:105], v[138:141], v[162:165], v[102:105]
	v_mfma_f32_16x16x32_bf16 v[98:101], v[146:149], v[162:165], v[98:101]
	v_mfma_f32_16x16x32_bf16 v[86:89], v[138:141], v[170:173], v[86:89]
	v_mfma_f32_16x16x32_bf16 v[82:85], v[146:149], v[170:173], v[82:85]
	v_mfma_f32_16x16x32_bf16 v[70:73], v[138:141], v[178:181], v[70:73]
	v_mfma_f32_16x16x32_bf16 v[66:69], v[146:149], v[178:181], v[66:69]
	s_barrier
	s_add_i32 s7, 0, 0x14000
	s_add_i32 s2, s35, s18
	v_add_u32_e32 v64, s7, v220
	v_lshl_add_u64 v[198:199], s[44:45], 0, v[130:131]
	s_mov_b32 m0, s2
	ds_read_b128 v[182:185], v64
	ds_read_b128 v[186:189], v64 offset:1024
	ds_read_b128 v[190:193], v64 offset:2048
	ds_read_b128 v[194:197], v64 offset:3072
	global_load_lds_dwordx4 v[198:199], off
	v_lshl_add_u64 v[246:247], s[44:45], 0, v[132:133]
	s_add_i32 m0, s2, 0x2000
	s_nop 0
	global_load_lds_dwordx4 v[246:247], off
	s_waitcnt lgkmcnt(0)
	s_barrier
	v_mfma_f32_16x16x32_bf16 v[126:129], v[182:185], v[150:153], v[126:129]
	v_mfma_f32_16x16x32_bf16 v[122:125], v[190:193], v[150:153], v[122:125]
	v_mfma_f32_16x16x32_bf16 v[110:113], v[182:185], v[158:161], v[110:113]
	v_mfma_f32_16x16x32_bf16 v[106:109], v[190:193], v[158:161], v[106:109]
	v_mfma_f32_16x16x32_bf16 v[94:97], v[182:185], v[166:169], v[94:97]
	v_mfma_f32_16x16x32_bf16 v[90:93], v[190:193], v[166:169], v[90:93]
	v_mfma_f32_16x16x32_bf16 v[78:81], v[182:185], v[174:177], v[78:81]
	v_mfma_f32_16x16x32_bf16 v[74:77], v[190:193], v[174:177], v[74:77]
	v_mfma_f32_16x16x32_bf16 v[126:129], v[186:189], v[154:157], v[126:129]
	v_mfma_f32_16x16x32_bf16 v[122:125], v[194:197], v[154:157], v[122:125]
	v_mfma_f32_16x16x32_bf16 v[110:113], v[186:189], v[162:165], v[110:113]
	v_mfma_f32_16x16x32_bf16 v[106:109], v[194:197], v[162:165], v[106:109]
	v_mfma_f32_16x16x32_bf16 v[94:97], v[186:189], v[170:173], v[94:97]
	v_mfma_f32_16x16x32_bf16 v[90:93], v[194:197], v[170:173], v[90:93]
	v_mfma_f32_16x16x32_bf16 v[78:81], v[186:189], v[178:181], v[78:81]
	v_mfma_f32_16x16x32_bf16 v[74:77], v[194:197], v[178:181], v[74:77]
	s_mov_b32 m0, s19
	v_lshl_add_u64 v[212:213], vcc, 0, v[130:131]
	s_barrier
	ds_read_b128 v[150:153], v229 offset:16384
	ds_read_b128 v[154:157], v229 offset:17408
	ds_read_b128 v[158:161], v229 offset:18432
	ds_read_b128 v[162:165], v229 offset:19456
	ds_read_b128 v[166:169], v229 offset:20480
	ds_read_b128 v[170:173], v229 offset:21504
	ds_read_b128 v[174:177], v229 offset:22528
	ds_read_b128 v[178:181], v229 offset:23552
	global_load_lds_dwordx4 v[212:213], off
	v_lshl_add_u64 v[208:209], vcc, 0, v[132:133]
	s_mov_b32 m0, s21
	s_nop 0
	global_load_lds_dwordx4 v[208:209], off
	s_waitcnt lgkmcnt(0)
	s_barrier
	v_mfma_f32_16x16x32_bf16 v[52:55], v[134:137], v[150:153], v[52:55]
	v_mfma_f32_16x16x32_bf16 v[48:51], v[142:145], v[150:153], v[48:51]
	v_mfma_f32_16x16x32_bf16 v[36:39], v[134:137], v[158:161], v[36:39]
	v_mfma_f32_16x16x32_bf16 v[32:35], v[142:145], v[158:161], v[32:35]
	v_mfma_f32_16x16x32_bf16 v[20:23], v[134:137], v[166:169], v[20:23]
	v_mfma_f32_16x16x32_bf16 v[16:19], v[142:145], v[166:169], v[16:19]
	v_mfma_f32_16x16x32_bf16 v[4:7], v[134:137], v[174:177], v[4:7]
	v_mfma_f32_16x16x32_bf16 v[0:3], v[142:145], v[174:177], v[0:3]
	v_mfma_f32_16x16x32_bf16 v[52:55], v[138:141], v[154:157], v[52:55]
	v_mfma_f32_16x16x32_bf16 v[48:51], v[146:149], v[154:157], v[48:51]
	v_mfma_f32_16x16x32_bf16 v[36:39], v[138:141], v[162:165], v[36:39]
	v_mfma_f32_16x16x32_bf16 v[32:35], v[146:149], v[162:165], v[32:35]
	v_mfma_f32_16x16x32_bf16 v[20:23], v[138:141], v[170:173], v[20:23]
	v_mfma_f32_16x16x32_bf16 v[16:19], v[146:149], v[170:173], v[16:19]
	v_mfma_f32_16x16x32_bf16 v[4:7], v[138:141], v[178:181], v[4:7]
	v_mfma_f32_16x16x32_bf16 v[0:3], v[146:149], v[178:181], v[0:3]
	s_barrier
; #define PG8_STAGE(bufoff, gbase, voff) do { _Pragma("unroll") for (int _i = 0; _i < 2; ++_i) \
;         __builtin_amdgcn_global_load_lds((const unsigned*)((const char*)(gbase) + (voff)[_i]), (LAS unsigned*)(lds + (bufoff) + ldsw + _i * 8192), 16, 0, 0); } while (0)
; #define PG8_LDA(dst, b, h) do { _Pragma("unroll") for (int m = 0; m < 4; ++m) _Pragma("unroll") for (int k = 0; k < 2; ++k) dst[m][k] = *(const LAS bf16x8*)(lds + PG8_SA(b, h) + aoff + m * 2048 + k * 1024); } while (0)
; #define PG8_LDB(dst, b, h) do { _Pragma("unroll") for (int n = 0; n < 2; ++n) _Pragma("unroll") for (int k = 0; k < 2; ++k) dst[n][k] = *(const LAS bf16x8*)(lds + PG8_SB(b, h) + boff + n * 2048 + k * 1024); } while (0)
; #define PG8_MMA(ai, bj, At, Bt) do { __builtin_amdgcn_s_setprio(1); _Pragma("unroll") for (int m = 0; m < 4; ++m) _Pragma("unroll") for (int n = 0; n < 2; ++n) _Pragma("unroll") for (int k = 0; k < 2; ++k) \
;         acc[ai][bj][m][n] = __builtin_amdgcn_mfma_f32_16x16x32_bf16(Bt[n][k], At[m][k], acc[ai][bj][m][n], 0, 0, 0); __builtin_amdgcn_s_setprio(0); } while (0)
; #define PG8_WAIT_V(n) asm volatile("s_waitcnt vmcnt(" #n ")" ::: "memory")
; #define PG8_WAIT_L(n) asm volatile("s_waitcnt lgkmcnt(" #n ")" ::: "memory")
; #define PG8_BAR __builtin_amdgcn_s_barrier()
; #define PG8_SCHED __builtin_amdgcn_sched_barrier(0)
;     ...
;             PG8_STAGE(PG8_SB(0, 1), b2 + hstep, voffB);
;             PG8_WAIT_V(6); PG8_BAR; PG8_MMA(1, 1, At, B1); PG8_BAR;
;             PG8_LDB(B0, 1, 0); PG8_SCHED; PG8_LDA(At, 1, 0); PG8_STAGE(PG8_SA(0, 1), a2 + hstep, voffA);
;             PG8_WAIT_L(8); PG8_BAR; PG8_WAIT_L(0); PG8_MMA(0, 0, At, B0); PG8_BAR; PG8_SCHED;
;             PG8_LDB(B1, 1, 1); PG8_STAGE(PG8_SB(1, 0), b3, voffB);
;             PG8_BAR; PG8_WAIT_L(0); PG8_MMA(0, 1, At, B1); PG8_BAR;
;             PG8_LDA(At, 1, 1); PG8_STAGE(PG8_SA(1, 0), a3, voffA);
;             PG8_BAR; PG8_WAIT_L(0); PG8_MMA(1, 0, At, B0); PG8_BAR; PG8_SCHED;
	s_add_u32 s2, s44, s82
	s_addc_u32 s3, s45, 0
	s_add_i32 s7, s7, s18
	v_lshl_add_u64 v[210:211], s[2:3], 0, v[130:131]
	s_mov_b32 m0, s7
	v_lshl_add_u64 v[214:215], s[2:3], 0, v[132:133]
	global_load_lds_dwordx4 v[210:211], off
	s_add_i32 m0, s7, 0x2000
	s_nop 0
	global_load_lds_dwordx4 v[214:215], off
	s_waitcnt vmcnt(6)
	s_barrier
	v_mfma_f32_16x16x32_bf16 v[60:63], v[182:185], v[150:153], v[60:63]
	v_mfma_f32_16x16x32_bf16 v[56:59], v[190:193], v[150:153], v[56:59]
	v_mfma_f32_16x16x32_bf16 v[44:47], v[182:185], v[158:161], v[44:47]
	v_mfma_f32_16x16x32_bf16 v[40:43], v[190:193], v[158:161], v[40:43]
	v_mfma_f32_16x16x32_bf16 v[28:31], v[182:185], v[166:169], v[28:31]
	v_mfma_f32_16x16x32_bf16 v[24:27], v[190:193], v[166:169], v[24:27]
	v_mfma_f32_16x16x32_bf16 v[12:15], v[182:185], v[174:177], v[12:15]
	v_mfma_f32_16x16x32_bf16 v[8:11], v[190:193], v[174:177], v[8:11]
	v_mfma_f32_16x16x32_bf16 v[60:63], v[186:189], v[154:157], v[60:63]
	v_mfma_f32_16x16x32_bf16 v[56:59], v[194:197], v[154:157], v[56:59]
	v_mfma_f32_16x16x32_bf16 v[44:47], v[186:189], v[162:165], v[44:47]
	v_mfma_f32_16x16x32_bf16 v[40:43], v[194:197], v[162:165], v[40:43]
	v_mfma_f32_16x16x32_bf16 v[28:31], v[186:189], v[170:173], v[28:31]
	v_mfma_f32_16x16x32_bf16 v[24:27], v[194:197], v[170:173], v[24:27]
	v_mfma_f32_16x16x32_bf16 v[12:15], v[186:189], v[178:181], v[12:15]
	v_mfma_f32_16x16x32_bf16 v[8:11], v[194:197], v[178:181], v[8:11]
	s_add_i32 s7, 0, 0x18000
	v_add_u32_e32 v64, s7, v220
	s_barrier
	ds_read_b128 v[134:137], v64
	ds_read_b128 v[138:141], v64 offset:1024
	ds_read_b128 v[142:145], v64 offset:2048
	ds_read_b128 v[146:149], v64 offset:3072
	s_add_u32 s2, vcc_lo, s82
	s_addc_u32 s3, vcc_hi, 0
	s_mov_b32 m0, s31
	v_lshl_add_u64 v[182:183], s[2:3], 0, v[130:131]
	ds_read_b128 v[150:153], v229 offset:32768
	ds_read_b128 v[154:157], v229 offset:33792
	ds_read_b128 v[158:161], v229 offset:34816
	ds_read_b128 v[162:165], v229 offset:35840
	ds_read_b128 v[166:169], v229 offset:36864
	ds_read_b128 v[170:173], v229 offset:37888
	ds_read_b128 v[174:177], v229 offset:38912
	ds_read_b128 v[178:181], v229 offset:39936
	global_load_lds_dwordx4 v[182:183], off
	v_lshl_add_u64 v[182:183], s[2:3], 0, v[132:133]
	s_mov_b32 m0, s83
	s_nop 0
	global_load_lds_dwordx4 v[182:183], off
	s_waitcnt lgkmcnt(8)
	s_barrier
	s_waitcnt lgkmcnt(0)
	v_mfma_f32_16x16x32_bf16 v[118:121], v[134:137], v[150:153], v[118:121]
	v_mfma_f32_16x16x32_bf16 v[114:117], v[142:145], v[150:153], v[114:117]
	v_mfma_f32_16x16x32_bf16 v[102:105], v[134:137], v[158:161], v[102:105]
	v_mfma_f32_16x16x32_bf16 v[98:101], v[142:145], v[158:161], v[98:101]
	v_mfma_f32_16x16x32_bf16 v[86:89], v[134:137], v[166:169], v[86:89]
	v_mfma_f32_16x16x32_bf16 v[82:85], v[142:145], v[166:169], v[82:85]
	v_mfma_f32_16x16x32_bf16 v[70:73], v[134:137], v[174:177], v[70:73]
	v_mfma_f32_16x16x32_bf16 v[66:69], v[142:145], v[174:177], v[66:69]
	v_mfma_f32_16x16x32_bf16 v[118:121], v[138:141], v[154:157], v[118:121]
	v_mfma_f32_16x16x32_bf16 v[114:117], v[146:149], v[154:157], v[114:117]
	v_mfma_f32_16x16x32_bf16 v[102:105], v[138:141], v[162:165], v[102:105]
	v_mfma_f32_16x16x32_bf16 v[98:101], v[146:149], v[162:165], v[98:101]
	v_mfma_f32_16x16x32_bf16 v[86:89], v[138:141], v[170:173], v[86:89]
	v_mfma_f32_16x16x32_bf16 v[82:85], v[146:149], v[170:173], v[82:85]
	v_mfma_f32_16x16x32_bf16 v[70:73], v[138:141], v[178:181], v[70:73]
	v_mfma_f32_16x16x32_bf16 v[66:69], v[146:149], v[178:181], v[66:69]
	s_barrier
	s_add_i32 s2, 0, 0x1c000
	s_add_i32 s3, s7, s18
	v_add_u32_e32 v64, s2, v220
	v_lshl_add_u64 v[198:199], v[198:199], 0, s[16:17]
	s_mov_b32 m0, s3
	ds_read_b128 v[182:185], v64
	ds_read_b128 v[186:189], v64 offset:1024
	ds_read_b128 v[190:193], v64 offset:2048
	ds_read_b128 v[194:197], v64 offset:3072
	global_load_lds_dwordx4 v[198:199], off
	v_lshl_add_u64 v[198:199], v[246:247], 0, s[16:17]
	s_add_i32 m0, s3, 0x2000
	s_nop 0
	global_load_lds_dwordx4 v[198:199], off
	s_waitcnt lgkmcnt(0)
	s_barrier
; #define PG8_STAGE(bufoff, gbase, voff) do { _Pragma("unroll") for (int _i = 0; _i < 2; ++_i) \
;         __builtin_amdgcn_global_load_lds((const unsigned*)((const char*)(gbase) + (voff)[_i]), (LAS unsigned*)(lds + (bufoff) + ldsw + _i * 8192), 16, 0, 0); } while (0)
; #define PG8_MMA(ai, bj, At, Bt) do { __builtin_amdgcn_s_setprio(1); _Pragma("unroll") for (int m = 0; m < 4; ++m) _Pragma("unroll") for (int n = 0; n < 2; ++n) _Pragma("unroll") for (int k = 0; k < 2; ++k) \
;         acc[ai][bj][m][n] = __builtin_amdgcn_mfma_f32_16x16x32_bf16(Bt[n][k], At[m][k], acc[ai][bj][m][n], 0, 0, 0); __builtin_amdgcn_s_setprio(0); } while (0)
; #define PG8_WAIT_V(n) asm volatile("s_waitcnt vmcnt(" #n ")" ::: "memory")
; #define PG8_WAIT_L(n) asm volatile("s_waitcnt lgkmcnt(" #n ")" ::: "memory")
; #define PG8_BAR __builtin_amdgcn_s_barrier()
; #define PG8_SCHED __builtin_amdgcn_sched_barrier(0)
;     ...
;             PG8_BAR; PG8_WAIT_L(0); PG8_MMA(1, 0, At, B0); PG8_BAR; PG8_SCHED;
;             PG8_STAGE(PG8_SB(1, 1), b3 + hstep, voffB);
;             PG8_WAIT_V(6); PG8_BAR; PG8_MMA(1, 1, At, B1); PG8_BAR;
;         }
	v_mfma_f32_16x16x32_bf16 v[126:129], v[182:185], v[150:153], v[126:129]
	v_mfma_f32_16x16x32_bf16 v[122:125], v[190:193], v[150:153], v[122:125]
	v_mfma_f32_16x16x32_bf16 v[110:113], v[182:185], v[158:161], v[110:113]
	v_mfma_f32_16x16x32_bf16 v[106:109], v[190:193], v[158:161], v[106:109]
	v_mfma_f32_16x16x32_bf16 v[94:97], v[182:185], v[166:169], v[94:97]
	v_mfma_f32_16x16x32_bf16 v[90:93], v[190:193], v[166:169], v[90:93]
	v_mfma_f32_16x16x32_bf16 v[78:81], v[182:185], v[174:177], v[78:81]
	v_mfma_f32_16x16x32_bf16 v[74:77], v[190:193], v[174:177], v[74:77]
	v_mfma_f32_16x16x32_bf16 v[126:129], v[186:189], v[154:157], v[126:129]
	v_mfma_f32_16x16x32_bf16 v[122:125], v[194:197], v[154:157], v[122:125]
	v_mfma_f32_16x16x32_bf16 v[110:113], v[186:189], v[162:165], v[110:113]
	v_mfma_f32_16x16x32_bf16 v[106:109], v[194:197], v[162:165], v[106:109]
	v_mfma_f32_16x16x32_bf16 v[94:97], v[186:189], v[170:173], v[94:97]
	v_mfma_f32_16x16x32_bf16 v[90:93], v[194:197], v[170:173], v[90:93]
	v_mfma_f32_16x16x32_bf16 v[78:81], v[186:189], v[178:181], v[78:81]
	v_mfma_f32_16x16x32_bf16 v[74:77], v[194:197], v[178:181], v[74:77]
	s_mov_b32 m0, s36
	v_lshl_add_u64 v[198:199], v[212:213], 0, s[16:17]
	s_barrier
	ds_read_b128 v[150:153], v229 offset:49152
	ds_read_b128 v[154:157], v229 offset:50176
	ds_read_b128 v[158:161], v229 offset:51200
	ds_read_b128 v[162:165], v229 offset:52224
	ds_read_b128 v[166:169], v229 offset:53248
	ds_read_b128 v[170:173], v229 offset:54272
	ds_read_b128 v[174:177], v229 offset:55296
	ds_read_b128 v[178:181], v229 offset:56320
	global_load_lds_dwordx4 v[198:199], off
	v_lshl_add_u64 v[198:199], v[208:209], 0, s[16:17]
	s_mov_b32 m0, s37
	s_nop 0
	global_load_lds_dwordx4 v[198:199], off
	s_waitcnt lgkmcnt(0)
	s_barrier
	v_mfma_f32_16x16x32_bf16 v[52:55], v[134:137], v[150:153], v[52:55]
	v_mfma_f32_16x16x32_bf16 v[48:51], v[142:145], v[150:153], v[48:51]
	v_mfma_f32_16x16x32_bf16 v[36:39], v[134:137], v[158:161], v[36:39]
	v_mfma_f32_16x16x32_bf16 v[32:35], v[142:145], v[158:161], v[32:35]
	v_mfma_f32_16x16x32_bf16 v[20:23], v[134:137], v[166:169], v[20:23]
	v_mfma_f32_16x16x32_bf16 v[16:19], v[142:145], v[166:169], v[16:19]
	v_mfma_f32_16x16x32_bf16 v[4:7], v[134:137], v[174:177], v[4:7]
	v_mfma_f32_16x16x32_bf16 v[0:3], v[142:145], v[174:177], v[0:3]
	v_mfma_f32_16x16x32_bf16 v[52:55], v[138:141], v[154:157], v[52:55]
	v_mfma_f32_16x16x32_bf16 v[48:51], v[146:149], v[154:157], v[48:51]
	v_mfma_f32_16x16x32_bf16 v[36:39], v[138:141], v[162:165], v[36:39]
	v_mfma_f32_16x16x32_bf16 v[32:35], v[146:149], v[162:165], v[32:35]
	v_mfma_f32_16x16x32_bf16 v[20:23], v[138:141], v[170:173], v[20:23]
	v_mfma_f32_16x16x32_bf16 v[16:19], v[146:149], v[170:173], v[16:19]
	v_mfma_f32_16x16x32_bf16 v[4:7], v[138:141], v[178:181], v[4:7]
	v_mfma_f32_16x16x32_bf16 v[0:3], v[146:149], v[178:181], v[0:3]
	s_barrier
	s_add_i32 s2, s2, s18
	v_lshl_add_u64 v[134:135], v[210:211], 0, s[16:17]
	s_mov_b32 m0, s2
	s_nop 0
	global_load_lds_dwordx4 v[134:135], off
	v_lshl_add_u64 v[134:135], v[214:215], 0, s[16:17]
	s_add_i32 m0, s2, 0x2000
	s_nop 0
	global_load_lds_dwordx4 v[134:135], off
	s_waitcnt vmcnt(6)
	s_barrier
	v_mfma_f32_16x16x32_bf16 v[60:63], v[182:185], v[150:153], v[60:63]
	v_mfma_f32_16x16x32_bf16 v[56:59], v[190:193], v[150:153], v[56:59]
	v_mfma_f32_16x16x32_bf16 v[44:47], v[182:185], v[158:161], v[44:47]
	v_mfma_f32_16x16x32_bf16 v[40:43], v[190:193], v[158:161], v[40:43]
	v_mfma_f32_16x16x32_bf16 v[28:31], v[182:185], v[166:169], v[28:31]
	v_mfma_f32_16x16x32_bf16 v[24:27], v[190:193], v[166:169], v[24:27]
	v_mfma_f32_16x16x32_bf16 v[12:15], v[182:185], v[174:177], v[12:15]
	v_mfma_f32_16x16x32_bf16 v[8:11], v[190:193], v[174:177], v[8:11]
	v_mfma_f32_16x16x32_bf16 v[60:63], v[186:189], v[154:157], v[60:63]
	v_mfma_f32_16x16x32_bf16 v[56:59], v[194:197], v[154:157], v[56:59]
	v_mfma_f32_16x16x32_bf16 v[44:47], v[186:189], v[162:165], v[44:47]
	v_mfma_f32_16x16x32_bf16 v[40:43], v[194:197], v[162:165], v[40:43]
	v_mfma_f32_16x16x32_bf16 v[28:31], v[186:189], v[170:173], v[28:31]
	v_mfma_f32_16x16x32_bf16 v[24:27], v[194:197], v[170:173], v[24:27]
	v_mfma_f32_16x16x32_bf16 v[12:15], v[186:189], v[178:181], v[12:15]
	v_mfma_f32_16x16x32_bf16 v[8:11], v[194:197], v[178:181], v[8:11]
	s_cmp_ge_u32 s12, s6
	s_barrier
	s_cbranch_scc1 .LBB0_482

; #define PG8_STAGE(bufoff, gbase, voff) do { _Pragma("unroll") for (int _i = 0; _i < 2; ++_i) \
;         __builtin_amdgcn_global_load_lds((const unsigned*)((const char*)(gbase) + (voff)[_i]), (LAS unsigned*)(lds + (bufoff) + ldsw + _i * 8192), 16, 0, 0); } while (0)
; #define PG8_LDA(dst, b, h) do { _Pragma("unroll") for (int m = 0; m < 4; ++m) _Pragma("unroll") for (int k = 0; k < 2; ++k) dst[m][k] = *(const LAS bf16x8*)(lds + PG8_SA(b, h) + aoff + m * 2048 + k * 1024); } while (0)
; #define PG8_LDB(dst, b, h) do { _Pragma("unroll") for (int n = 0; n < 2; ++n) _Pragma("unroll") for (int k = 0; k < 2; ++k) dst[n][k] = *(const LAS bf16x8*)(lds + PG8_SB(b, h) + boff + n * 2048 + k * 1024); } while (0)
; #define PG8_MMA(ai, bj, At, Bt) do { __builtin_amdgcn_s_setprio(1); _Pragma("unroll") for (int m = 0; m < 4; ++m) _Pragma("unroll") for (int n = 0; n < 2; ++n) _Pragma("unroll") for (int k = 0; k < 2; ++k) \
;         acc[ai][bj][m][n] = __builtin_amdgcn_mfma_f32_16x16x32_bf16(Bt[n][k], At[m][k], acc[ai][bj][m][n], 0, 0, 0); __builtin_amdgcn_s_setprio(0); } while (0)
; #define PG8_WAIT_L(n) asm volatile("s_waitcnt lgkmcnt(" #n ")" ::: "memory")
; #define PG8_BAR __builtin_amdgcn_s_barrier()
; #define PG8_SCHED __builtin_amdgcn_sched_barrier(0)
;     ...
;             const char* a1 = cA + (size_t)(t + 1) * kstep;
;             const char* a2 = last ? nA : cA + (size_t)(t + 2) * kstep; const char* b2 = last ? nB : cB + (size_t)(t + 2) * kstep;
;             const char* a3 = a2 + kstep; const char* b3 = b2 + kstep;
;             PG8_LDB(B0, 0, 0); PG8_SCHED; PG8_LDA(At, 0, 0); PG8_STAGE(PG8_SA(1, 1), a1 + hstep, voffA);
;             PG8_WAIT_L(8); PG8_BAR; PG8_WAIT_L(0); PG8_MMA(0, 0, At, B0); PG8_BAR; PG8_SCHED;
;             PG8_LDB(B1, 0, 1); PG8_STAGE(PG8_SB(0, 0), b2, voffB);
;             PG8_BAR; PG8_WAIT_L(0); PG8_MMA(0, 1, At, B1); PG8_BAR;
;             PG8_LDA(At, 0, 1); PG8_STAGE(PG8_SA(0, 0), a2, voffA);
;             PG8_BAR; PG8_WAIT_L(0); PG8_MMA(1, 0, At, B0); PG8_BAR; PG8_SCHED;
.LBB0_1275:
	s_add_u32 s2, s6, 0xe767c080
	s_addc_u32 s3, s7, -1
	s_cmp_lg_u32 s23, 28
	s_cselect_b32 s8, s2, 0
	s_cselect_b32 s9, s3, 0
	s_add_u32 s2, s4, s8
	s_addc_u32 s3, s5, s9
	s_add_i32 s24, 0, 0x10000
	v_add_u32_e32 v152, s24, v138
	ds_read_b128 v[140:143], v152
	ds_read_b128 v[144:147], v152 offset:1024
	ds_read_b128 v[148:151], v152 offset:2048
	ds_read_b128 v[152:155], v152 offset:3072
	s_add_u32 s8, s0, s8
	s_addc_u32 s9, s1, s9
	v_lshl_add_u64 v[188:189], v[132:133], 0, s[6:7]
	s_add_i32 m0, s15, 0xc000
	ds_read_b128 v[156:159], v139
	ds_read_b128 v[160:163], v139 offset:1024
	ds_read_b128 v[164:167], v139 offset:2048
	ds_read_b128 v[168:171], v139 offset:3072
	ds_read_b128 v[172:175], v139 offset:4096
	ds_read_b128 v[176:179], v139 offset:5120
	ds_read_b128 v[180:183], v139 offset:6144
	ds_read_b128 v[184:187], v139 offset:7168
	global_load_lds_dwordx4 v[188:189], off
	v_lshl_add_u64 v[188:189], v[134:135], 0, s[6:7]
	s_add_i32 m0, s15, 0xe000
	s_nop 0
	global_load_lds_dwordx4 v[188:189], off
	s_waitcnt lgkmcnt(8)
	s_barrier
	s_waitcnt lgkmcnt(0)
	v_mfma_f32_16x16x32_bf16 v[126:129], v[140:143], v[156:159], v[126:129]
	v_mfma_f32_16x16x32_bf16 v[122:125], v[148:151], v[156:159], v[122:125]
	v_mfma_f32_16x16x32_bf16 v[110:113], v[140:143], v[164:167], v[110:113]
	v_mfma_f32_16x16x32_bf16 v[106:109], v[148:151], v[164:167], v[106:109]
	v_mfma_f32_16x16x32_bf16 v[94:97], v[140:143], v[172:175], v[94:97]
	v_mfma_f32_16x16x32_bf16 v[90:93], v[148:151], v[172:175], v[90:93]
	v_mfma_f32_16x16x32_bf16 v[78:81], v[140:143], v[180:183], v[78:81]
	v_mfma_f32_16x16x32_bf16 v[74:77], v[148:151], v[180:183], v[74:77]
	v_mfma_f32_16x16x32_bf16 v[126:129], v[144:147], v[160:163], v[126:129]
	v_mfma_f32_16x16x32_bf16 v[122:125], v[152:155], v[160:163], v[122:125]
	v_mfma_f32_16x16x32_bf16 v[110:113], v[144:147], v[168:171], v[110:113]
	v_mfma_f32_16x16x32_bf16 v[106:109], v[152:155], v[168:171], v[106:109]
	v_mfma_f32_16x16x32_bf16 v[94:97], v[144:147], v[176:179], v[94:97]
	v_mfma_f32_16x16x32_bf16 v[90:93], v[152:155], v[176:179], v[90:93]
	v_mfma_f32_16x16x32_bf16 v[78:81], v[144:147], v[184:187], v[78:81]
	v_mfma_f32_16x16x32_bf16 v[74:77], v[152:155], v[184:187], v[74:77]
	s_barrier
	s_add_i32 s26, 0, 0x14000
	s_add_i32 s24, s24, s14
	v_add_u32_e32 v208, s26, v138
	v_lshl_add_u64 v[224:225], s[8:9], 0, v[64:65]
	s_mov_b32 m0, s24
	ds_read_b128 v[188:191], v208
	ds_read_b128 v[192:195], v208 offset:1024
	ds_read_b128 v[196:199], v208 offset:2048
	ds_read_b128 v[220:223], v208 offset:3072
	global_load_lds_dwordx4 v[224:225], off
	v_lshl_add_u64 v[226:227], s[8:9], 0, v[130:131]
	s_add_i32 m0, s24, 0x2000
	s_nop 0
	global_load_lds_dwordx4 v[226:227], off
	s_waitcnt lgkmcnt(0)
	s_barrier
	v_mfma_f32_16x16x32_bf16 v[118:121], v[188:191], v[156:159], v[118:121]
	v_mfma_f32_16x16x32_bf16 v[114:117], v[196:199], v[156:159], v[114:117]
	v_mfma_f32_16x16x32_bf16 v[102:105], v[188:191], v[164:167], v[102:105]
	v_mfma_f32_16x16x32_bf16 v[98:101], v[196:199], v[164:167], v[98:101]
	v_mfma_f32_16x16x32_bf16 v[86:89], v[188:191], v[172:175], v[86:89]
	v_mfma_f32_16x16x32_bf16 v[82:85], v[196:199], v[172:175], v[82:85]
	v_mfma_f32_16x16x32_bf16 v[70:73], v[188:191], v[180:183], v[70:73]
	v_mfma_f32_16x16x32_bf16 v[66:69], v[196:199], v[180:183], v[66:69]
	v_mfma_f32_16x16x32_bf16 v[118:121], v[192:195], v[160:163], v[118:121]
	v_mfma_f32_16x16x32_bf16 v[114:117], v[220:223], v[160:163], v[114:117]
	v_mfma_f32_16x16x32_bf16 v[102:105], v[192:195], v[168:171], v[102:105]
	v_mfma_f32_16x16x32_bf16 v[98:101], v[220:223], v[168:171], v[98:101]
	v_mfma_f32_16x16x32_bf16 v[86:89], v[192:195], v[176:179], v[86:89]
	v_mfma_f32_16x16x32_bf16 v[82:85], v[220:223], v[176:179], v[82:85]
	v_mfma_f32_16x16x32_bf16 v[70:73], v[192:195], v[184:187], v[70:73]
	v_mfma_f32_16x16x32_bf16 v[66:69], v[220:223], v[184:187], v[66:69]
	s_mov_b32 m0, s15
	v_lshl_add_u64 v[228:229], s[2:3], 0, v[64:65]
	s_barrier
	ds_read_b128 v[156:159], v139 offset:16384
	ds_read_b128 v[160:163], v139 offset:17408
	ds_read_b128 v[164:167], v139 offset:18432
	ds_read_b128 v[168:171], v139 offset:19456
	ds_read_b128 v[172:175], v139 offset:20480
	ds_read_b128 v[176:179], v139 offset:21504
	ds_read_b128 v[180:183], v139 offset:22528
	ds_read_b128 v[184:187], v139 offset:23552
	global_load_lds_dwordx4 v[228:229], off
	v_lshl_add_u64 v[230:231], s[2:3], 0, v[130:131]
	s_mov_b32 m0, s18
	s_nop 0
	global_load_lds_dwordx4 v[230:231], off
	s_waitcnt lgkmcnt(0)
	s_barrier
	v_mfma_f32_16x16x32_bf16 v[60:63], v[140:143], v[156:159], v[60:63]
	v_mfma_f32_16x16x32_bf16 v[56:59], v[148:151], v[156:159], v[56:59]
	v_mfma_f32_16x16x32_bf16 v[44:47], v[140:143], v[164:167], v[44:47]
	v_mfma_f32_16x16x32_bf16 v[40:43], v[148:151], v[164:167], v[40:43]
	v_mfma_f32_16x16x32_bf16 v[28:31], v[140:143], v[172:175], v[28:31]
	v_mfma_f32_16x16x32_bf16 v[24:27], v[148:151], v[172:175], v[24:27]
	v_mfma_f32_16x16x32_bf16 v[12:15], v[140:143], v[180:183], v[12:15]
	v_mfma_f32_16x16x32_bf16 v[8:11], v[148:151], v[180:183], v[8:11]
	v_mfma_f32_16x16x32_bf16 v[60:63], v[144:147], v[160:163], v[60:63]
	v_mfma_f32_16x16x32_bf16 v[56:59], v[152:155], v[160:163], v[56:59]
	v_mfma_f32_16x16x32_bf16 v[44:47], v[144:147], v[168:171], v[44:47]
	v_mfma_f32_16x16x32_bf16 v[40:43], v[152:155], v[168:171], v[40:43]
	v_mfma_f32_16x16x32_bf16 v[28:31], v[144:147], v[176:179], v[28:31]
	v_mfma_f32_16x16x32_bf16 v[24:27], v[152:155], v[176:179], v[24:27]
	v_mfma_f32_16x16x32_bf16 v[12:15], v[144:147], v[184:187], v[12:15]
	v_mfma_f32_16x16x32_bf16 v[8:11], v[152:155], v[184:187], v[8:11]
	s_barrier
; #define PG8_STAGE(bufoff, gbase, voff) do { _Pragma("unroll") for (int _i = 0; _i < 2; ++_i) \
;         __builtin_amdgcn_global_load_lds((const unsigned*)((const char*)(gbase) + (voff)[_i]), (LAS unsigned*)(lds + (bufoff) + ldsw + _i * 8192), 16, 0, 0); } while (0)
; #define PG8_LDA(dst, b, h) do { _Pragma("unroll") for (int m = 0; m < 4; ++m) _Pragma("unroll") for (int k = 0; k < 2; ++k) dst[m][k] = *(const LAS bf16x8*)(lds + PG8_SA(b, h) + aoff + m * 2048 + k * 1024); } while (0)
; #define PG8_LDB(dst, b, h) do { _Pragma("unroll") for (int n = 0; n < 2; ++n) _Pragma("unroll") for (int k = 0; k < 2; ++k) dst[n][k] = *(const LAS bf16x8*)(lds + PG8_SB(b, h) + boff + n * 2048 + k * 1024); } while (0)
; #define PG8_MMA(ai, bj, At, Bt) do { __builtin_amdgcn_s_setprio(1); _Pragma("unroll") for (int m = 0; m < 4; ++m) _Pragma("unroll") for (int n = 0; n < 2; ++n) _Pragma("unroll") for (int k = 0; k < 2; ++k) \
;         acc[ai][bj][m][n] = __builtin_amdgcn_mfma_f32_16x16x32_bf16(Bt[n][k], At[m][k], acc[ai][bj][m][n], 0, 0, 0); __builtin_amdgcn_s_setprio(0); } while (0)
; #define PG8_WAIT_V(n) asm volatile("s_waitcnt vmcnt(" #n ")" ::: "memory")
; #define PG8_WAIT_L(n) asm volatile("s_waitcnt lgkmcnt(" #n ")" ::: "memory")
; #define PG8_BAR __builtin_amdgcn_s_barrier()
; #define PG8_SCHED __builtin_amdgcn_sched_barrier(0)
;     ...
;             PG8_STAGE(PG8_SB(0, 1), b2 + hstep, voffB);
;             PG8_WAIT_V(6); PG8_BAR; PG8_MMA(1, 1, At, B1); PG8_BAR;
;             PG8_LDB(B0, 1, 0); PG8_SCHED; PG8_LDA(At, 1, 0); PG8_STAGE(PG8_SA(0, 1), a2 + hstep, voffA);
;             PG8_WAIT_L(8); PG8_BAR; PG8_WAIT_L(0); PG8_MMA(0, 0, At, B0); PG8_BAR; PG8_SCHED;
;             PG8_LDB(B1, 1, 1); PG8_STAGE(PG8_SB(1, 0), b3, voffB);
;             PG8_BAR; PG8_WAIT_L(0); PG8_MMA(0, 1, At, B1); PG8_BAR;
;             PG8_LDA(At, 1, 1); PG8_STAGE(PG8_SA(1, 0), a3, voffA);
;             PG8_BAR; PG8_WAIT_L(0); PG8_MMA(1, 0, At, B0); PG8_BAR; PG8_SCHED;
	s_add_u32 s24, s8, 0x84000
	s_addc_u32 s25, s9, 0
	s_add_i32 s26, s26, s14
	v_lshl_add_u64 v[140:141], s[24:25], 0, v[64:65]
	s_mov_b32 m0, s26
	s_nop 0
	global_load_lds_dwordx4 v[140:141], off
	v_lshl_add_u64 v[140:141], s[24:25], 0, v[130:131]
	s_add_i32 m0, s26, 0x2000
	s_nop 0
	global_load_lds_dwordx4 v[140:141], off
	s_waitcnt vmcnt(6)
	s_barrier
	v_mfma_f32_16x16x32_bf16 v[52:55], v[188:191], v[156:159], v[52:55]
	v_mfma_f32_16x16x32_bf16 v[48:51], v[196:199], v[156:159], v[48:51]
	v_mfma_f32_16x16x32_bf16 v[36:39], v[188:191], v[164:167], v[36:39]
	v_mfma_f32_16x16x32_bf16 v[32:35], v[196:199], v[164:167], v[32:35]
	v_mfma_f32_16x16x32_bf16 v[20:23], v[188:191], v[172:175], v[20:23]
	v_mfma_f32_16x16x32_bf16 v[16:19], v[196:199], v[172:175], v[16:19]
	v_mfma_f32_16x16x32_bf16 v[4:7], v[188:191], v[180:183], v[4:7]
	v_mfma_f32_16x16x32_bf16 v[0:3], v[196:199], v[180:183], v[0:3]
	v_mfma_f32_16x16x32_bf16 v[52:55], v[192:195], v[160:163], v[52:55]
	v_mfma_f32_16x16x32_bf16 v[48:51], v[220:223], v[160:163], v[48:51]
	v_mfma_f32_16x16x32_bf16 v[36:39], v[192:195], v[168:171], v[36:39]
	v_mfma_f32_16x16x32_bf16 v[32:35], v[220:223], v[168:171], v[32:35]
	v_mfma_f32_16x16x32_bf16 v[20:23], v[192:195], v[176:179], v[20:23]
	v_mfma_f32_16x16x32_bf16 v[16:19], v[220:223], v[176:179], v[16:19]
	v_mfma_f32_16x16x32_bf16 v[4:7], v[192:195], v[184:187], v[4:7]
	v_mfma_f32_16x16x32_bf16 v[0:3], v[220:223], v[184:187], v[0:3]
	s_add_i32 s24, 0, 0x18000
	v_add_u32_e32 v152, s24, v138
	s_barrier
	ds_read_b128 v[140:143], v152
	ds_read_b128 v[144:147], v152 offset:1024
	ds_read_b128 v[148:151], v152 offset:2048
	ds_read_b128 v[152:155], v152 offset:3072
	s_add_u32 s2, s2, 0x84000
	s_addc_u32 s3, s3, 0
	s_mov_b32 m0, s19
	v_lshl_add_u64 v[188:189], s[2:3], 0, v[64:65]
	ds_read_b128 v[156:159], v139 offset:32768
	ds_read_b128 v[160:163], v139 offset:33792
	ds_read_b128 v[164:167], v139 offset:34816
	ds_read_b128 v[168:171], v139 offset:35840
	ds_read_b128 v[172:175], v139 offset:36864
	ds_read_b128 v[176:179], v139 offset:37888
	ds_read_b128 v[180:183], v139 offset:38912
	ds_read_b128 v[184:187], v139 offset:39936
	global_load_lds_dwordx4 v[188:189], off
	v_lshl_add_u64 v[188:189], s[2:3], 0, v[130:131]
	s_mov_b32 m0, s20
	s_nop 0
	global_load_lds_dwordx4 v[188:189], off
	s_waitcnt lgkmcnt(8)
	s_barrier
	s_waitcnt lgkmcnt(0)
	v_mfma_f32_16x16x32_bf16 v[126:129], v[140:143], v[156:159], v[126:129]
	v_mfma_f32_16x16x32_bf16 v[122:125], v[148:151], v[156:159], v[122:125]
	v_mfma_f32_16x16x32_bf16 v[110:113], v[140:143], v[164:167], v[110:113]
	v_mfma_f32_16x16x32_bf16 v[106:109], v[148:151], v[164:167], v[106:109]
	v_mfma_f32_16x16x32_bf16 v[94:97], v[140:143], v[172:175], v[94:97]
	v_mfma_f32_16x16x32_bf16 v[90:93], v[148:151], v[172:175], v[90:93]
	v_mfma_f32_16x16x32_bf16 v[78:81], v[140:143], v[180:183], v[78:81]
	v_mfma_f32_16x16x32_bf16 v[74:77], v[148:151], v[180:183], v[74:77]
	v_mfma_f32_16x16x32_bf16 v[126:129], v[144:147], v[160:163], v[126:129]
	v_mfma_f32_16x16x32_bf16 v[122:125], v[152:155], v[160:163], v[122:125]
	v_mfma_f32_16x16x32_bf16 v[110:113], v[144:147], v[168:171], v[110:113]
	v_mfma_f32_16x16x32_bf16 v[106:109], v[152:155], v[168:171], v[106:109]
	v_mfma_f32_16x16x32_bf16 v[94:97], v[144:147], v[176:179], v[94:97]
	v_mfma_f32_16x16x32_bf16 v[90:93], v[152:155], v[176:179], v[90:93]
	v_mfma_f32_16x16x32_bf16 v[78:81], v[144:147], v[184:187], v[78:81]
	v_mfma_f32_16x16x32_bf16 v[74:77], v[152:155], v[184:187], v[74:77]
	s_barrier
	s_add_i32 s25, 0, 0x1c000
	s_add_i32 s2, s24, s14
	v_add_u32_e32 v208, s25, v138
	v_lshl_add_u64 v[224:225], v[224:225], 0, s[16:17]
	s_mov_b32 m0, s2
	ds_read_b128 v[188:191], v208
	ds_read_b128 v[192:195], v208 offset:1024
	ds_read_b128 v[196:199], v208 offset:2048
	ds_read_b128 v[220:223], v208 offset:3072
	global_load_lds_dwordx4 v[224:225], off
	v_lshl_add_u64 v[224:225], v[226:227], 0, s[16:17]
	s_add_i32 m0, s2, 0x2000
	s_nop 0
	global_load_lds_dwordx4 v[224:225], off
	s_waitcnt lgkmcnt(0)
	s_barrier
	v_mfma_f32_16x16x32_bf16 v[118:121], v[188:191], v[156:159], v[118:121]
	v_mfma_f32_16x16x32_bf16 v[114:117], v[196:199], v[156:159], v[114:117]
	v_mfma_f32_16x16x32_bf16 v[102:105], v[188:191], v[164:167], v[102:105]
	v_mfma_f32_16x16x32_bf16 v[98:101], v[196:199], v[164:167], v[98:101]
	v_mfma_f32_16x16x32_bf16 v[86:89], v[188:191], v[172:175], v[86:89]
	v_mfma_f32_16x16x32_bf16 v[82:85], v[196:199], v[172:175], v[82:85]
	v_mfma_f32_16x16x32_bf16 v[70:73], v[188:191], v[180:183], v[70:73]
	v_mfma_f32_16x16x32_bf16 v[66:69], v[196:199], v[180:183], v[66:69]
	v_mfma_f32_16x16x32_bf16 v[118:121], v[192:195], v[160:163], v[118:121]
	v_mfma_f32_16x16x32_bf16 v[114:117], v[220:223], v[160:163], v[114:117]
	v_mfma_f32_16x16x32_bf16 v[102:105], v[192:195], v[168:171], v[102:105]
	v_mfma_f32_16x16x32_bf16 v[98:101], v[220:223], v[168:171], v[98:101]
	v_mfma_f32_16x16x32_bf16 v[86:89], v[192:195], v[176:179], v[86:89]
	v_mfma_f32_16x16x32_bf16 v[82:85], v[220:223], v[176:179], v[82:85]
	v_mfma_f32_16x16x32_bf16 v[70:73], v[192:195], v[184:187], v[70:73]
	v_mfma_f32_16x16x32_bf16 v[66:69], v[220:223], v[184:187], v[66:69]
	s_mov_b32 m0, s21
	v_lshl_add_u64 v[224:225], v[228:229], 0, s[16:17]
	s_barrier
; #define PG8_STAGE(bufoff, gbase, voff) do { _Pragma("unroll") for (int _i = 0; _i < 2; ++_i) \
;         __builtin_amdgcn_global_load_lds((const unsigned*)((const char*)(gbase) + (voff)[_i]), (LAS unsigned*)(lds + (bufoff) + ldsw + _i * 8192), 16, 0, 0); } while (0)
; #define PG8_MMA(ai, bj, At, Bt) do { __builtin_amdgcn_s_setprio(1); _Pragma("unroll") for (int m = 0; m < 4; ++m) _Pragma("unroll") for (int n = 0; n < 2; ++n) _Pragma("unroll") for (int k = 0; k < 2; ++k) \
;         acc[ai][bj][m][n] = __builtin_amdgcn_mfma_f32_16x16x32_bf16(Bt[n][k], At[m][k], acc[ai][bj][m][n], 0, 0, 0); __builtin_amdgcn_s_setprio(0); } while (0)
; #define PG8_WAIT_V(n) asm volatile("s_waitcnt vmcnt(" #n ")" ::: "memory")
; #define PG8_WAIT_L(n) asm volatile("s_waitcnt lgkmcnt(" #n ")" ::: "memory")
; #define PG8_BAR __builtin_amdgcn_s_barrier()
; #define PG8_SCHED __builtin_amdgcn_sched_barrier(0)
; __device__ __forceinline__ f32x4 gelu4(const f32x4 x) {
;     const f32x4 t = x * x, a = x * (t * -0.10294324f + -2.3022082f);
;     f32x4 e; e[0] = __builtin_amdgcn_exp2f(a[0]); e[1] = __builtin_amdgcn_exp2f(a[1]); e[2] = __builtin_amdgcn_exp2f(a[2]); e[3] = __builtin_amdgcn_exp2f(a[3]);
;     const f32x4 d = e + 1.0f;
;     f32x4 r; r[0] = __builtin_amdgcn_rcpf(d[0]); r[1] = __builtin_amdgcn_rcpf(d[1]); r[2] = __builtin_amdgcn_rcpf(d[2]); r[3] = __builtin_amdgcn_rcpf(d[3]);
;     return x * r;
;     ...
;             PG8_BAR; PG8_WAIT_L(0); PG8_MMA(1, 0, At, B0); PG8_BAR; PG8_SCHED;
;             PG8_STAGE(PG8_SB(1, 1), b3 + hstep, voffB);
;             PG8_WAIT_V(6); PG8_BAR; PG8_MMA(1, 1, At, B1); PG8_BAR;
;         }
	ds_read_b128 v[156:159], v139 offset:49152
	ds_read_b128 v[160:163], v139 offset:50176
	ds_read_b128 v[164:167], v139 offset:51200
	ds_read_b128 v[168:171], v139 offset:52224
	ds_read_b128 v[172:175], v139 offset:53248
	ds_read_b128 v[176:179], v139 offset:54272
	ds_read_b128 v[180:183], v139 offset:55296
	ds_read_b128 v[184:187], v139 offset:56320
	global_load_lds_dwordx4 v[224:225], off
	v_lshl_add_u64 v[224:225], v[230:231], 0, s[16:17]
	s_mov_b32 m0, s22
	s_nop 0
	global_load_lds_dwordx4 v[224:225], off
	s_waitcnt lgkmcnt(0)
	s_barrier
	v_mfma_f32_16x16x32_bf16 v[60:63], v[140:143], v[156:159], v[60:63]
	v_mfma_f32_16x16x32_bf16 v[56:59], v[148:151], v[156:159], v[56:59]
	v_mfma_f32_16x16x32_bf16 v[44:47], v[140:143], v[164:167], v[44:47]
	v_mfma_f32_16x16x32_bf16 v[40:43], v[148:151], v[164:167], v[40:43]
	v_mfma_f32_16x16x32_bf16 v[28:31], v[140:143], v[172:175], v[28:31]
	v_mfma_f32_16x16x32_bf16 v[24:27], v[148:151], v[172:175], v[24:27]
	v_mfma_f32_16x16x32_bf16 v[12:15], v[140:143], v[180:183], v[12:15]
	v_mfma_f32_16x16x32_bf16 v[8:11], v[148:151], v[180:183], v[8:11]
	v_mfma_f32_16x16x32_bf16 v[60:63], v[144:147], v[160:163], v[60:63]
	v_mfma_f32_16x16x32_bf16 v[56:59], v[152:155], v[160:163], v[56:59]
	v_mfma_f32_16x16x32_bf16 v[44:47], v[144:147], v[168:171], v[44:47]
	v_mfma_f32_16x16x32_bf16 v[40:43], v[152:155], v[168:171], v[40:43]
	v_mfma_f32_16x16x32_bf16 v[28:31], v[144:147], v[176:179], v[28:31]
	v_mfma_f32_16x16x32_bf16 v[24:27], v[152:155], v[176:179], v[24:27]
	v_mfma_f32_16x16x32_bf16 v[12:15], v[144:147], v[184:187], v[12:15]
	v_mfma_f32_16x16x32_bf16 v[8:11], v[152:155], v[184:187], v[8:11]
	s_barrier
	s_add_u32 s2, s8, 0x84080
	s_addc_u32 s3, s9, 0
	s_add_i32 s8, s25, s14
	v_lshl_add_u64 v[140:141], s[2:3], 0, v[64:65]
	s_mov_b32 m0, s8
	s_nop 0
	global_load_lds_dwordx4 v[140:141], off
	v_lshl_add_u64 v[140:141], s[2:3], 0, v[130:131]
	s_add_i32 m0, s8, 0x2000
	s_nop 0
	global_load_lds_dwordx4 v[140:141], off
	s_waitcnt vmcnt(6)
	s_barrier
	v_mfma_f32_16x16x32_bf16 v[52:55], v[188:191], v[156:159], v[52:55]
	v_mfma_f32_16x16x32_bf16 v[48:51], v[196:199], v[156:159], v[48:51]
	v_mfma_f32_16x16x32_bf16 v[36:39], v[188:191], v[164:167], v[36:39]
	v_mfma_f32_16x16x32_bf16 v[32:35], v[196:199], v[164:167], v[32:35]
	v_mfma_f32_16x16x32_bf16 v[20:23], v[188:191], v[172:175], v[20:23]
	v_mfma_f32_16x16x32_bf16 v[16:19], v[196:199], v[172:175], v[16:19]
	v_mfma_f32_16x16x32_bf16 v[4:7], v[188:191], v[180:183], v[4:7]
	v_mfma_f32_16x16x32_bf16 v[0:3], v[196:199], v[180:183], v[0:3]
	v_mfma_f32_16x16x32_bf16 v[52:55], v[192:195], v[160:163], v[52:55]
	v_mfma_f32_16x16x32_bf16 v[48:51], v[220:223], v[160:163], v[48:51]
	v_mfma_f32_16x16x32_bf16 v[36:39], v[192:195], v[168:171], v[36:39]
	v_mfma_f32_16x16x32_bf16 v[32:35], v[220:223], v[168:171], v[32:35]
	v_mfma_f32_16x16x32_bf16 v[20:23], v[192:195], v[176:179], v[20:23]
	v_mfma_f32_16x16x32_bf16 v[16:19], v[220:223], v[176:179], v[16:19]
	v_mfma_f32_16x16x32_bf16 v[4:7], v[192:195], v[184:187], v[4:7]
	v_mfma_f32_16x16x32_bf16 v[0:3], v[220:223], v[184:187], v[0:3]
	s_add_i32 s23, s23, 2
	s_add_u32 s6, s6, 0x100
	s_addc_u32 s7, s7, 0
	s_cmp_gt_u32 s23, 29
	s_barrier
	s_cbranch_scc0 .LBB0_1275
	s_add_i32 s0, s11, -2
	s_cmp_lt_u32 s0, 8
	s_cselect_b64 s[2:3], -1, 0
	s_cmp_gt_u32 s0, 7
	s_cbranch_scc1 .LBB0_1278
	s_mov_b32 s0, 0xc0135761
	v_pk_mul_f32 v[130:131], v[128:129], v[128:129]
	v_pk_mul_f32 v[132:133], v[126:127], v[126:127]
	v_mov_b64_e32 v[134:135], s[0:1]
	s_mov_b32 s0, 0xbdd2d3e8
	v_pk_fma_f32 v[130:131], v[130:131], s[0:1], v[134:135] op_sel_hi:[1,0,0]
	v_pk_fma_f32 v[132:133], v[132:133], s[0:1], v[134:135] op_sel_hi:[1,0,0]
	v_pk_mul_f32 v[130:131], v[128:129], v[130:131]
	v_pk_mul_f32 v[132:133], v[126:127], v[132:133]
	v_exp_f32_e32 v130, v130
	v_exp_f32_e32 v132, v132
	v_exp_f32_e32 v131, v131
	v_exp_f32_e32 v133, v133
	v_pk_add_f32 v[130:131], v[130:131], 1.0 op_sel_hi:[1,0]
	v_pk_add_f32 v[132:133], v[132:133], 1.0 op_sel_hi:[1,0]
	v_rcp_f32_e32 v130, v130
	v_rcp_f32_e32 v132, v132
	v_rcp_f32_e32 v131, v131
	v_rcp_f32_e32 v133, v133
	v_pk_mul_f32 v[128:129], v[128:129], v[130:131]
	v_pk_mul_f32 v[126:127], v[126:127], v[132:133]

; #define PG8_STAGE(bufoff, gbase, voff) do { _Pragma("unroll") for (int _i = 0; _i < 2; ++_i) \
;         __builtin_amdgcn_global_load_lds((const unsigned*)((const char*)(gbase) + (voff)[_i]), (LAS unsigned*)(lds + (bufoff) + ldsw + _i * 8192), 16, 0, 0); } while (0)
; #define PG8_LDA(dst, b, h) do { _Pragma("unroll") for (int m = 0; m < 4; ++m) _Pragma("unroll") for (int k = 0; k < 2; ++k) dst[m][k] = *(const LAS bf16x8*)(lds + PG8_SA(b, h) + aoff + m * 2048 + k * 1024); } while (0)
; #define PG8_LDB(dst, b, h) do { _Pragma("unroll") for (int n = 0; n < 2; ++n) _Pragma("unroll") for (int k = 0; k < 2; ++k) dst[n][k] = *(const LAS bf16x8*)(lds + PG8_SB(b, h) + boff + n * 2048 + k * 1024); } while (0)
; #define PG8_MMA(ai, bj, At, Bt) do { __builtin_amdgcn_s_setprio(1); _Pragma("unroll") for (int m = 0; m < 4; ++m) _Pragma("unroll") for (int n = 0; n < 2; ++n) _Pragma("unroll") for (int k = 0; k < 2; ++k) \
;         acc[ai][bj][m][n] = __builtin_amdgcn_mfma_f32_16x16x32_bf16(Bt[n][k], At[m][k], acc[ai][bj][m][n], 0, 0, 0); __builtin_amdgcn_s_setprio(0); } while (0)
; #define PG8_WAIT_L(n) asm volatile("s_waitcnt lgkmcnt(" #n ")" ::: "memory")
; #define PG8_BAR __builtin_amdgcn_s_barrier()
; #define PG8_SCHED __builtin_amdgcn_sched_barrier(0)
;     ...
;             const char* a1 = cA + (size_t)(t + 1) * kstep;
;             const char* a2 = last ? nA : cA + (size_t)(t + 2) * kstep; const char* b2 = last ? nB : cB + (size_t)(t + 2) * kstep;
;             const char* a3 = a2 + kstep; const char* b3 = b2 + kstep;
;             PG8_LDB(B0, 0, 0); PG8_SCHED; PG8_LDA(At, 0, 0); PG8_STAGE(PG8_SA(1, 1), a1 + hstep, voffA);
;             PG8_WAIT_L(8); PG8_BAR; PG8_WAIT_L(0); PG8_MMA(0, 0, At, B0); PG8_BAR; PG8_SCHED;
;             PG8_LDB(B1, 0, 1); PG8_STAGE(PG8_SB(0, 0), b2, voffB);
;             PG8_BAR; PG8_WAIT_L(0); PG8_MMA(0, 1, At, B1); PG8_BAR;
;             PG8_LDA(At, 0, 1); PG8_STAGE(PG8_SA(0, 0), a2, voffA);
;             PG8_BAR; PG8_WAIT_L(0); PG8_MMA(1, 0, At, B0); PG8_BAR; PG8_SCHED;
.LBB0_1441:
	s_add_u32 s4, s0, 0x100
	s_addc_u32 s5, s1, 0
	s_add_i32 s43, 0, 0x10000
	v_add_u32_e32 v140, s43, v143
	ds_read_b128 v[136:139], v140
	ds_read_b128 v[146:149], v140 offset:1024
	ds_read_b128 v[150:153], v140 offset:2048
	ds_read_b128 v[154:157], v140 offset:3072
	s_cmp_eq_u32 s42, 28
	s_cselect_b32 s3, s21, s5
	s_cselect_b32 s2, s20, s4
	s_cselect_b32 s9, s23, s41
	s_cselect_b32 s8, s22, s40
	v_lshl_add_u64 v[140:141], s[0:1], 0, v[132:133]
	s_add_i32 m0, s12, 0xc000
	ds_read_b128 v[158:161], v145
	ds_read_b128 v[162:165], v145 offset:1024
	ds_read_b128 v[166:169], v145 offset:2048
	ds_read_b128 v[170:173], v145 offset:3072
	ds_read_b128 v[174:177], v145 offset:4096
	ds_read_b128 v[178:181], v145 offset:5120
	ds_read_b128 v[182:185], v145 offset:6144
	ds_read_b128 v[186:189], v145 offset:7168
	global_load_lds_dwordx4 v[140:141], off
	v_lshl_add_u64 v[140:141], s[0:1], 0, v[134:135]
	s_add_i32 m0, s12, 0xe000
	s_nop 0
	global_load_lds_dwordx4 v[140:141], off
	s_waitcnt lgkmcnt(8)
	s_barrier
	s_waitcnt lgkmcnt(0)
	v_mfma_f32_16x16x32_bf16 v[126:129], v[136:139], v[158:161], v[126:129]
	v_mfma_f32_16x16x32_bf16 v[122:125], v[150:153], v[158:161], v[122:125]
	v_mfma_f32_16x16x32_bf16 v[110:113], v[136:139], v[166:169], v[110:113]
	v_mfma_f32_16x16x32_bf16 v[106:109], v[150:153], v[166:169], v[106:109]
	v_mfma_f32_16x16x32_bf16 v[94:97], v[136:139], v[174:177], v[94:97]
	v_mfma_f32_16x16x32_bf16 v[90:93], v[150:153], v[174:177], v[90:93]
	v_mfma_f32_16x16x32_bf16 v[78:81], v[136:139], v[182:185], v[78:81]
	v_mfma_f32_16x16x32_bf16 v[74:77], v[150:153], v[182:185], v[74:77]
	v_mfma_f32_16x16x32_bf16 v[126:129], v[146:149], v[162:165], v[126:129]
	v_mfma_f32_16x16x32_bf16 v[122:125], v[154:157], v[162:165], v[122:125]
	v_mfma_f32_16x16x32_bf16 v[110:113], v[146:149], v[170:173], v[110:113]
	v_mfma_f32_16x16x32_bf16 v[106:109], v[154:157], v[170:173], v[106:109]
	v_mfma_f32_16x16x32_bf16 v[94:97], v[146:149], v[178:181], v[94:97]
	v_mfma_f32_16x16x32_bf16 v[90:93], v[154:157], v[178:181], v[90:93]
	v_mfma_f32_16x16x32_bf16 v[78:81], v[146:149], v[186:189], v[78:81]
	v_mfma_f32_16x16x32_bf16 v[74:77], v[154:157], v[186:189], v[74:77]
	s_barrier
	s_add_i32 s44, 0, 0x14000
	v_add_u32_e32 v140, s44, v143
	s_add_i32 s0, s43, s11
	ds_read_b128 v[190:193], v140
	ds_read_b128 v[194:197], v140 offset:1024
	ds_read_b128 v[220:223], v140 offset:2048
	ds_read_b128 v[224:227], v140 offset:3072
	v_lshl_add_u64 v[140:141], s[8:9], 0, v[64:65]
	s_mov_b32 m0, s0
	v_lshl_add_u64 v[198:199], s[8:9], 0, v[130:131]
	global_load_lds_dwordx4 v[140:141], off
	s_add_i32 m0, s0, 0x2000
	s_nop 0
	global_load_lds_dwordx4 v[198:199], off
	s_waitcnt lgkmcnt(0)
	s_barrier
	v_mfma_f32_16x16x32_bf16 v[118:121], v[190:193], v[158:161], v[118:121]
	v_mfma_f32_16x16x32_bf16 v[114:117], v[220:223], v[158:161], v[114:117]
	v_mfma_f32_16x16x32_bf16 v[102:105], v[190:193], v[166:169], v[102:105]
	v_mfma_f32_16x16x32_bf16 v[98:101], v[220:223], v[166:169], v[98:101]
	v_mfma_f32_16x16x32_bf16 v[86:89], v[190:193], v[174:177], v[86:89]
	v_mfma_f32_16x16x32_bf16 v[82:85], v[220:223], v[174:177], v[82:85]
	v_mfma_f32_16x16x32_bf16 v[70:73], v[190:193], v[182:185], v[70:73]
	v_mfma_f32_16x16x32_bf16 v[66:69], v[220:223], v[182:185], v[66:69]
	v_mfma_f32_16x16x32_bf16 v[118:121], v[194:197], v[162:165], v[118:121]
	v_mfma_f32_16x16x32_bf16 v[114:117], v[224:227], v[162:165], v[114:117]
	v_mfma_f32_16x16x32_bf16 v[102:105], v[194:197], v[170:173], v[102:105]
	v_mfma_f32_16x16x32_bf16 v[98:101], v[224:227], v[170:173], v[98:101]
	v_mfma_f32_16x16x32_bf16 v[86:89], v[194:197], v[178:181], v[86:89]
	v_mfma_f32_16x16x32_bf16 v[82:85], v[224:227], v[178:181], v[82:85]
	v_mfma_f32_16x16x32_bf16 v[70:73], v[194:197], v[186:189], v[70:73]
	v_mfma_f32_16x16x32_bf16 v[66:69], v[224:227], v[186:189], v[66:69]
	s_mov_b32 m0, s12
	v_lshl_add_u64 v[228:229], s[2:3], 0, v[64:65]
	s_barrier
	ds_read_b128 v[158:161], v145 offset:16384
	ds_read_b128 v[162:165], v145 offset:17408
	ds_read_b128 v[166:169], v145 offset:18432
	ds_read_b128 v[170:173], v145 offset:19456
	ds_read_b128 v[174:177], v145 offset:20480
	ds_read_b128 v[178:181], v145 offset:21504
	ds_read_b128 v[182:185], v145 offset:22528
	ds_read_b128 v[186:189], v145 offset:23552
	global_load_lds_dwordx4 v[228:229], off
	v_lshl_add_u64 v[230:231], s[2:3], 0, v[130:131]
	s_mov_b32 m0, s13
	s_nop 0
	global_load_lds_dwordx4 v[230:231], off
	s_waitcnt lgkmcnt(0)
	s_barrier
	v_mfma_f32_16x16x32_bf16 v[60:63], v[136:139], v[158:161], v[60:63]
	v_mfma_f32_16x16x32_bf16 v[56:59], v[150:153], v[158:161], v[56:59]
	v_mfma_f32_16x16x32_bf16 v[44:47], v[136:139], v[166:169], v[44:47]
	v_mfma_f32_16x16x32_bf16 v[40:43], v[150:153], v[166:169], v[40:43]
	v_mfma_f32_16x16x32_bf16 v[28:31], v[136:139], v[174:177], v[28:31]
	v_mfma_f32_16x16x32_bf16 v[24:27], v[150:153], v[174:177], v[24:27]
	v_mfma_f32_16x16x32_bf16 v[12:15], v[136:139], v[182:185], v[12:15]
	v_mfma_f32_16x16x32_bf16 v[8:11], v[150:153], v[182:185], v[8:11]
	v_mfma_f32_16x16x32_bf16 v[60:63], v[146:149], v[162:165], v[60:63]
	v_mfma_f32_16x16x32_bf16 v[56:59], v[154:157], v[162:165], v[56:59]
	v_mfma_f32_16x16x32_bf16 v[44:47], v[146:149], v[170:173], v[44:47]
	v_mfma_f32_16x16x32_bf16 v[40:43], v[154:157], v[170:173], v[40:43]
	v_mfma_f32_16x16x32_bf16 v[28:31], v[146:149], v[178:181], v[28:31]
	v_mfma_f32_16x16x32_bf16 v[24:27], v[154:157], v[178:181], v[24:27]
	v_mfma_f32_16x16x32_bf16 v[12:15], v[146:149], v[186:189], v[12:15]
	v_mfma_f32_16x16x32_bf16 v[8:11], v[154:157], v[186:189], v[8:11]
	s_barrier
; #define PG8_STAGE(bufoff, gbase, voff) do { _Pragma("unroll") for (int _i = 0; _i < 2; ++_i) \
;         __builtin_amdgcn_global_load_lds((const unsigned*)((const char*)(gbase) + (voff)[_i]), (LAS unsigned*)(lds + (bufoff) + ldsw + _i * 8192), 16, 0, 0); } while (0)
; #define PG8_LDA(dst, b, h) do { _Pragma("unroll") for (int m = 0; m < 4; ++m) _Pragma("unroll") for (int k = 0; k < 2; ++k) dst[m][k] = *(const LAS bf16x8*)(lds + PG8_SA(b, h) + aoff + m * 2048 + k * 1024); } while (0)
; #define PG8_LDB(dst, b, h) do { _Pragma("unroll") for (int n = 0; n < 2; ++n) _Pragma("unroll") for (int k = 0; k < 2; ++k) dst[n][k] = *(const LAS bf16x8*)(lds + PG8_SB(b, h) + boff + n * 2048 + k * 1024); } while (0)
; #define PG8_MMA(ai, bj, At, Bt) do { __builtin_amdgcn_s_setprio(1); _Pragma("unroll") for (int m = 0; m < 4; ++m) _Pragma("unroll") for (int n = 0; n < 2; ++n) _Pragma("unroll") for (int k = 0; k < 2; ++k) \
;         acc[ai][bj][m][n] = __builtin_amdgcn_mfma_f32_16x16x32_bf16(Bt[n][k], At[m][k], acc[ai][bj][m][n], 0, 0, 0); __builtin_amdgcn_s_setprio(0); } while (0)
; #define PG8_WAIT_V(n) asm volatile("s_waitcnt vmcnt(" #n ")" ::: "memory")
; #define PG8_WAIT_L(n) asm volatile("s_waitcnt lgkmcnt(" #n ")" ::: "memory")
; #define PG8_BAR __builtin_amdgcn_s_barrier()
; #define PG8_SCHED __builtin_amdgcn_sched_barrier(0)
;     ...
;             PG8_STAGE(PG8_SB(0, 1), b2 + hstep, voffB);
;             PG8_WAIT_V(6); PG8_BAR; PG8_MMA(1, 1, At, B1); PG8_BAR;
;             PG8_LDB(B0, 1, 0); PG8_SCHED; PG8_LDA(At, 1, 0); PG8_STAGE(PG8_SA(0, 1), a2 + hstep, voffA);
;             PG8_WAIT_L(8); PG8_BAR; PG8_WAIT_L(0); PG8_MMA(0, 0, At, B0); PG8_BAR; PG8_SCHED;
;             PG8_LDB(B1, 1, 1); PG8_STAGE(PG8_SB(1, 0), b3, voffB);
;             PG8_BAR; PG8_WAIT_L(0); PG8_MMA(0, 1, At, B1); PG8_BAR;
;             PG8_LDA(At, 1, 1); PG8_STAGE(PG8_SA(1, 0), a3, voffA);
;             PG8_BAR; PG8_WAIT_L(0); PG8_MMA(1, 0, At, B0); PG8_BAR; PG8_SCHED;
	s_add_u32 s0, s8, 0x84000
	s_addc_u32 s1, s9, 0
	s_add_i32 s43, s44, s11
	v_lshl_add_u64 v[136:137], s[0:1], 0, v[64:65]
	s_mov_b32 m0, s43
	s_nop 0
	global_load_lds_dwordx4 v[136:137], off
	v_lshl_add_u64 v[136:137], s[0:1], 0, v[130:131]
	s_add_i32 m0, s43, 0x2000
	s_nop 0
	global_load_lds_dwordx4 v[136:137], off
	s_waitcnt vmcnt(6)
	s_barrier
	v_mfma_f32_16x16x32_bf16 v[52:55], v[190:193], v[158:161], v[52:55]
	v_mfma_f32_16x16x32_bf16 v[48:51], v[220:223], v[158:161], v[48:51]
	v_mfma_f32_16x16x32_bf16 v[36:39], v[190:193], v[166:169], v[36:39]
	v_mfma_f32_16x16x32_bf16 v[32:35], v[220:223], v[166:169], v[32:35]
	v_mfma_f32_16x16x32_bf16 v[20:23], v[190:193], v[174:177], v[20:23]
	v_mfma_f32_16x16x32_bf16 v[16:19], v[220:223], v[174:177], v[16:19]
	v_mfma_f32_16x16x32_bf16 v[4:7], v[190:193], v[182:185], v[4:7]
	v_mfma_f32_16x16x32_bf16 v[0:3], v[220:223], v[182:185], v[0:3]
	v_mfma_f32_16x16x32_bf16 v[52:55], v[194:197], v[162:165], v[52:55]
	v_mfma_f32_16x16x32_bf16 v[48:51], v[224:227], v[162:165], v[48:51]
	v_mfma_f32_16x16x32_bf16 v[36:39], v[194:197], v[170:173], v[36:39]
	v_mfma_f32_16x16x32_bf16 v[32:35], v[224:227], v[170:173], v[32:35]
	v_mfma_f32_16x16x32_bf16 v[20:23], v[194:197], v[178:181], v[20:23]
	v_mfma_f32_16x16x32_bf16 v[16:19], v[224:227], v[178:181], v[16:19]
	v_mfma_f32_16x16x32_bf16 v[4:7], v[194:197], v[186:189], v[4:7]
	v_mfma_f32_16x16x32_bf16 v[0:3], v[224:227], v[186:189], v[0:3]
	s_add_i32 s43, 0, 0x18000
	v_add_u32_e32 v154, s43, v143
	s_barrier
	ds_read_b128 v[136:139], v154
	ds_read_b128 v[146:149], v154 offset:1024
	ds_read_b128 v[150:153], v154 offset:2048
	ds_read_b128 v[154:157], v154 offset:3072
	s_add_u32 s0, s2, 0x84000
	s_addc_u32 s1, s3, 0
	s_mov_b32 m0, s14
	v_lshl_add_u64 v[190:191], s[0:1], 0, v[64:65]
	ds_read_b128 v[158:161], v145 offset:32768
	ds_read_b128 v[162:165], v145 offset:33792
	ds_read_b128 v[166:169], v145 offset:34816
	ds_read_b128 v[170:173], v145 offset:35840
	ds_read_b128 v[174:177], v145 offset:36864
	ds_read_b128 v[178:181], v145 offset:37888
	ds_read_b128 v[182:185], v145 offset:38912
	ds_read_b128 v[186:189], v145 offset:39936
	global_load_lds_dwordx4 v[190:191], off
	v_lshl_add_u64 v[190:191], s[0:1], 0, v[130:131]
	s_mov_b32 m0, s15
	s_nop 0
	global_load_lds_dwordx4 v[190:191], off
	s_waitcnt lgkmcnt(8)
	s_barrier
	s_waitcnt lgkmcnt(0)
	v_mfma_f32_16x16x32_bf16 v[126:129], v[136:139], v[158:161], v[126:129]
	v_mfma_f32_16x16x32_bf16 v[122:125], v[150:153], v[158:161], v[122:125]
	v_mfma_f32_16x16x32_bf16 v[110:113], v[136:139], v[166:169], v[110:113]
	v_mfma_f32_16x16x32_bf16 v[106:109], v[150:153], v[166:169], v[106:109]
	v_mfma_f32_16x16x32_bf16 v[94:97], v[136:139], v[174:177], v[94:97]
	v_mfma_f32_16x16x32_bf16 v[90:93], v[150:153], v[174:177], v[90:93]
	v_mfma_f32_16x16x32_bf16 v[78:81], v[136:139], v[182:185], v[78:81]
	v_mfma_f32_16x16x32_bf16 v[74:77], v[150:153], v[182:185], v[74:77]
	v_mfma_f32_16x16x32_bf16 v[126:129], v[146:149], v[162:165], v[126:129]
	v_mfma_f32_16x16x32_bf16 v[122:125], v[154:157], v[162:165], v[122:125]
	v_mfma_f32_16x16x32_bf16 v[110:113], v[146:149], v[170:173], v[110:113]
	v_mfma_f32_16x16x32_bf16 v[106:109], v[154:157], v[170:173], v[106:109]
	v_mfma_f32_16x16x32_bf16 v[94:97], v[146:149], v[178:181], v[94:97]
	v_mfma_f32_16x16x32_bf16 v[90:93], v[154:157], v[178:181], v[90:93]
	v_mfma_f32_16x16x32_bf16 v[78:81], v[146:149], v[186:189], v[78:81]
	v_mfma_f32_16x16x32_bf16 v[74:77], v[154:157], v[186:189], v[74:77]
	s_barrier
	s_add_i32 s2, 0, 0x1c000
	s_add_i32 s0, s43, s11
	v_add_u32_e32 v208, s2, v143
	v_lshl_add_u64 v[140:141], v[140:141], 0, s[16:17]
	s_mov_b32 m0, s0
	ds_read_b128 v[190:193], v208
	ds_read_b128 v[194:197], v208 offset:1024
	ds_read_b128 v[220:223], v208 offset:2048
	ds_read_b128 v[224:227], v208 offset:3072
	global_load_lds_dwordx4 v[140:141], off
	v_lshl_add_u64 v[140:141], v[198:199], 0, s[16:17]
	s_add_i32 m0, s0, 0x2000
	s_nop 0
	global_load_lds_dwordx4 v[140:141], off
	s_waitcnt lgkmcnt(0)
	s_barrier
	v_mfma_f32_16x16x32_bf16 v[118:121], v[190:193], v[158:161], v[118:121]
	v_mfma_f32_16x16x32_bf16 v[114:117], v[220:223], v[158:161], v[114:117]
	v_mfma_f32_16x16x32_bf16 v[102:105], v[190:193], v[166:169], v[102:105]
	v_mfma_f32_16x16x32_bf16 v[98:101], v[220:223], v[166:169], v[98:101]
	v_mfma_f32_16x16x32_bf16 v[86:89], v[190:193], v[174:177], v[86:89]
	v_mfma_f32_16x16x32_bf16 v[82:85], v[220:223], v[174:177], v[82:85]
	v_mfma_f32_16x16x32_bf16 v[70:73], v[190:193], v[182:185], v[70:73]
	v_mfma_f32_16x16x32_bf16 v[66:69], v[220:223], v[182:185], v[66:69]
	v_mfma_f32_16x16x32_bf16 v[118:121], v[194:197], v[162:165], v[118:121]
	v_mfma_f32_16x16x32_bf16 v[114:117], v[224:227], v[162:165], v[114:117]
	v_mfma_f32_16x16x32_bf16 v[102:105], v[194:197], v[170:173], v[102:105]
	v_mfma_f32_16x16x32_bf16 v[98:101], v[224:227], v[170:173], v[98:101]
	v_mfma_f32_16x16x32_bf16 v[86:89], v[194:197], v[178:181], v[86:89]
	v_mfma_f32_16x16x32_bf16 v[82:85], v[224:227], v[178:181], v[82:85]
	v_mfma_f32_16x16x32_bf16 v[70:73], v[194:197], v[186:189], v[70:73]
	v_mfma_f32_16x16x32_bf16 v[66:69], v[224:227], v[186:189], v[66:69]
	s_mov_b32 m0, s24
	v_lshl_add_u64 v[140:141], v[228:229], 0, s[16:17]
	s_barrier
; #define PG8_STAGE(bufoff, gbase, voff) do { _Pragma("unroll") for (int _i = 0; _i < 2; ++_i) \
;         __builtin_amdgcn_global_load_lds((const unsigned*)((const char*)(gbase) + (voff)[_i]), (LAS unsigned*)(lds + (bufoff) + ldsw + _i * 8192), 16, 0, 0); } while (0)
; #define PG8_MMA(ai, bj, At, Bt) do { __builtin_amdgcn_s_setprio(1); _Pragma("unroll") for (int m = 0; m < 4; ++m) _Pragma("unroll") for (int n = 0; n < 2; ++n) _Pragma("unroll") for (int k = 0; k < 2; ++k) \
;         acc[ai][bj][m][n] = __builtin_amdgcn_mfma_f32_16x16x32_bf16(Bt[n][k], At[m][k], acc[ai][bj][m][n], 0, 0, 0); __builtin_amdgcn_s_setprio(0); } while (0)
; #define PG8_WAIT_V(n) asm volatile("s_waitcnt vmcnt(" #n ")" ::: "memory")
; #define PG8_WAIT_L(n) asm volatile("s_waitcnt lgkmcnt(" #n ")" ::: "memory")
; #define PG8_BAR __builtin_amdgcn_s_barrier()
; #define PG8_SCHED __builtin_amdgcn_sched_barrier(0)
; __device__ __forceinline__ f32x4 gelu4(const f32x4 x) {
;     const f32x4 t = x * x, a = x * (t * -0.10294324f + -2.3022082f);
;     f32x4 e; e[0] = __builtin_amdgcn_exp2f(a[0]); e[1] = __builtin_amdgcn_exp2f(a[1]); e[2] = __builtin_amdgcn_exp2f(a[2]); e[3] = __builtin_amdgcn_exp2f(a[3]);
;     const f32x4 d = e + 1.0f;
;     f32x4 r; r[0] = __builtin_amdgcn_rcpf(d[0]); r[1] = __builtin_amdgcn_rcpf(d[1]); r[2] = __builtin_amdgcn_rcpf(d[2]); r[3] = __builtin_amdgcn_rcpf(d[3]);
;     return x * r;
;     ...
;             PG8_BAR; PG8_WAIT_L(0); PG8_MMA(1, 0, At, B0); PG8_BAR; PG8_SCHED;
;             PG8_STAGE(PG8_SB(1, 1), b3 + hstep, voffB);
;             PG8_WAIT_V(6); PG8_BAR; PG8_MMA(1, 1, At, B1); PG8_BAR;
;         }
	ds_read_b128 v[158:161], v145 offset:49152
	ds_read_b128 v[162:165], v145 offset:50176
	ds_read_b128 v[166:169], v145 offset:51200
	ds_read_b128 v[170:173], v145 offset:52224
	ds_read_b128 v[174:177], v145 offset:53248
	ds_read_b128 v[178:181], v145 offset:54272
	ds_read_b128 v[182:185], v145 offset:55296
	ds_read_b128 v[186:189], v145 offset:56320
	global_load_lds_dwordx4 v[140:141], off
	v_lshl_add_u64 v[140:141], v[230:231], 0, s[16:17]
	s_mov_b32 m0, s25
	s_nop 0
	global_load_lds_dwordx4 v[140:141], off
	s_waitcnt lgkmcnt(0)
	s_barrier
	v_mfma_f32_16x16x32_bf16 v[60:63], v[136:139], v[158:161], v[60:63]
	v_mfma_f32_16x16x32_bf16 v[56:59], v[150:153], v[158:161], v[56:59]
	v_mfma_f32_16x16x32_bf16 v[44:47], v[136:139], v[166:169], v[44:47]
	v_mfma_f32_16x16x32_bf16 v[40:43], v[150:153], v[166:169], v[40:43]
	v_mfma_f32_16x16x32_bf16 v[28:31], v[136:139], v[174:177], v[28:31]
	v_mfma_f32_16x16x32_bf16 v[24:27], v[150:153], v[174:177], v[24:27]
	v_mfma_f32_16x16x32_bf16 v[12:15], v[136:139], v[182:185], v[12:15]
	v_mfma_f32_16x16x32_bf16 v[8:11], v[150:153], v[182:185], v[8:11]
	v_mfma_f32_16x16x32_bf16 v[60:63], v[146:149], v[162:165], v[60:63]
	v_mfma_f32_16x16x32_bf16 v[56:59], v[154:157], v[162:165], v[56:59]
	v_mfma_f32_16x16x32_bf16 v[44:47], v[146:149], v[170:173], v[44:47]
	v_mfma_f32_16x16x32_bf16 v[40:43], v[154:157], v[170:173], v[40:43]
	v_mfma_f32_16x16x32_bf16 v[28:31], v[146:149], v[178:181], v[28:31]
	v_mfma_f32_16x16x32_bf16 v[24:27], v[154:157], v[178:181], v[24:27]
	v_mfma_f32_16x16x32_bf16 v[12:15], v[146:149], v[186:189], v[12:15]
	v_mfma_f32_16x16x32_bf16 v[8:11], v[154:157], v[186:189], v[8:11]
	s_barrier
	s_add_u32 s0, s8, 0x84080
	s_addc_u32 s1, s9, 0
	s_add_i32 s2, s2, s11
	v_lshl_add_u64 v[136:137], s[0:1], 0, v[64:65]
	s_mov_b32 m0, s2
	s_nop 0
	global_load_lds_dwordx4 v[136:137], off
	v_lshl_add_u64 v[136:137], s[0:1], 0, v[130:131]
	s_add_i32 m0, s2, 0x2000
	s_nop 0
	global_load_lds_dwordx4 v[136:137], off
	s_waitcnt vmcnt(6)
	s_barrier
	v_mfma_f32_16x16x32_bf16 v[52:55], v[190:193], v[158:161], v[52:55]
	v_mfma_f32_16x16x32_bf16 v[48:51], v[220:223], v[158:161], v[48:51]
	v_mfma_f32_16x16x32_bf16 v[36:39], v[190:193], v[166:169], v[36:39]
	v_mfma_f32_16x16x32_bf16 v[32:35], v[220:223], v[166:169], v[32:35]
	v_mfma_f32_16x16x32_bf16 v[20:23], v[190:193], v[174:177], v[20:23]
	v_mfma_f32_16x16x32_bf16 v[16:19], v[220:223], v[174:177], v[16:19]
	v_mfma_f32_16x16x32_bf16 v[4:7], v[190:193], v[182:185], v[4:7]
	v_mfma_f32_16x16x32_bf16 v[0:3], v[220:223], v[182:185], v[0:3]
	v_mfma_f32_16x16x32_bf16 v[52:55], v[194:197], v[162:165], v[52:55]
	v_mfma_f32_16x16x32_bf16 v[48:51], v[224:227], v[162:165], v[48:51]
	v_mfma_f32_16x16x32_bf16 v[36:39], v[194:197], v[170:173], v[36:39]
	v_mfma_f32_16x16x32_bf16 v[32:35], v[224:227], v[170:173], v[32:35]
	v_mfma_f32_16x16x32_bf16 v[20:23], v[194:197], v[178:181], v[20:23]
	v_mfma_f32_16x16x32_bf16 v[16:19], v[224:227], v[178:181], v[16:19]
	v_mfma_f32_16x16x32_bf16 v[4:7], v[194:197], v[186:189], v[4:7]
	v_mfma_f32_16x16x32_bf16 v[0:3], v[224:227], v[186:189], v[0:3]
	s_add_i32 s42, s42, 2
	s_add_u32 s40, s40, 0x100
	s_addc_u32 s41, s41, 0
	s_cmp_gt_u32 s42, 29
	s_mov_b64 s[0:1], s[4:5]
	s_barrier
	s_cbranch_scc0 .LBB0_1441
	s_add_i32 s0, s38, -2
	s_cmp_lt_u32 s0, 8
	s_cselect_b64 s[2:3], -1, 0
	s_cmp_gt_u32 s0, 7
	s_cbranch_scc1 .LBB0_1444
	s_mov_b32 s40, 0xc0135761
	v_pk_mul_f32 v[136:137], v[128:129], v[128:129]
	v_pk_mul_f32 v[138:139], v[126:127], v[126:127]
	v_mov_b64_e32 v[140:141], s[40:41]
	s_mov_b32 s0, 0xbdd2d3e8
	v_pk_fma_f32 v[136:137], v[136:137], s[0:1], v[140:141] op_sel_hi:[1,0,0]
	v_pk_fma_f32 v[138:139], v[138:139], s[0:1], v[140:141] op_sel_hi:[1,0,0]
	v_pk_mul_f32 v[136:137], v[128:129], v[136:137]
	v_pk_mul_f32 v[138:139], v[126:127], v[138:139]
	v_exp_f32_e32 v136, v136
	v_exp_f32_e32 v138, v138
	v_exp_f32_e32 v137, v137
	v_exp_f32_e32 v139, v139
	v_pk_add_f32 v[136:137], v[136:137], 1.0 op_sel_hi:[1,0]
	v_pk_add_f32 v[138:139], v[138:139], 1.0 op_sel_hi:[1,0]
	v_rcp_f32_e32 v136, v136
	v_rcp_f32_e32 v138, v138
	v_rcp_f32_e32 v137, v137
	v_rcp_f32_e32 v139, v139
	v_pk_mul_f32 v[128:129], v[128:129], v[136:137]
	v_pk_mul_f32 v[126:127], v[126:127], v[138:139]
	s_branch .LBB0_1445
